# GEMM units: first two vmcnt waits of a unit count the previous epilogue's stores (vmcnt(8+S)), so the first K-tile does not wait for store acks
# baseline (speedup 1.0000x reference)
.Lpk354_peel:
	ds_read_b128 v[166:169], v139
	ds_read_b128 v[170:173], v139 offset:1024
	ds_read_b128 v[178:181], v139 offset:2048
	ds_read_b128 v[182:185], v139 offset:3072
	ds_read_b128 v[186:189], v164
	ds_read_b128 v[190:193], v164 offset:1024
	ds_read_b128 v[194:197], v164 offset:2048
	ds_read_b128 v[198:201], v164 offset:3072
	s_add_u32 s2, s26, 0xfffc0080
	s_addc_u32 s3, s27, -1
	s_cmp_eq_u32 s52, 12
	s_cselect_b32 s3, s11, s3
	s_cselect_b32 s2, s13, s2
	s_cselect_b32 s29, s44, s47
	s_cselect_b32 s28, s45, s46
	v_lshl_add_u64 v[148:149], s[26:27], 0, v[142:143]
	s_add_i32 m0, s34, 0xc000
	ds_read_b128 v[202:205], v165
	ds_read_b128 v[206:209], v165 offset:1024
	ds_read_b128 v[210:213], v165 offset:2048
	ds_read_b128 v[214:217], v165 offset:3072
	ds_read_b128 v[218:221], v165 offset:4096
	ds_read_b128 v[222:225], v165 offset:5120
	ds_read_b128 v[226:229], v165 offset:6144
	ds_read_b128 v[230:233], v165 offset:7168
	global_load_lds_dwordx4 v[148:149], off
	v_lshl_add_u64 v[148:149], s[26:27], 0, v[144:145]
	s_add_i32 m0, s34, 0xe000
	s_nop 0
	global_load_lds_dwordx4 v[148:149], off
	s_waitcnt vmcnt(16)
	s_waitcnt lgkmcnt(0)
	s_barrier
	s_setprio 1
	s_waitcnt lgkmcnt(0)
	v_mfma_f32_16x16x32_bf16 v[126:129], v[166:169], v[202:205], 0
	v_mfma_f32_16x16x32_bf16 v[122:125], v[178:181], v[202:205], 0
	v_mfma_f32_16x16x32_bf16 v[110:113], v[166:169], v[210:213], 0
	v_mfma_f32_16x16x32_bf16 v[106:109], v[178:181], v[210:213], 0
	v_mfma_f32_16x16x32_bf16 v[94:97], v[166:169], v[218:221], 0
	v_mfma_f32_16x16x32_bf16 v[90:93], v[178:181], v[218:221], 0
	v_mfma_f32_16x16x32_bf16 v[78:81], v[166:169], v[226:229], 0
	v_mfma_f32_16x16x32_bf16 v[74:77], v[178:181], v[226:229], 0
	v_mfma_f32_16x16x32_bf16 v[126:129], v[170:173], v[206:209], v[126:129]
	v_mfma_f32_16x16x32_bf16 v[122:125], v[182:185], v[206:209], v[122:125]
	v_mfma_f32_16x16x32_bf16 v[110:113], v[170:173], v[214:217], v[110:113]
	v_mfma_f32_16x16x32_bf16 v[106:109], v[182:185], v[214:217], v[106:109]
	v_mfma_f32_16x16x32_bf16 v[94:97], v[170:173], v[222:225], v[94:97]
	v_mfma_f32_16x16x32_bf16 v[90:93], v[182:185], v[222:225], v[90:93]
	v_mfma_f32_16x16x32_bf16 v[78:81], v[170:173], v[230:233], v[78:81]
	v_mfma_f32_16x16x32_bf16 v[74:77], v[182:185], v[230:233], v[74:77]
	s_setprio 0
	s_setprio 1
	v_mfma_f32_16x16x32_bf16 v[118:121], v[186:189], v[202:205], 0
	v_mfma_f32_16x16x32_bf16 v[114:117], v[194:197], v[202:205], 0
	v_mfma_f32_16x16x32_bf16 v[102:105], v[186:189], v[210:213], 0
	v_mfma_f32_16x16x32_bf16 v[98:101], v[194:197], v[210:213], 0
	v_mfma_f32_16x16x32_bf16 v[86:89], v[186:189], v[218:221], 0
	v_mfma_f32_16x16x32_bf16 v[82:85], v[194:197], v[218:221], 0
	v_mfma_f32_16x16x32_bf16 v[70:73], v[186:189], v[226:229], 0
	v_mfma_f32_16x16x32_bf16 v[66:69], v[194:197], v[226:229], 0
	v_mfma_f32_16x16x32_bf16 v[118:121], v[190:193], v[206:209], v[118:121]
	v_mfma_f32_16x16x32_bf16 v[114:117], v[198:201], v[206:209], v[114:117]
	v_mfma_f32_16x16x32_bf16 v[102:105], v[190:193], v[214:217], v[102:105]
	v_mfma_f32_16x16x32_bf16 v[98:101], v[198:201], v[214:217], v[98:101]
	v_mfma_f32_16x16x32_bf16 v[86:89], v[190:193], v[222:225], v[86:89]
	v_mfma_f32_16x16x32_bf16 v[82:85], v[198:201], v[222:225], v[82:85]
	v_mfma_f32_16x16x32_bf16 v[70:73], v[190:193], v[230:233], v[70:73]
	v_mfma_f32_16x16x32_bf16 v[66:69], v[198:201], v[230:233], v[66:69]
	s_setprio 0
	s_barrier
	s_add_i32 s53, s41, s30
	v_lshl_add_u64 v[148:149], s[28:29], 0, v[132:133]
	s_mov_b32 m0, s53
	ds_read_b128 v[202:205], v165 offset:16384
	ds_read_b128 v[206:209], v165 offset:17408
	ds_read_b128 v[210:213], v165 offset:18432
	ds_read_b128 v[214:217], v165 offset:19456
	ds_read_b128 v[218:221], v165 offset:20480
	ds_read_b128 v[222:225], v165 offset:21504
	ds_read_b128 v[226:229], v165 offset:22528
	ds_read_b128 v[230:233], v165 offset:23552
	global_load_lds_dwordx4 v[148:149], off
	s_add_i32 m0, s53, 0x2000
	s_add_u32 s54, s28, 0x40000
	v_lshl_add_u64 v[174:175], s[28:29], 0, v[136:137]
	s_addc_u32 s55, s29, 0
	s_add_i32 s53, s42, s30
	global_load_lds_dwordx4 v[174:175], off
	v_lshl_add_u64 v[234:235], s[54:55], 0, v[132:133]
	s_mov_b32 m0, s53
	v_lshl_add_u64 v[236:237], s[2:3], 0, v[134:135]
	global_load_lds_dwordx4 v[234:235], off
	v_lshl_add_u64 v[234:235], s[54:55], 0, v[136:137]
	s_add_i32 m0, s53, 0x2000
	s_nop 0
	global_load_lds_dwordx4 v[234:235], off
	v_lshl_add_u64 v[234:235], s[2:3], 0, v[130:131]
	s_mov_b32 m0, s34
	s_nop 0
	global_load_lds_dwordx4 v[234:235], off
	s_mov_b32 m0, s25
	s_nop 0
	global_load_lds_dwordx4 v[236:237], off
	s_waitcnt vmcnt(16)
	s_waitcnt lgkmcnt(0)
	s_barrier
	s_setprio 1
	s_waitcnt lgkmcnt(0)
	v_mfma_f32_16x16x32_bf16 v[62:65], v[166:169], v[202:205], 0
	v_mfma_f32_16x16x32_bf16 v[58:61], v[178:181], v[202:205], 0
	v_mfma_f32_16x16x32_bf16 v[46:49], v[166:169], v[210:213], 0
	v_mfma_f32_16x16x32_bf16 v[42:45], v[178:181], v[210:213], 0
	v_mfma_f32_16x16x32_bf16 v[30:33], v[166:169], v[218:221], 0
	v_mfma_f32_16x16x32_bf16 v[26:29], v[178:181], v[218:221], 0
	v_mfma_f32_16x16x32_bf16 v[14:17], v[166:169], v[226:229], 0
	v_mfma_f32_16x16x32_bf16 v[10:13], v[178:181], v[226:229], 0
	v_mfma_f32_16x16x32_bf16 v[62:65], v[170:173], v[206:209], v[62:65]
	v_mfma_f32_16x16x32_bf16 v[58:61], v[182:185], v[206:209], v[58:61]
	v_mfma_f32_16x16x32_bf16 v[46:49], v[170:173], v[214:217], v[46:49]
	v_mfma_f32_16x16x32_bf16 v[42:45], v[182:185], v[214:217], v[42:45]
	v_mfma_f32_16x16x32_bf16 v[30:33], v[170:173], v[222:225], v[30:33]
	v_mfma_f32_16x16x32_bf16 v[26:29], v[182:185], v[222:225], v[26:29]
	v_mfma_f32_16x16x32_bf16 v[14:17], v[170:173], v[230:233], v[14:17]
	v_mfma_f32_16x16x32_bf16 v[10:13], v[182:185], v[230:233], v[10:13]
	s_setprio 0
	s_setprio 1
	v_mfma_f32_16x16x32_bf16 v[54:57], v[186:189], v[202:205], 0
	v_mfma_f32_16x16x32_bf16 v[50:53], v[194:197], v[202:205], 0
	v_mfma_f32_16x16x32_bf16 v[38:41], v[186:189], v[210:213], 0
	v_mfma_f32_16x16x32_bf16 v[34:37], v[194:197], v[210:213], 0
	v_mfma_f32_16x16x32_bf16 v[22:25], v[186:189], v[218:221], 0
	v_mfma_f32_16x16x32_bf16 v[18:21], v[194:197], v[218:221], 0
	v_mfma_f32_16x16x32_bf16 v[6:9], v[186:189], v[226:229], 0
	v_mfma_f32_16x16x32_bf16 v[2:5], v[194:197], v[226:229], 0
	v_mfma_f32_16x16x32_bf16 v[54:57], v[190:193], v[206:209], v[54:57]
	v_mfma_f32_16x16x32_bf16 v[50:53], v[198:201], v[206:209], v[50:53]
	v_mfma_f32_16x16x32_bf16 v[38:41], v[190:193], v[214:217], v[38:41]
	v_mfma_f32_16x16x32_bf16 v[34:37], v[198:201], v[214:217], v[34:37]
	v_mfma_f32_16x16x32_bf16 v[22:25], v[190:193], v[222:225], v[22:25]
	v_mfma_f32_16x16x32_bf16 v[18:21], v[198:201], v[222:225], v[18:21]
	v_mfma_f32_16x16x32_bf16 v[6:9], v[190:193], v[230:233], v[6:9]
	v_mfma_f32_16x16x32_bf16 v[2:5], v[198:201], v[230:233], v[2:5]
	s_setprio 0
	s_barrier
	s_add_i32 s53, 0, 0x18000
	v_add_u32_e32 v176, s53, v163
	s_add_i32 s54, 0, 0x1c000
	ds_read_b128 v[166:169], v176
	ds_read_b128 v[170:173], v176 offset:1024
	ds_read_b128 v[178:181], v176 offset:2048
	ds_read_b128 v[182:185], v176 offset:3072
	v_add_u32_e32 v176, s54, v163
	ds_read_b128 v[186:189], v176
	ds_read_b128 v[190:193], v176 offset:1024
	ds_read_b128 v[194:197], v176 offset:2048
	ds_read_b128 v[198:201], v176 offset:3072
	s_add_u32 s2, s2, 0x40000
	s_addc_u32 s3, s3, 0
	s_mov_b32 m0, s35
	v_lshl_add_u64 v[238:239], s[2:3], 0, v[130:131]
	ds_read_b128 v[202:205], v165 offset:32768
	ds_read_b128 v[206:209], v165 offset:33792
	ds_read_b128 v[210:213], v165 offset:34816
	ds_read_b128 v[214:217], v165 offset:35840
	ds_read_b128 v[218:221], v165 offset:36864
	ds_read_b128 v[222:225], v165 offset:37888
	ds_read_b128 v[226:229], v165 offset:38912
	ds_read_b128 v[230:233], v165 offset:39936
	global_load_lds_dwordx4 v[238:239], off
	v_lshl_add_u64 v[238:239], s[2:3], 0, v[134:135]
	s_mov_b32 m0, s36
	s_nop 0
	global_load_lds_dwordx4 v[238:239], off
	s_waitcnt vmcnt(8)
	s_waitcnt lgkmcnt(0)
	s_barrier
	s_setprio 1
	s_waitcnt lgkmcnt(0)
	v_mfma_f32_16x16x32_bf16 v[126:129], v[166:169], v[202:205], v[126:129]
	v_mfma_f32_16x16x32_bf16 v[122:125], v[178:181], v[202:205], v[122:125]
	v_mfma_f32_16x16x32_bf16 v[110:113], v[166:169], v[210:213], v[110:113]
	v_mfma_f32_16x16x32_bf16 v[106:109], v[178:181], v[210:213], v[106:109]
	v_mfma_f32_16x16x32_bf16 v[94:97], v[166:169], v[218:221], v[94:97]
	v_mfma_f32_16x16x32_bf16 v[90:93], v[178:181], v[218:221], v[90:93]
	v_mfma_f32_16x16x32_bf16 v[78:81], v[166:169], v[226:229], v[78:81]
	v_mfma_f32_16x16x32_bf16 v[74:77], v[178:181], v[226:229], v[74:77]
	v_mfma_f32_16x16x32_bf16 v[126:129], v[170:173], v[206:209], v[126:129]
	v_mfma_f32_16x16x32_bf16 v[122:125], v[182:185], v[206:209], v[122:125]
	v_mfma_f32_16x16x32_bf16 v[110:113], v[170:173], v[214:217], v[110:113]
	v_mfma_f32_16x16x32_bf16 v[106:109], v[182:185], v[214:217], v[106:109]
	v_mfma_f32_16x16x32_bf16 v[94:97], v[170:173], v[222:225], v[94:97]
	v_mfma_f32_16x16x32_bf16 v[90:93], v[182:185], v[222:225], v[90:93]
	v_mfma_f32_16x16x32_bf16 v[78:81], v[170:173], v[230:233], v[78:81]
	v_mfma_f32_16x16x32_bf16 v[74:77], v[182:185], v[230:233], v[74:77]
	s_setprio 0
	s_setprio 1
	v_mfma_f32_16x16x32_bf16 v[118:121], v[186:189], v[202:205], v[118:121]
	v_mfma_f32_16x16x32_bf16 v[114:117], v[194:197], v[202:205], v[114:117]
	v_mfma_f32_16x16x32_bf16 v[102:105], v[186:189], v[210:213], v[102:105]
	v_mfma_f32_16x16x32_bf16 v[98:101], v[194:197], v[210:213], v[98:101]
	v_mfma_f32_16x16x32_bf16 v[86:89], v[186:189], v[218:221], v[86:89]
	v_mfma_f32_16x16x32_bf16 v[82:85], v[194:197], v[218:221], v[82:85]
	v_mfma_f32_16x16x32_bf16 v[70:73], v[186:189], v[226:229], v[70:73]
	v_mfma_f32_16x16x32_bf16 v[66:69], v[194:197], v[226:229], v[66:69]
	v_mfma_f32_16x16x32_bf16 v[118:121], v[190:193], v[206:209], v[118:121]
	v_mfma_f32_16x16x32_bf16 v[114:117], v[198:201], v[206:209], v[114:117]
	v_mfma_f32_16x16x32_bf16 v[102:105], v[190:193], v[214:217], v[102:105]
	v_mfma_f32_16x16x32_bf16 v[98:101], v[198:201], v[214:217], v[98:101]
	v_mfma_f32_16x16x32_bf16 v[86:89], v[190:193], v[222:225], v[86:89]
	v_mfma_f32_16x16x32_bf16 v[82:85], v[198:201], v[222:225], v[82:85]
	v_mfma_f32_16x16x32_bf16 v[70:73], v[190:193], v[230:233], v[70:73]
	v_mfma_f32_16x16x32_bf16 v[66:69], v[198:201], v[230:233], v[66:69]
	s_setprio 0
	s_barrier
	s_add_i32 s2, s53, s30
	v_lshl_add_u64 v[148:149], v[148:149], 0, s[6:7]
	s_mov_b32 m0, s2
	ds_read_b128 v[202:205], v165 offset:49152
	ds_read_b128 v[206:209], v165 offset:50176
	ds_read_b128 v[210:213], v165 offset:51200
	ds_read_b128 v[214:217], v165 offset:52224
	ds_read_b128 v[218:221], v165 offset:53248
	ds_read_b128 v[222:225], v165 offset:54272
	ds_read_b128 v[226:229], v165 offset:55296
	ds_read_b128 v[230:233], v165 offset:56320
	global_load_lds_dwordx4 v[148:149], off
	s_add_i32 m0, s2, 0x2000
	s_add_u32 s2, s28, 0x40080
	v_lshl_add_u64 v[148:149], v[174:175], 0, s[6:7]
	s_addc_u32 s3, s29, 0
	s_add_i32 s28, s54, s30
	global_load_lds_dwordx4 v[148:149], off
	v_lshl_add_u64 v[148:149], s[2:3], 0, v[132:133]
	s_mov_b32 m0, s28
	s_nop 0
	global_load_lds_dwordx4 v[148:149], off
	v_lshl_add_u64 v[148:149], s[2:3], 0, v[136:137]
	s_add_i32 m0, s28, 0x2000
	s_nop 0
	global_load_lds_dwordx4 v[148:149], off
	v_lshl_add_u64 v[148:149], v[234:235], 0, s[6:7]
	s_mov_b32 m0, s38
	s_nop 0
	global_load_lds_dwordx4 v[148:149], off
	v_lshl_add_u64 v[148:149], v[236:237], 0, s[6:7]
	s_mov_b32 m0, s39
	s_nop 0
	global_load_lds_dwordx4 v[148:149], off
	s_waitcnt vmcnt(8)
	s_waitcnt lgkmcnt(0)
	s_barrier
	s_setprio 1
	s_waitcnt lgkmcnt(0)
	v_mfma_f32_16x16x32_bf16 v[62:65], v[166:169], v[202:205], v[62:65]
	v_mfma_f32_16x16x32_bf16 v[58:61], v[178:181], v[202:205], v[58:61]
	v_mfma_f32_16x16x32_bf16 v[46:49], v[166:169], v[210:213], v[46:49]
	v_mfma_f32_16x16x32_bf16 v[42:45], v[178:181], v[210:213], v[42:45]
	v_mfma_f32_16x16x32_bf16 v[30:33], v[166:169], v[218:221], v[30:33]
	v_mfma_f32_16x16x32_bf16 v[26:29], v[178:181], v[218:221], v[26:29]
	v_mfma_f32_16x16x32_bf16 v[14:17], v[166:169], v[226:229], v[14:17]
	v_mfma_f32_16x16x32_bf16 v[10:13], v[178:181], v[226:229], v[10:13]
	v_mfma_f32_16x16x32_bf16 v[62:65], v[170:173], v[206:209], v[62:65]
	v_mfma_f32_16x16x32_bf16 v[58:61], v[182:185], v[206:209], v[58:61]
	v_mfma_f32_16x16x32_bf16 v[46:49], v[170:173], v[214:217], v[46:49]
	v_mfma_f32_16x16x32_bf16 v[42:45], v[182:185], v[214:217], v[42:45]
	v_mfma_f32_16x16x32_bf16 v[30:33], v[170:173], v[222:225], v[30:33]
	v_mfma_f32_16x16x32_bf16 v[26:29], v[182:185], v[222:225], v[26:29]
	v_mfma_f32_16x16x32_bf16 v[14:17], v[170:173], v[230:233], v[14:17]
	v_mfma_f32_16x16x32_bf16 v[10:13], v[182:185], v[230:233], v[10:13]
	s_setprio 0
	s_setprio 1
	v_mfma_f32_16x16x32_bf16 v[54:57], v[186:189], v[202:205], v[54:57]
	v_mfma_f32_16x16x32_bf16 v[50:53], v[194:197], v[202:205], v[50:53]
	v_mfma_f32_16x16x32_bf16 v[38:41], v[186:189], v[210:213], v[38:41]
	v_mfma_f32_16x16x32_bf16 v[34:37], v[194:197], v[210:213], v[34:37]
	v_mfma_f32_16x16x32_bf16 v[22:25], v[186:189], v[218:221], v[22:25]
	v_mfma_f32_16x16x32_bf16 v[18:21], v[194:197], v[218:221], v[18:21]
	v_mfma_f32_16x16x32_bf16 v[6:9], v[186:189], v[226:229], v[6:9]
	v_mfma_f32_16x16x32_bf16 v[2:5], v[194:197], v[226:229], v[2:5]
	v_mfma_f32_16x16x32_bf16 v[54:57], v[190:193], v[206:209], v[54:57]
	v_mfma_f32_16x16x32_bf16 v[50:53], v[198:201], v[206:209], v[50:53]
	v_mfma_f32_16x16x32_bf16 v[38:41], v[190:193], v[214:217], v[38:41]
	v_mfma_f32_16x16x32_bf16 v[34:37], v[198:201], v[214:217], v[34:37]
	v_mfma_f32_16x16x32_bf16 v[22:25], v[190:193], v[222:225], v[22:25]
	v_mfma_f32_16x16x32_bf16 v[18:21], v[198:201], v[222:225], v[18:21]
	v_mfma_f32_16x16x32_bf16 v[6:9], v[190:193], v[230:233], v[6:9]
	v_mfma_f32_16x16x32_bf16 v[2:5], v[198:201], v[230:233], v[2:5]
	s_setprio 0
	s_barrier
	s_add_i32 s52, s52, 2
	s_add_u32 s26, s26, 0x100
	s_addc_u32 s27, s27, 0
	s_add_u32 s46, s46, 0x100
	s_addc_u32 s47, s47, 0
	s_cmp_gt_u32 s52, 13
	s_cbranch_scc0 .LBB0_354
	s_branch .Lpk354_exit

.LBB0_444:
	s_mov_b64 s[6:7], 0x80
	s_add_i32 m0, s25, 0x18000
	v_lshl_add_u64 v[8:9], v[8:9], 0, s[6:7]
	s_and_b32 s9, s3, 3
	s_lshl_b32 s12, s8, 13
	s_waitcnt vmcnt(2)
	s_barrier
	global_load_lds_dwordx4 v[8:9], off
	v_lshl_add_u64 v[4:5], v[4:5], 0, s[6:7]
	s_add_i32 m0, s25, 0x1a000
	s_add_i32 s39, s25, 0x8000
	s_add_i32 s40, s25, 0xa000
	global_load_lds_dwordx4 v[4:5], off
	v_lshl_add_u64 v[2:3], v[2:3], 0, s[6:7]
	s_mov_b32 m0, s39
	s_add_u32 s10, s30, 0x40080
	global_load_lds_dwordx4 v[2:3], off
	v_lshl_add_u64 v[2:3], v[6:7], 0, s[6:7]
	s_mov_b32 m0, s40
	s_addc_u32 s11, s31, 0
	global_load_lds_dwordx4 v[2:3], off
	s_add_i32 m0, s25, 0x1c000
	v_lshl_add_u64 v[2:3], s[10:11], 0, v[132:133]
	global_load_lds_dwordx4 v[2:3], off
	v_lshl_add_u64 v[2:3], s[10:11], 0, v[136:137]
	s_add_i32 m0, s25, 0x1e000
	s_cmpk_lt_u32 s2, 0x100
	global_load_lds_dwordx4 v[2:3], off
	v_lshl_or_b32 v2, s8, 6, v156
	v_lshl_or_b32 v148, s9, 12, v157
	s_cselect_b64 s[8:9], -1, 0
	s_lshl_b32 s2, s3, 6
	v_lshlrev_b32_e32 v4, 2, v156
	s_bfe_u32 s41, s3, 0x10001
	s_and_b32 s2, s2, 64
	v_readlane_b32 s3, v253, 54
	v_lshl_or_b32 v3, v156, 6, v138
	v_and_b32_e32 v4, 32, v4
	s_add_u32 s2, s3, s2
	v_readlane_b32 s3, v253, 7
	v_bitop3_b32 v6, v3, s12, v4 bitop3:0xde
	v_mov_b32_e32 v3, v133
	s_addc_u32 s3, s3, 0
	v_mov_b32_e32 v139, v133
	v_lshl_add_u64 v[4:5], s[2:3], 0, v[138:139]
	v_lshlrev_b64 v[2:3], 7, v[2:3]
	v_lshl_add_u64 v[138:139], v[4:5], 0, v[2:3]
	v_lshlrev_b32_e32 v2, 8, v0
	v_and_b32_e32 v2, 0x18000, v2
	v_lshlrev_b32_e32 v3, 11, v154
	v_or3_b32 v2, v152, v2, v3
	v_add_u32_e32 v140, v2, v153
	v_lshlrev_b32_e32 v2, 4, v155
	s_waitcnt vmcnt(6)
	v_and_b32_e32 v2, 0x38000, v2
	v_or3_b32 v2, v152, v2, v3
	s_add_i32 s42, 0, 0x10000
	s_add_i32 s43, 0, 0x14000
	v_mov_b32_e32 v141, v133
	v_add_u32_e32 v142, v2, v153
	v_mov_b32_e32 v143, v133
	v_add_u32_e32 v149, s42, v148
	v_add_u32_e32 v150, s43, v148
	v_add_u32_e32 v151, 0, v6
	v_mov_b64_e32 v[144:145], 0xaff
	s_barrier
	s_waitcnt vmcnt(0)
	s_branch .LBB0_447

.Lpk451_peel:
	ds_read_b128 v[152:155], v149
	ds_read_b128 v[156:159], v149 offset:1024
	ds_read_b128 v[160:163], v149 offset:2048
	ds_read_b128 v[164:167], v149 offset:3072
	ds_read_b128 v[168:171], v150
	ds_read_b128 v[172:175], v150 offset:1024
	ds_read_b128 v[178:181], v150 offset:2048
	ds_read_b128 v[182:185], v150 offset:3072
	s_add_u32 s2, s28, 0xfffc0080
	s_addc_u32 s3, s29, -1
	s_cmp_eq_u32 s52, 12
	s_cselect_b32 s3, s11, s3
	s_cselect_b32 s2, s13, s2
	s_cselect_b32 s31, s44, s47
	s_cselect_b32 s30, s45, s46
	v_lshl_add_u64 v[146:147], s[28:29], 0, v[140:141]
	s_add_i32 m0, s25, 0xc000
	ds_read_b128 v[186:189], v151
	ds_read_b128 v[190:193], v151 offset:1024
	ds_read_b128 v[194:197], v151 offset:2048
	ds_read_b128 v[198:201], v151 offset:3072
	ds_read_b128 v[202:205], v151 offset:4096
	ds_read_b128 v[206:209], v151 offset:5120
	ds_read_b128 v[210:213], v151 offset:6144
	ds_read_b128 v[214:217], v151 offset:7168
	global_load_lds_dwordx4 v[146:147], off
	v_lshl_add_u64 v[146:147], s[28:29], 0, v[142:143]
	s_add_i32 m0, s25, 0xe000
	s_nop 0
	global_load_lds_dwordx4 v[146:147], off
	s_waitcnt vmcnt(16)
	s_waitcnt lgkmcnt(0)
	s_barrier
	s_setprio 1
	s_waitcnt lgkmcnt(0)
	v_mfma_f32_16x16x32_bf16 v[126:129], v[152:155], v[186:189], 0
	v_mfma_f32_16x16x32_bf16 v[122:125], v[160:163], v[186:189], 0
	v_mfma_f32_16x16x32_bf16 v[110:113], v[152:155], v[194:197], 0
	v_mfma_f32_16x16x32_bf16 v[106:109], v[160:163], v[194:197], 0
	v_mfma_f32_16x16x32_bf16 v[94:97], v[152:155], v[202:205], 0
	v_mfma_f32_16x16x32_bf16 v[90:93], v[160:163], v[202:205], 0
	v_mfma_f32_16x16x32_bf16 v[78:81], v[152:155], v[210:213], 0
	v_mfma_f32_16x16x32_bf16 v[74:77], v[160:163], v[210:213], 0
	v_mfma_f32_16x16x32_bf16 v[126:129], v[156:159], v[190:193], v[126:129]
	v_mfma_f32_16x16x32_bf16 v[122:125], v[164:167], v[190:193], v[122:125]
	v_mfma_f32_16x16x32_bf16 v[110:113], v[156:159], v[198:201], v[110:113]
	v_mfma_f32_16x16x32_bf16 v[106:109], v[164:167], v[198:201], v[106:109]
	v_mfma_f32_16x16x32_bf16 v[94:97], v[156:159], v[206:209], v[94:97]
	v_mfma_f32_16x16x32_bf16 v[90:93], v[164:167], v[206:209], v[90:93]
	v_mfma_f32_16x16x32_bf16 v[78:81], v[156:159], v[214:217], v[78:81]
	v_mfma_f32_16x16x32_bf16 v[74:77], v[164:167], v[214:217], v[74:77]
	s_setprio 0
	s_setprio 1
	v_mfma_f32_16x16x32_bf16 v[118:121], v[168:171], v[186:189], 0
	v_mfma_f32_16x16x32_bf16 v[114:117], v[178:181], v[186:189], 0
	v_mfma_f32_16x16x32_bf16 v[102:105], v[168:171], v[194:197], 0
	v_mfma_f32_16x16x32_bf16 v[98:101], v[178:181], v[194:197], 0
	v_mfma_f32_16x16x32_bf16 v[86:89], v[168:171], v[202:205], 0
	v_mfma_f32_16x16x32_bf16 v[82:85], v[178:181], v[202:205], 0
	v_mfma_f32_16x16x32_bf16 v[70:73], v[168:171], v[210:213], 0
	v_mfma_f32_16x16x32_bf16 v[66:69], v[178:181], v[210:213], 0
	v_mfma_f32_16x16x32_bf16 v[118:121], v[172:175], v[190:193], v[118:121]
	v_mfma_f32_16x16x32_bf16 v[114:117], v[182:185], v[190:193], v[114:117]
	v_mfma_f32_16x16x32_bf16 v[102:105], v[172:175], v[198:201], v[102:105]
	v_mfma_f32_16x16x32_bf16 v[98:101], v[182:185], v[198:201], v[98:101]
	v_mfma_f32_16x16x32_bf16 v[86:89], v[172:175], v[206:209], v[86:89]
	v_mfma_f32_16x16x32_bf16 v[82:85], v[182:185], v[206:209], v[82:85]
	v_mfma_f32_16x16x32_bf16 v[70:73], v[172:175], v[214:217], v[70:73]
	v_mfma_f32_16x16x32_bf16 v[66:69], v[182:185], v[214:217], v[66:69]
	s_setprio 0
	s_barrier
	s_add_i32 s53, s42, s34
	v_lshl_add_u64 v[146:147], s[30:31], 0, v[132:133]
	s_mov_b32 m0, s53
	ds_read_b128 v[186:189], v151 offset:16384
	ds_read_b128 v[190:193], v151 offset:17408
	ds_read_b128 v[194:197], v151 offset:18432
	ds_read_b128 v[198:201], v151 offset:19456
	ds_read_b128 v[202:205], v151 offset:20480
	ds_read_b128 v[206:209], v151 offset:21504
	ds_read_b128 v[210:213], v151 offset:22528
	ds_read_b128 v[214:217], v151 offset:23552
	global_load_lds_dwordx4 v[146:147], off
	s_add_i32 m0, s53, 0x2000
	s_add_u32 s54, s30, 0x40000
	v_lshl_add_u64 v[218:219], s[30:31], 0, v[136:137]
	s_addc_u32 s55, s31, 0
	s_add_i32 s53, s43, s34
	global_load_lds_dwordx4 v[218:219], off
	v_lshl_add_u64 v[220:221], s[54:55], 0, v[132:133]
	s_mov_b32 m0, s53
	v_lshl_add_u64 v[222:223], s[2:3], 0, v[134:135]
	global_load_lds_dwordx4 v[220:221], off
	v_lshl_add_u64 v[220:221], s[54:55], 0, v[136:137]
	s_add_i32 m0, s53, 0x2000
	s_nop 0
	global_load_lds_dwordx4 v[220:221], off
	v_lshl_add_u64 v[220:221], s[2:3], 0, v[130:131]
	s_mov_b32 m0, s25
	s_nop 0
	global_load_lds_dwordx4 v[220:221], off
	s_mov_b32 m0, s27
	s_nop 0
	global_load_lds_dwordx4 v[222:223], off
	s_waitcnt vmcnt(16)
	s_waitcnt lgkmcnt(0)
	s_barrier
	s_setprio 1
	s_waitcnt lgkmcnt(0)
	v_mfma_f32_16x16x32_bf16 v[62:65], v[152:155], v[186:189], 0
	v_mfma_f32_16x16x32_bf16 v[58:61], v[160:163], v[186:189], 0
	v_mfma_f32_16x16x32_bf16 v[46:49], v[152:155], v[194:197], 0
	v_mfma_f32_16x16x32_bf16 v[42:45], v[160:163], v[194:197], 0
	v_mfma_f32_16x16x32_bf16 v[30:33], v[152:155], v[202:205], 0
	v_mfma_f32_16x16x32_bf16 v[26:29], v[160:163], v[202:205], 0
	v_mfma_f32_16x16x32_bf16 v[14:17], v[152:155], v[210:213], 0
	v_mfma_f32_16x16x32_bf16 v[10:13], v[160:163], v[210:213], 0
	v_mfma_f32_16x16x32_bf16 v[62:65], v[156:159], v[190:193], v[62:65]
	v_mfma_f32_16x16x32_bf16 v[58:61], v[164:167], v[190:193], v[58:61]
	v_mfma_f32_16x16x32_bf16 v[46:49], v[156:159], v[198:201], v[46:49]
	v_mfma_f32_16x16x32_bf16 v[42:45], v[164:167], v[198:201], v[42:45]
	v_mfma_f32_16x16x32_bf16 v[30:33], v[156:159], v[206:209], v[30:33]
	v_mfma_f32_16x16x32_bf16 v[26:29], v[164:167], v[206:209], v[26:29]
	v_mfma_f32_16x16x32_bf16 v[14:17], v[156:159], v[214:217], v[14:17]
	v_mfma_f32_16x16x32_bf16 v[10:13], v[164:167], v[214:217], v[10:13]
	s_setprio 0
	s_setprio 1
	v_mfma_f32_16x16x32_bf16 v[54:57], v[168:171], v[186:189], 0
	v_mfma_f32_16x16x32_bf16 v[50:53], v[178:181], v[186:189], 0
	v_mfma_f32_16x16x32_bf16 v[38:41], v[168:171], v[194:197], 0
	v_mfma_f32_16x16x32_bf16 v[34:37], v[178:181], v[194:197], 0
	v_mfma_f32_16x16x32_bf16 v[22:25], v[168:171], v[202:205], 0
	v_mfma_f32_16x16x32_bf16 v[18:21], v[178:181], v[202:205], 0
	v_mfma_f32_16x16x32_bf16 v[6:9], v[168:171], v[210:213], 0
	v_mfma_f32_16x16x32_bf16 v[2:5], v[178:181], v[210:213], 0
	v_mfma_f32_16x16x32_bf16 v[54:57], v[172:175], v[190:193], v[54:57]
	v_mfma_f32_16x16x32_bf16 v[50:53], v[182:185], v[190:193], v[50:53]
	v_mfma_f32_16x16x32_bf16 v[38:41], v[172:175], v[198:201], v[38:41]
	v_mfma_f32_16x16x32_bf16 v[34:37], v[182:185], v[198:201], v[34:37]
	v_mfma_f32_16x16x32_bf16 v[22:25], v[172:175], v[206:209], v[22:25]
	v_mfma_f32_16x16x32_bf16 v[18:21], v[182:185], v[206:209], v[18:21]
	v_mfma_f32_16x16x32_bf16 v[6:9], v[172:175], v[214:217], v[6:9]
	v_mfma_f32_16x16x32_bf16 v[2:5], v[182:185], v[214:217], v[2:5]
	s_setprio 0
	s_barrier
	s_add_i32 s53, 0, 0x18000
	s_add_i32 s54, 0, 0x1c000
	v_add_u32_e32 v164, s53, v148
	v_add_u32_e32 v176, s54, v148
	ds_read_b128 v[152:155], v164
	ds_read_b128 v[156:159], v164 offset:1024
	ds_read_b128 v[160:163], v164 offset:2048
	ds_read_b128 v[164:167], v164 offset:3072
	ds_read_b128 v[168:171], v176
	ds_read_b128 v[172:175], v176 offset:1024
	ds_read_b128 v[178:181], v176 offset:2048
	ds_read_b128 v[182:185], v176 offset:3072
	s_add_u32 s2, s2, 0x40000
	s_addc_u32 s3, s3, 0
	s_mov_b32 m0, s36
	v_lshl_add_u64 v[224:225], s[2:3], 0, v[130:131]
	ds_read_b128 v[186:189], v151 offset:32768
	ds_read_b128 v[190:193], v151 offset:33792
	ds_read_b128 v[194:197], v151 offset:34816
	ds_read_b128 v[198:201], v151 offset:35840
	ds_read_b128 v[202:205], v151 offset:36864
	ds_read_b128 v[206:209], v151 offset:37888
	ds_read_b128 v[210:213], v151 offset:38912
	ds_read_b128 v[214:217], v151 offset:39936
	global_load_lds_dwordx4 v[224:225], off
	v_lshl_add_u64 v[224:225], s[2:3], 0, v[134:135]
	s_mov_b32 m0, s37
	s_nop 0
	global_load_lds_dwordx4 v[224:225], off
	s_waitcnt vmcnt(8)
	s_waitcnt lgkmcnt(0)
	s_barrier
	s_setprio 1
	s_waitcnt lgkmcnt(0)
	v_mfma_f32_16x16x32_bf16 v[126:129], v[152:155], v[186:189], v[126:129]
	v_mfma_f32_16x16x32_bf16 v[122:125], v[160:163], v[186:189], v[122:125]
	v_mfma_f32_16x16x32_bf16 v[110:113], v[152:155], v[194:197], v[110:113]
	v_mfma_f32_16x16x32_bf16 v[106:109], v[160:163], v[194:197], v[106:109]
	v_mfma_f32_16x16x32_bf16 v[94:97], v[152:155], v[202:205], v[94:97]
	v_mfma_f32_16x16x32_bf16 v[90:93], v[160:163], v[202:205], v[90:93]
	v_mfma_f32_16x16x32_bf16 v[78:81], v[152:155], v[210:213], v[78:81]
	v_mfma_f32_16x16x32_bf16 v[74:77], v[160:163], v[210:213], v[74:77]
	v_mfma_f32_16x16x32_bf16 v[126:129], v[156:159], v[190:193], v[126:129]
	v_mfma_f32_16x16x32_bf16 v[122:125], v[164:167], v[190:193], v[122:125]
	v_mfma_f32_16x16x32_bf16 v[110:113], v[156:159], v[198:201], v[110:113]
	v_mfma_f32_16x16x32_bf16 v[106:109], v[164:167], v[198:201], v[106:109]
	v_mfma_f32_16x16x32_bf16 v[94:97], v[156:159], v[206:209], v[94:97]
	v_mfma_f32_16x16x32_bf16 v[90:93], v[164:167], v[206:209], v[90:93]
	v_mfma_f32_16x16x32_bf16 v[78:81], v[156:159], v[214:217], v[78:81]
	v_mfma_f32_16x16x32_bf16 v[74:77], v[164:167], v[214:217], v[74:77]
	s_setprio 0
	s_setprio 1
	v_mfma_f32_16x16x32_bf16 v[118:121], v[168:171], v[186:189], v[118:121]
	v_mfma_f32_16x16x32_bf16 v[114:117], v[178:181], v[186:189], v[114:117]
	v_mfma_f32_16x16x32_bf16 v[102:105], v[168:171], v[194:197], v[102:105]
	v_mfma_f32_16x16x32_bf16 v[98:101], v[178:181], v[194:197], v[98:101]
	v_mfma_f32_16x16x32_bf16 v[86:89], v[168:171], v[202:205], v[86:89]
	v_mfma_f32_16x16x32_bf16 v[82:85], v[178:181], v[202:205], v[82:85]
	v_mfma_f32_16x16x32_bf16 v[70:73], v[168:171], v[210:213], v[70:73]
	v_mfma_f32_16x16x32_bf16 v[66:69], v[178:181], v[210:213], v[66:69]
	v_mfma_f32_16x16x32_bf16 v[118:121], v[172:175], v[190:193], v[118:121]
	v_mfma_f32_16x16x32_bf16 v[114:117], v[182:185], v[190:193], v[114:117]
	v_mfma_f32_16x16x32_bf16 v[102:105], v[172:175], v[198:201], v[102:105]
	v_mfma_f32_16x16x32_bf16 v[98:101], v[182:185], v[198:201], v[98:101]
	v_mfma_f32_16x16x32_bf16 v[86:89], v[172:175], v[206:209], v[86:89]
	v_mfma_f32_16x16x32_bf16 v[82:85], v[182:185], v[206:209], v[82:85]
	v_mfma_f32_16x16x32_bf16 v[70:73], v[172:175], v[214:217], v[70:73]
	v_mfma_f32_16x16x32_bf16 v[66:69], v[182:185], v[214:217], v[66:69]
	s_setprio 0
	s_barrier
	s_add_i32 s2, s53, s34
	v_lshl_add_u64 v[146:147], v[146:147], 0, s[6:7]
	s_mov_b32 m0, s2
	ds_read_b128 v[186:189], v151 offset:49152
	ds_read_b128 v[190:193], v151 offset:50176
	ds_read_b128 v[194:197], v151 offset:51200
	ds_read_b128 v[198:201], v151 offset:52224
	ds_read_b128 v[202:205], v151 offset:53248
	ds_read_b128 v[206:209], v151 offset:54272
	ds_read_b128 v[210:213], v151 offset:55296
	ds_read_b128 v[214:217], v151 offset:56320
	global_load_lds_dwordx4 v[146:147], off
	s_add_i32 m0, s2, 0x2000
	s_add_u32 s2, s30, 0x40080
	v_lshl_add_u64 v[146:147], v[218:219], 0, s[6:7]
	s_addc_u32 s3, s31, 0
	s_add_i32 s30, s54, s34
	global_load_lds_dwordx4 v[146:147], off
	v_lshl_add_u64 v[146:147], s[2:3], 0, v[132:133]
	s_mov_b32 m0, s30
	s_nop 0
	global_load_lds_dwordx4 v[146:147], off
	v_lshl_add_u64 v[146:147], s[2:3], 0, v[136:137]
	s_add_i32 m0, s30, 0x2000
	s_nop 0
	global_load_lds_dwordx4 v[146:147], off
	v_lshl_add_u64 v[146:147], v[220:221], 0, s[6:7]
	s_mov_b32 m0, s39
	s_nop 0
	global_load_lds_dwordx4 v[146:147], off
	v_lshl_add_u64 v[146:147], v[222:223], 0, s[6:7]
	s_mov_b32 m0, s40
	s_nop 0
	global_load_lds_dwordx4 v[146:147], off
	s_waitcnt vmcnt(8)
	s_waitcnt lgkmcnt(0)
	s_barrier
	s_setprio 1
	s_waitcnt lgkmcnt(0)
	v_mfma_f32_16x16x32_bf16 v[62:65], v[152:155], v[186:189], v[62:65]
	v_mfma_f32_16x16x32_bf16 v[58:61], v[160:163], v[186:189], v[58:61]
	v_mfma_f32_16x16x32_bf16 v[46:49], v[152:155], v[194:197], v[46:49]
	v_mfma_f32_16x16x32_bf16 v[42:45], v[160:163], v[194:197], v[42:45]
	v_mfma_f32_16x16x32_bf16 v[30:33], v[152:155], v[202:205], v[30:33]
	v_mfma_f32_16x16x32_bf16 v[26:29], v[160:163], v[202:205], v[26:29]
	v_mfma_f32_16x16x32_bf16 v[14:17], v[152:155], v[210:213], v[14:17]
	v_mfma_f32_16x16x32_bf16 v[10:13], v[160:163], v[210:213], v[10:13]
	v_mfma_f32_16x16x32_bf16 v[62:65], v[156:159], v[190:193], v[62:65]
	v_mfma_f32_16x16x32_bf16 v[58:61], v[164:167], v[190:193], v[58:61]
	v_mfma_f32_16x16x32_bf16 v[46:49], v[156:159], v[198:201], v[46:49]
	v_mfma_f32_16x16x32_bf16 v[42:45], v[164:167], v[198:201], v[42:45]
	v_mfma_f32_16x16x32_bf16 v[30:33], v[156:159], v[206:209], v[30:33]
	v_mfma_f32_16x16x32_bf16 v[26:29], v[164:167], v[206:209], v[26:29]
	v_mfma_f32_16x16x32_bf16 v[14:17], v[156:159], v[214:217], v[14:17]
	v_mfma_f32_16x16x32_bf16 v[10:13], v[164:167], v[214:217], v[10:13]
	s_setprio 0
	s_setprio 1
	v_mfma_f32_16x16x32_bf16 v[54:57], v[168:171], v[186:189], v[54:57]
	v_mfma_f32_16x16x32_bf16 v[50:53], v[178:181], v[186:189], v[50:53]
	v_mfma_f32_16x16x32_bf16 v[38:41], v[168:171], v[194:197], v[38:41]
	v_mfma_f32_16x16x32_bf16 v[34:37], v[178:181], v[194:197], v[34:37]
	v_mfma_f32_16x16x32_bf16 v[22:25], v[168:171], v[202:205], v[22:25]
	v_mfma_f32_16x16x32_bf16 v[18:21], v[178:181], v[202:205], v[18:21]
	v_mfma_f32_16x16x32_bf16 v[6:9], v[168:171], v[210:213], v[6:9]
	v_mfma_f32_16x16x32_bf16 v[2:5], v[178:181], v[210:213], v[2:5]
	v_mfma_f32_16x16x32_bf16 v[54:57], v[172:175], v[190:193], v[54:57]
	v_mfma_f32_16x16x32_bf16 v[50:53], v[182:185], v[190:193], v[50:53]
	v_mfma_f32_16x16x32_bf16 v[38:41], v[172:175], v[198:201], v[38:41]
	v_mfma_f32_16x16x32_bf16 v[34:37], v[182:185], v[198:201], v[34:37]
	v_mfma_f32_16x16x32_bf16 v[22:25], v[172:175], v[206:209], v[22:25]
	v_mfma_f32_16x16x32_bf16 v[18:21], v[182:185], v[206:209], v[18:21]
	v_mfma_f32_16x16x32_bf16 v[6:9], v[172:175], v[214:217], v[6:9]
	v_mfma_f32_16x16x32_bf16 v[2:5], v[182:185], v[214:217], v[2:5]
	s_setprio 0
	s_barrier
	s_add_i32 s52, s52, 2
	s_add_u32 s28, s28, 0x100
	s_addc_u32 s29, s29, 0
	s_add_u32 s46, s46, 0x100
	s_addc_u32 s47, s47, 0
	s_cmp_gt_u32 s52, 13
	s_cbranch_scc0 .LBB0_451
	s_branch .Lpk451_exit

.Lpk495_peel:
	ds_read_b128 v[152:155], v149
	ds_read_b128 v[156:159], v149 offset:1024
	ds_read_b128 v[160:163], v149 offset:2048
	ds_read_b128 v[164:167], v149 offset:3072
	ds_read_b128 v[168:171], v150
	ds_read_b128 v[172:175], v150 offset:1024
	ds_read_b128 v[178:181], v150 offset:2048
	ds_read_b128 v[182:185], v150 offset:3072
	s_add_u32 s2, s18, 0x4000
	s_addc_u32 s3, s19, 0
	s_cmp_eq_u32 s50, 40
	s_cselect_b32 s2, s45, s2
	s_cselect_b32 s3, s44, s3
	s_cselect_b32 s23, s46, s49
	s_cselect_b32 s22, s47, s48
	s_add_u32 s20, s2, 0x8000
	s_addc_u32 s21, s3, 0
	v_lshl_add_u64 v[144:145], s[18:19], 0, v[138:139]
	s_add_i32 m0, s29, 0xc000
	ds_read_b128 v[186:189], v151
	ds_read_b128 v[190:193], v151 offset:1024
	ds_read_b128 v[194:197], v151 offset:2048
	ds_read_b128 v[198:201], v151 offset:3072
	ds_read_b128 v[202:205], v151 offset:4096
	ds_read_b128 v[206:209], v151 offset:5120
	ds_read_b128 v[210:213], v151 offset:6144
	ds_read_b128 v[214:217], v151 offset:7168
	global_load_lds_dwordx4 v[144:145], off
	v_lshl_add_u64 v[144:145], s[18:19], 0, v[140:141]
	s_add_i32 m0, s29, 0xe000
	s_nop 0
	global_load_lds_dwordx4 v[144:145], off
	s_waitcnt vmcnt(24)
	s_waitcnt lgkmcnt(0)
	s_barrier
	s_setprio 1
	s_waitcnt lgkmcnt(0)
	v_mfma_f32_16x16x32_bf16 v[126:129], v[152:155], v[186:189], 0
	v_mfma_f32_16x16x32_bf16 v[122:125], v[160:163], v[186:189], 0
	v_mfma_f32_16x16x32_bf16 v[114:117], v[152:155], v[194:197], 0
	v_mfma_f32_16x16x32_bf16 v[106:109], v[160:163], v[194:197], 0
	v_mfma_f32_16x16x32_bf16 v[98:101], v[152:155], v[202:205], 0
	v_mfma_f32_16x16x32_bf16 v[90:93], v[160:163], v[202:205], 0
	v_mfma_f32_16x16x32_bf16 v[82:85], v[152:155], v[210:213], 0
	v_mfma_f32_16x16x32_bf16 v[74:77], v[160:163], v[210:213], 0
	v_mfma_f32_16x16x32_bf16 v[126:129], v[156:159], v[190:193], v[126:129]
	v_mfma_f32_16x16x32_bf16 v[122:125], v[164:167], v[190:193], v[122:125]
	v_mfma_f32_16x16x32_bf16 v[114:117], v[156:159], v[198:201], v[114:117]
	v_mfma_f32_16x16x32_bf16 v[106:109], v[164:167], v[198:201], v[106:109]
	v_mfma_f32_16x16x32_bf16 v[98:101], v[156:159], v[206:209], v[98:101]
	v_mfma_f32_16x16x32_bf16 v[90:93], v[164:167], v[206:209], v[90:93]
	v_mfma_f32_16x16x32_bf16 v[82:85], v[156:159], v[214:217], v[82:85]
	v_mfma_f32_16x16x32_bf16 v[74:77], v[164:167], v[214:217], v[74:77]
	s_setprio 0
	s_setprio 1
	v_mfma_f32_16x16x32_bf16 v[118:121], v[168:171], v[186:189], 0
	v_mfma_f32_16x16x32_bf16 v[110:113], v[178:181], v[186:189], 0
	v_mfma_f32_16x16x32_bf16 v[102:105], v[168:171], v[194:197], 0
	v_mfma_f32_16x16x32_bf16 v[94:97], v[178:181], v[194:197], 0
	v_mfma_f32_16x16x32_bf16 v[86:89], v[168:171], v[202:205], 0
	v_mfma_f32_16x16x32_bf16 v[78:81], v[178:181], v[202:205], 0
	v_mfma_f32_16x16x32_bf16 v[70:73], v[168:171], v[210:213], 0
	v_mfma_f32_16x16x32_bf16 v[66:69], v[178:181], v[210:213], 0
	v_mfma_f32_16x16x32_bf16 v[118:121], v[172:175], v[190:193], v[118:121]
	v_mfma_f32_16x16x32_bf16 v[110:113], v[182:185], v[190:193], v[110:113]
	v_mfma_f32_16x16x32_bf16 v[102:105], v[172:175], v[198:201], v[102:105]
	v_mfma_f32_16x16x32_bf16 v[94:97], v[182:185], v[198:201], v[94:97]
	v_mfma_f32_16x16x32_bf16 v[86:89], v[172:175], v[206:209], v[86:89]
	v_mfma_f32_16x16x32_bf16 v[78:81], v[182:185], v[206:209], v[78:81]
	v_mfma_f32_16x16x32_bf16 v[70:73], v[172:175], v[214:217], v[70:73]
	v_mfma_f32_16x16x32_bf16 v[66:69], v[182:185], v[214:217], v[66:69]
	s_setprio 0
	s_barrier
	s_add_i32 s51, s38, s28
	v_lshl_add_u64 v[144:145], s[22:23], 0, v[132:133]
	s_mov_b32 m0, s51
	ds_read_b128 v[186:189], v151 offset:16384
	ds_read_b128 v[190:193], v151 offset:17408
	ds_read_b128 v[194:197], v151 offset:18432
	ds_read_b128 v[198:201], v151 offset:19456
	ds_read_b128 v[202:205], v151 offset:20480
	ds_read_b128 v[206:209], v151 offset:21504
	ds_read_b128 v[210:213], v151 offset:22528
	ds_read_b128 v[214:217], v151 offset:23552
	global_load_lds_dwordx4 v[144:145], off
	s_add_i32 m0, s51, 0x2000
	s_add_u32 s52, s22, 0x4000
	v_lshl_add_u64 v[144:145], s[22:23], 0, v[136:137]
	s_addc_u32 s53, s23, 0
	s_add_i32 s51, s39, s28
	global_load_lds_dwordx4 v[144:145], off
	v_lshl_add_u64 v[144:145], s[52:53], 0, v[132:133]
	s_mov_b32 m0, s51
	s_nop 0
	global_load_lds_dwordx4 v[144:145], off
	v_lshl_add_u64 v[144:145], s[52:53], 0, v[136:137]
	s_add_i32 m0, s51, 0x2000
	s_nop 0
	global_load_lds_dwordx4 v[144:145], off
	v_lshl_add_u64 v[144:145], s[2:3], 0, v[130:131]
	s_mov_b32 m0, s29
	s_nop 0
	global_load_lds_dwordx4 v[144:145], off
	v_lshl_add_u64 v[144:145], s[2:3], 0, v[134:135]
	s_mov_b32 m0, s30
	s_nop 0
	global_load_lds_dwordx4 v[144:145], off
	s_waitcnt vmcnt(24)
	s_waitcnt lgkmcnt(0)
	s_barrier
	s_setprio 1
	s_waitcnt lgkmcnt(0)
	v_mfma_f32_16x16x32_bf16 v[62:65], v[152:155], v[186:189], 0
	v_mfma_f32_16x16x32_bf16 v[58:61], v[160:163], v[186:189], 0
	v_mfma_f32_16x16x32_bf16 v[50:53], v[152:155], v[194:197], 0
	v_mfma_f32_16x16x32_bf16 v[42:45], v[160:163], v[194:197], 0
	v_mfma_f32_16x16x32_bf16 v[34:37], v[152:155], v[202:205], 0
	v_mfma_f32_16x16x32_bf16 v[26:29], v[160:163], v[202:205], 0
	v_mfma_f32_16x16x32_bf16 v[18:21], v[152:155], v[210:213], 0
	v_mfma_f32_16x16x32_bf16 v[10:13], v[160:163], v[210:213], 0
	v_mfma_f32_16x16x32_bf16 v[62:65], v[156:159], v[190:193], v[62:65]
	v_mfma_f32_16x16x32_bf16 v[58:61], v[164:167], v[190:193], v[58:61]
	v_mfma_f32_16x16x32_bf16 v[50:53], v[156:159], v[198:201], v[50:53]
	v_mfma_f32_16x16x32_bf16 v[42:45], v[164:167], v[198:201], v[42:45]
	v_mfma_f32_16x16x32_bf16 v[34:37], v[156:159], v[206:209], v[34:37]
	v_mfma_f32_16x16x32_bf16 v[26:29], v[164:167], v[206:209], v[26:29]
	v_mfma_f32_16x16x32_bf16 v[18:21], v[156:159], v[214:217], v[18:21]
	v_mfma_f32_16x16x32_bf16 v[10:13], v[164:167], v[214:217], v[10:13]
	s_setprio 0
	s_setprio 1
	v_mfma_f32_16x16x32_bf16 v[54:57], v[168:171], v[186:189], 0
	v_mfma_f32_16x16x32_bf16 v[46:49], v[178:181], v[186:189], 0
	v_mfma_f32_16x16x32_bf16 v[38:41], v[168:171], v[194:197], 0
	v_mfma_f32_16x16x32_bf16 v[30:33], v[178:181], v[194:197], 0
	v_mfma_f32_16x16x32_bf16 v[22:25], v[168:171], v[202:205], 0
	v_mfma_f32_16x16x32_bf16 v[14:17], v[178:181], v[202:205], 0
	v_mfma_f32_16x16x32_bf16 v[6:9], v[168:171], v[210:213], 0
	v_mfma_f32_16x16x32_bf16 v[2:5], v[178:181], v[210:213], 0
	v_mfma_f32_16x16x32_bf16 v[54:57], v[172:175], v[190:193], v[54:57]
	v_mfma_f32_16x16x32_bf16 v[46:49], v[182:185], v[190:193], v[46:49]
	v_mfma_f32_16x16x32_bf16 v[38:41], v[172:175], v[198:201], v[38:41]
	v_mfma_f32_16x16x32_bf16 v[30:33], v[182:185], v[198:201], v[30:33]
	v_mfma_f32_16x16x32_bf16 v[22:25], v[172:175], v[206:209], v[22:25]
	v_mfma_f32_16x16x32_bf16 v[14:17], v[182:185], v[206:209], v[14:17]
	v_mfma_f32_16x16x32_bf16 v[6:9], v[172:175], v[214:217], v[6:9]
	v_mfma_f32_16x16x32_bf16 v[2:5], v[182:185], v[214:217], v[2:5]
	s_setprio 0
	s_barrier
	s_add_i32 s51, 0, 0x18000
	v_add_u32_e32 v144, s51, v147
	s_add_i32 s52, 0, 0x1c000
	ds_read_b128 v[152:155], v144
	ds_read_b128 v[156:159], v144 offset:1024
	ds_read_b128 v[160:163], v144 offset:2048
	ds_read_b128 v[164:167], v144 offset:3072
	v_add_u32_e32 v144, s52, v147
	ds_read_b128 v[168:171], v144
	ds_read_b128 v[172:175], v144 offset:1024
	ds_read_b128 v[178:181], v144 offset:2048
	ds_read_b128 v[182:185], v144 offset:3072
	s_add_u32 s2, s2, 0x4000
	s_addc_u32 s3, s3, 0
	s_mov_b32 m0, s31
	v_lshl_add_u64 v[144:145], s[2:3], 0, v[130:131]
	ds_read_b128 v[186:189], v151 offset:32768
	ds_read_b128 v[190:193], v151 offset:33792
	ds_read_b128 v[194:197], v151 offset:34816
	ds_read_b128 v[198:201], v151 offset:35840
	ds_read_b128 v[202:205], v151 offset:36864
	ds_read_b128 v[206:209], v151 offset:37888
	ds_read_b128 v[210:213], v151 offset:38912
	ds_read_b128 v[214:217], v151 offset:39936
	global_load_lds_dwordx4 v[144:145], off
	v_lshl_add_u64 v[144:145], s[2:3], 0, v[134:135]
	s_mov_b32 m0, s34
	s_nop 0
	global_load_lds_dwordx4 v[144:145], off
	s_waitcnt vmcnt(8)
	s_waitcnt lgkmcnt(0)
	s_barrier
	s_setprio 1
	s_waitcnt lgkmcnt(0)
	v_mfma_f32_16x16x32_bf16 v[126:129], v[152:155], v[186:189], v[126:129]
	v_mfma_f32_16x16x32_bf16 v[122:125], v[160:163], v[186:189], v[122:125]
	v_mfma_f32_16x16x32_bf16 v[114:117], v[152:155], v[194:197], v[114:117]
	v_mfma_f32_16x16x32_bf16 v[106:109], v[160:163], v[194:197], v[106:109]
	v_mfma_f32_16x16x32_bf16 v[98:101], v[152:155], v[202:205], v[98:101]
	v_mfma_f32_16x16x32_bf16 v[90:93], v[160:163], v[202:205], v[90:93]
	v_mfma_f32_16x16x32_bf16 v[82:85], v[152:155], v[210:213], v[82:85]
	v_mfma_f32_16x16x32_bf16 v[74:77], v[160:163], v[210:213], v[74:77]
	v_mfma_f32_16x16x32_bf16 v[126:129], v[156:159], v[190:193], v[126:129]
	v_mfma_f32_16x16x32_bf16 v[122:125], v[164:167], v[190:193], v[122:125]
	v_mfma_f32_16x16x32_bf16 v[114:117], v[156:159], v[198:201], v[114:117]
	v_mfma_f32_16x16x32_bf16 v[106:109], v[164:167], v[198:201], v[106:109]
	v_mfma_f32_16x16x32_bf16 v[98:101], v[156:159], v[206:209], v[98:101]
	v_mfma_f32_16x16x32_bf16 v[90:93], v[164:167], v[206:209], v[90:93]
	v_mfma_f32_16x16x32_bf16 v[82:85], v[156:159], v[214:217], v[82:85]
	v_mfma_f32_16x16x32_bf16 v[74:77], v[164:167], v[214:217], v[74:77]
	s_setprio 0
	s_setprio 1
	v_mfma_f32_16x16x32_bf16 v[118:121], v[168:171], v[186:189], v[118:121]
	v_mfma_f32_16x16x32_bf16 v[110:113], v[178:181], v[186:189], v[110:113]
	v_mfma_f32_16x16x32_bf16 v[102:105], v[168:171], v[194:197], v[102:105]
	v_mfma_f32_16x16x32_bf16 v[94:97], v[178:181], v[194:197], v[94:97]
	v_mfma_f32_16x16x32_bf16 v[86:89], v[168:171], v[202:205], v[86:89]
	v_mfma_f32_16x16x32_bf16 v[78:81], v[178:181], v[202:205], v[78:81]
	v_mfma_f32_16x16x32_bf16 v[70:73], v[168:171], v[210:213], v[70:73]
	v_mfma_f32_16x16x32_bf16 v[66:69], v[178:181], v[210:213], v[66:69]
	v_mfma_f32_16x16x32_bf16 v[118:121], v[172:175], v[190:193], v[118:121]
	v_mfma_f32_16x16x32_bf16 v[110:113], v[182:185], v[190:193], v[110:113]
	v_mfma_f32_16x16x32_bf16 v[102:105], v[172:175], v[198:201], v[102:105]
	v_mfma_f32_16x16x32_bf16 v[94:97], v[182:185], v[198:201], v[94:97]
	v_mfma_f32_16x16x32_bf16 v[86:89], v[172:175], v[206:209], v[86:89]
	v_mfma_f32_16x16x32_bf16 v[78:81], v[182:185], v[206:209], v[78:81]
	v_mfma_f32_16x16x32_bf16 v[70:73], v[172:175], v[214:217], v[70:73]
	v_mfma_f32_16x16x32_bf16 v[66:69], v[182:185], v[214:217], v[66:69]
	s_setprio 0
	s_barrier
	s_add_u32 s2, s22, 0x8000
	s_addc_u32 s3, s23, 0
	s_add_i32 s51, s51, s28
	v_lshl_add_u64 v[144:145], s[2:3], 0, v[132:133]
	s_mov_b32 m0, s51
	ds_read_b128 v[186:189], v151 offset:49152
	ds_read_b128 v[190:193], v151 offset:50176
	ds_read_b128 v[194:197], v151 offset:51200
	ds_read_b128 v[198:201], v151 offset:52224
	ds_read_b128 v[202:205], v151 offset:53248
	ds_read_b128 v[206:209], v151 offset:54272
	ds_read_b128 v[210:213], v151 offset:55296
	ds_read_b128 v[214:217], v151 offset:56320
	global_load_lds_dwordx4 v[144:145], off
	s_add_i32 m0, s51, 0x2000
	v_lshl_add_u64 v[144:145], s[2:3], 0, v[136:137]
	s_add_u32 s2, s22, 0xc000
	s_addc_u32 s3, s23, 0
	s_add_i32 s22, s52, s28
	global_load_lds_dwordx4 v[144:145], off
	v_lshl_add_u64 v[144:145], s[2:3], 0, v[132:133]
	s_mov_b32 m0, s22
	s_nop 0
	global_load_lds_dwordx4 v[144:145], off
	v_lshl_add_u64 v[144:145], s[2:3], 0, v[136:137]
	s_add_i32 m0, s22, 0x2000
	s_nop 0
	global_load_lds_dwordx4 v[144:145], off
	v_lshl_add_u64 v[144:145], s[20:21], 0, v[130:131]
	s_mov_b32 m0, s36
	s_nop 0
	global_load_lds_dwordx4 v[144:145], off
	v_lshl_add_u64 v[144:145], s[20:21], 0, v[134:135]
	s_mov_b32 m0, s37
	s_nop 0
	global_load_lds_dwordx4 v[144:145], off
	s_waitcnt vmcnt(8)
	s_waitcnt lgkmcnt(0)
	s_barrier
	s_setprio 1
	s_waitcnt lgkmcnt(0)
	v_mfma_f32_16x16x32_bf16 v[62:65], v[152:155], v[186:189], v[62:65]
	v_mfma_f32_16x16x32_bf16 v[58:61], v[160:163], v[186:189], v[58:61]
	v_mfma_f32_16x16x32_bf16 v[50:53], v[152:155], v[194:197], v[50:53]
	v_mfma_f32_16x16x32_bf16 v[42:45], v[160:163], v[194:197], v[42:45]
	v_mfma_f32_16x16x32_bf16 v[34:37], v[152:155], v[202:205], v[34:37]
	v_mfma_f32_16x16x32_bf16 v[26:29], v[160:163], v[202:205], v[26:29]
	v_mfma_f32_16x16x32_bf16 v[18:21], v[152:155], v[210:213], v[18:21]
	v_mfma_f32_16x16x32_bf16 v[10:13], v[160:163], v[210:213], v[10:13]
	v_mfma_f32_16x16x32_bf16 v[62:65], v[156:159], v[190:193], v[62:65]
	v_mfma_f32_16x16x32_bf16 v[58:61], v[164:167], v[190:193], v[58:61]
	v_mfma_f32_16x16x32_bf16 v[50:53], v[156:159], v[198:201], v[50:53]
	v_mfma_f32_16x16x32_bf16 v[42:45], v[164:167], v[198:201], v[42:45]
	v_mfma_f32_16x16x32_bf16 v[34:37], v[156:159], v[206:209], v[34:37]
	v_mfma_f32_16x16x32_bf16 v[26:29], v[164:167], v[206:209], v[26:29]
	v_mfma_f32_16x16x32_bf16 v[18:21], v[156:159], v[214:217], v[18:21]
	v_mfma_f32_16x16x32_bf16 v[10:13], v[164:167], v[214:217], v[10:13]
	s_setprio 0
	s_setprio 1
	v_mfma_f32_16x16x32_bf16 v[54:57], v[168:171], v[186:189], v[54:57]
	v_mfma_f32_16x16x32_bf16 v[46:49], v[178:181], v[186:189], v[46:49]
	v_mfma_f32_16x16x32_bf16 v[38:41], v[168:171], v[194:197], v[38:41]
	v_mfma_f32_16x16x32_bf16 v[30:33], v[178:181], v[194:197], v[30:33]
	v_mfma_f32_16x16x32_bf16 v[22:25], v[168:171], v[202:205], v[22:25]
	v_mfma_f32_16x16x32_bf16 v[14:17], v[178:181], v[202:205], v[14:17]
	v_mfma_f32_16x16x32_bf16 v[6:9], v[168:171], v[210:213], v[6:9]
	v_mfma_f32_16x16x32_bf16 v[2:5], v[178:181], v[210:213], v[2:5]
	v_mfma_f32_16x16x32_bf16 v[54:57], v[172:175], v[190:193], v[54:57]
	v_mfma_f32_16x16x32_bf16 v[46:49], v[182:185], v[190:193], v[46:49]
	v_mfma_f32_16x16x32_bf16 v[38:41], v[172:175], v[198:201], v[38:41]
	v_mfma_f32_16x16x32_bf16 v[30:33], v[182:185], v[198:201], v[30:33]
	v_mfma_f32_16x16x32_bf16 v[22:25], v[172:175], v[206:209], v[22:25]
	v_mfma_f32_16x16x32_bf16 v[14:17], v[182:185], v[206:209], v[14:17]
	v_mfma_f32_16x16x32_bf16 v[6:9], v[172:175], v[214:217], v[6:9]
	v_mfma_f32_16x16x32_bf16 v[2:5], v[182:185], v[214:217], v[2:5]
	s_setprio 0
	s_barrier
	s_add_i32 s50, s50, 2
	s_add_u32 s18, s18, 0x10000
	s_addc_u32 s19, s19, 0
	s_add_u32 s48, s48, 0x10000
	s_addc_u32 s49, s49, 0
	s_cmp_gt_u32 s50, 41
	s_cbranch_scc0 .LBB0_495
	s_branch .Lpk495_exit

.Lpk555_peel:
	ds_read_b128 v[154:157], v151
	ds_read_b128 v[158:161], v151 offset:1024
	ds_read_b128 v[162:165], v151 offset:2048
	ds_read_b128 v[166:169], v151 offset:3072
	ds_read_b128 v[170:173], v152
	ds_read_b128 v[178:181], v152 offset:1024
	ds_read_b128 v[182:185], v152 offset:2048
	ds_read_b128 v[186:189], v152 offset:3072
	s_add_u32 s2, s26, 0xfffc0080
	s_addc_u32 s3, s27, -1
	s_cmp_eq_u32 s52, 12
	s_cselect_b32 s3, s11, s3
	s_cselect_b32 s2, s13, s2
	s_cselect_b32 s29, s48, s51
	s_cselect_b32 s28, s49, s50
	v_lshl_add_u64 v[144:145], s[26:27], 0, v[138:139]
	s_add_i32 m0, s37, 0xc000
	ds_read_b128 v[190:193], v153
	ds_read_b128 v[194:197], v153 offset:1024
	ds_read_b128 v[198:201], v153 offset:2048
	ds_read_b128 v[202:205], v153 offset:3072
	ds_read_b128 v[206:209], v153 offset:4096
	ds_read_b128 v[210:213], v153 offset:5120
	ds_read_b128 v[214:217], v153 offset:6144
	ds_read_b128 v[218:221], v153 offset:7168
	global_load_lds_dwordx4 v[144:145], off
	v_lshl_add_u64 v[144:145], s[26:27], 0, v[140:141]
	s_add_i32 m0, s37, 0xe000
	s_nop 0
	global_load_lds_dwordx4 v[144:145], off
	s_waitcnt vmcnt(24)
	s_waitcnt lgkmcnt(0)
	s_barrier
	s_setprio 1
	s_waitcnt lgkmcnt(0)
	v_mfma_f32_16x16x32_bf16 v[126:129], v[154:157], v[190:193], 0
	v_mfma_f32_16x16x32_bf16 v[122:125], v[162:165], v[190:193], 0
	v_mfma_f32_16x16x32_bf16 v[114:117], v[154:157], v[198:201], 0
	v_mfma_f32_16x16x32_bf16 v[106:109], v[162:165], v[198:201], 0
	v_mfma_f32_16x16x32_bf16 v[98:101], v[154:157], v[206:209], 0
	v_mfma_f32_16x16x32_bf16 v[90:93], v[162:165], v[206:209], 0
	v_mfma_f32_16x16x32_bf16 v[82:85], v[154:157], v[214:217], 0
	v_mfma_f32_16x16x32_bf16 v[74:77], v[162:165], v[214:217], 0
	v_mfma_f32_16x16x32_bf16 v[126:129], v[158:161], v[194:197], v[126:129]
	v_mfma_f32_16x16x32_bf16 v[122:125], v[166:169], v[194:197], v[122:125]
	v_mfma_f32_16x16x32_bf16 v[114:117], v[158:161], v[202:205], v[114:117]
	v_mfma_f32_16x16x32_bf16 v[106:109], v[166:169], v[202:205], v[106:109]
	v_mfma_f32_16x16x32_bf16 v[98:101], v[158:161], v[210:213], v[98:101]
	v_mfma_f32_16x16x32_bf16 v[90:93], v[166:169], v[210:213], v[90:93]
	v_mfma_f32_16x16x32_bf16 v[82:85], v[158:161], v[218:221], v[82:85]
	v_mfma_f32_16x16x32_bf16 v[74:77], v[166:169], v[218:221], v[74:77]
	s_setprio 0
	s_setprio 1
	v_mfma_f32_16x16x32_bf16 v[118:121], v[170:173], v[190:193], 0
	v_mfma_f32_16x16x32_bf16 v[110:113], v[182:185], v[190:193], 0
	v_mfma_f32_16x16x32_bf16 v[102:105], v[170:173], v[198:201], 0
	v_mfma_f32_16x16x32_bf16 v[94:97], v[182:185], v[198:201], 0
	v_mfma_f32_16x16x32_bf16 v[86:89], v[170:173], v[206:209], 0
	v_mfma_f32_16x16x32_bf16 v[78:81], v[182:185], v[206:209], 0
	v_mfma_f32_16x16x32_bf16 v[70:73], v[170:173], v[214:217], 0
	v_mfma_f32_16x16x32_bf16 v[66:69], v[182:185], v[214:217], 0
	v_mfma_f32_16x16x32_bf16 v[118:121], v[178:181], v[194:197], v[118:121]
	v_mfma_f32_16x16x32_bf16 v[110:113], v[186:189], v[194:197], v[110:113]
	v_mfma_f32_16x16x32_bf16 v[102:105], v[178:181], v[202:205], v[102:105]
	v_mfma_f32_16x16x32_bf16 v[94:97], v[186:189], v[202:205], v[94:97]
	v_mfma_f32_16x16x32_bf16 v[86:89], v[178:181], v[210:213], v[86:89]
	v_mfma_f32_16x16x32_bf16 v[78:81], v[186:189], v[210:213], v[78:81]
	v_mfma_f32_16x16x32_bf16 v[70:73], v[178:181], v[218:221], v[70:73]
	v_mfma_f32_16x16x32_bf16 v[66:69], v[186:189], v[218:221], v[66:69]
	s_setprio 0
	s_barrier
	s_add_i32 s53, s44, s34
	v_lshl_add_u64 v[144:145], s[28:29], 0, v[134:135]
	s_mov_b32 m0, s53
	ds_read_b128 v[190:193], v153 offset:16384
	ds_read_b128 v[194:197], v153 offset:17408
	ds_read_b128 v[198:201], v153 offset:18432
	ds_read_b128 v[202:205], v153 offset:19456
	ds_read_b128 v[206:209], v153 offset:20480
	ds_read_b128 v[210:213], v153 offset:21504
	ds_read_b128 v[214:217], v153 offset:22528
	ds_read_b128 v[218:221], v153 offset:23552
	global_load_lds_dwordx4 v[144:145], off
	s_add_i32 m0, s53, 0x2000
	s_add_u32 s54, s28, 0x40000
	v_lshl_add_u64 v[174:175], s[28:29], 0, v[130:131]
	s_addc_u32 s55, s29, 0
	s_add_i32 s53, s45, s34
	global_load_lds_dwordx4 v[174:175], off
	v_lshl_add_u64 v[222:223], s[54:55], 0, v[134:135]
	s_mov_b32 m0, s53
	v_lshl_add_u64 v[224:225], s[2:3], 0, v[132:133]
	global_load_lds_dwordx4 v[222:223], off
	v_lshl_add_u64 v[222:223], s[54:55], 0, v[130:131]
	s_add_i32 m0, s53, 0x2000
	s_nop 0
	global_load_lds_dwordx4 v[222:223], off
	v_lshl_add_u64 v[222:223], s[2:3], 0, v[136:137]
	s_mov_b32 m0, s37
	s_nop 0
	global_load_lds_dwordx4 v[222:223], off
	s_mov_b32 m0, s25
	s_nop 0
	global_load_lds_dwordx4 v[224:225], off
	s_waitcnt vmcnt(24)
	s_waitcnt lgkmcnt(0)
	s_barrier
	s_setprio 1
	s_waitcnt lgkmcnt(0)
	v_mfma_f32_16x16x32_bf16 v[62:65], v[154:157], v[190:193], 0
	v_mfma_f32_16x16x32_bf16 v[58:61], v[162:165], v[190:193], 0
	v_mfma_f32_16x16x32_bf16 v[50:53], v[154:157], v[198:201], 0
	v_mfma_f32_16x16x32_bf16 v[42:45], v[162:165], v[198:201], 0
	v_mfma_f32_16x16x32_bf16 v[34:37], v[154:157], v[206:209], 0
	v_mfma_f32_16x16x32_bf16 v[26:29], v[162:165], v[206:209], 0
	v_mfma_f32_16x16x32_bf16 v[18:21], v[154:157], v[214:217], 0
	v_mfma_f32_16x16x32_bf16 v[10:13], v[162:165], v[214:217], 0
	v_mfma_f32_16x16x32_bf16 v[62:65], v[158:161], v[194:197], v[62:65]
	v_mfma_f32_16x16x32_bf16 v[58:61], v[166:169], v[194:197], v[58:61]
	v_mfma_f32_16x16x32_bf16 v[50:53], v[158:161], v[202:205], v[50:53]
	v_mfma_f32_16x16x32_bf16 v[42:45], v[166:169], v[202:205], v[42:45]
	v_mfma_f32_16x16x32_bf16 v[34:37], v[158:161], v[210:213], v[34:37]
	v_mfma_f32_16x16x32_bf16 v[26:29], v[166:169], v[210:213], v[26:29]
	v_mfma_f32_16x16x32_bf16 v[18:21], v[158:161], v[218:221], v[18:21]
	v_mfma_f32_16x16x32_bf16 v[10:13], v[166:169], v[218:221], v[10:13]
	s_setprio 0
	s_setprio 1
	v_mfma_f32_16x16x32_bf16 v[54:57], v[170:173], v[190:193], 0
	v_mfma_f32_16x16x32_bf16 v[46:49], v[182:185], v[190:193], 0
	v_mfma_f32_16x16x32_bf16 v[38:41], v[170:173], v[198:201], 0
	v_mfma_f32_16x16x32_bf16 v[30:33], v[182:185], v[198:201], 0
	v_mfma_f32_16x16x32_bf16 v[22:25], v[170:173], v[206:209], 0
	v_mfma_f32_16x16x32_bf16 v[14:17], v[182:185], v[206:209], 0
	v_mfma_f32_16x16x32_bf16 v[6:9], v[170:173], v[214:217], 0
	v_mfma_f32_16x16x32_bf16 v[2:5], v[182:185], v[214:217], 0
	v_mfma_f32_16x16x32_bf16 v[54:57], v[178:181], v[194:197], v[54:57]
	v_mfma_f32_16x16x32_bf16 v[46:49], v[186:189], v[194:197], v[46:49]
	v_mfma_f32_16x16x32_bf16 v[38:41], v[178:181], v[202:205], v[38:41]
	v_mfma_f32_16x16x32_bf16 v[30:33], v[186:189], v[202:205], v[30:33]
	v_mfma_f32_16x16x32_bf16 v[22:25], v[178:181], v[210:213], v[22:25]
	v_mfma_f32_16x16x32_bf16 v[14:17], v[186:189], v[210:213], v[14:17]
	v_mfma_f32_16x16x32_bf16 v[6:9], v[178:181], v[218:221], v[6:9]
	v_mfma_f32_16x16x32_bf16 v[2:5], v[186:189], v[218:221], v[2:5]
	s_setprio 0
	s_barrier
	s_add_i32 s53, 0, 0x18000
	s_add_i32 s54, 0, 0x1c000
	v_add_u32_e32 v166, s53, v149
	v_add_u32_e32 v176, s54, v149
	ds_read_b128 v[154:157], v166
	ds_read_b128 v[158:161], v166 offset:1024
	ds_read_b128 v[162:165], v166 offset:2048
	ds_read_b128 v[166:169], v166 offset:3072
	ds_read_b128 v[170:173], v176
	ds_read_b128 v[178:181], v176 offset:1024
	ds_read_b128 v[182:185], v176 offset:2048
	ds_read_b128 v[186:189], v176 offset:3072
	s_add_u32 s2, s2, 0x40000
	s_addc_u32 s3, s3, 0
	s_mov_b32 m0, s38
	v_lshl_add_u64 v[226:227], s[2:3], 0, v[136:137]
	ds_read_b128 v[190:193], v153 offset:32768
	ds_read_b128 v[194:197], v153 offset:33792
	ds_read_b128 v[198:201], v153 offset:34816
	ds_read_b128 v[202:205], v153 offset:35840
	ds_read_b128 v[206:209], v153 offset:36864
	ds_read_b128 v[210:213], v153 offset:37888
	ds_read_b128 v[214:217], v153 offset:38912
	ds_read_b128 v[218:221], v153 offset:39936
	global_load_lds_dwordx4 v[226:227], off
	v_lshl_add_u64 v[226:227], s[2:3], 0, v[132:133]
	s_mov_b32 m0, s39
	s_nop 0
	global_load_lds_dwordx4 v[226:227], off
	s_waitcnt vmcnt(8)
	s_waitcnt lgkmcnt(0)
	s_barrier
	s_setprio 1
	s_waitcnt lgkmcnt(0)
	v_mfma_f32_16x16x32_bf16 v[126:129], v[154:157], v[190:193], v[126:129]
	v_mfma_f32_16x16x32_bf16 v[122:125], v[162:165], v[190:193], v[122:125]
	v_mfma_f32_16x16x32_bf16 v[114:117], v[154:157], v[198:201], v[114:117]
	v_mfma_f32_16x16x32_bf16 v[106:109], v[162:165], v[198:201], v[106:109]
	v_mfma_f32_16x16x32_bf16 v[98:101], v[154:157], v[206:209], v[98:101]
	v_mfma_f32_16x16x32_bf16 v[90:93], v[162:165], v[206:209], v[90:93]
	v_mfma_f32_16x16x32_bf16 v[82:85], v[154:157], v[214:217], v[82:85]
	v_mfma_f32_16x16x32_bf16 v[74:77], v[162:165], v[214:217], v[74:77]
	v_mfma_f32_16x16x32_bf16 v[126:129], v[158:161], v[194:197], v[126:129]
	v_mfma_f32_16x16x32_bf16 v[122:125], v[166:169], v[194:197], v[122:125]
	v_mfma_f32_16x16x32_bf16 v[114:117], v[158:161], v[202:205], v[114:117]
	v_mfma_f32_16x16x32_bf16 v[106:109], v[166:169], v[202:205], v[106:109]
	v_mfma_f32_16x16x32_bf16 v[98:101], v[158:161], v[210:213], v[98:101]
	v_mfma_f32_16x16x32_bf16 v[90:93], v[166:169], v[210:213], v[90:93]
	v_mfma_f32_16x16x32_bf16 v[82:85], v[158:161], v[218:221], v[82:85]
	v_mfma_f32_16x16x32_bf16 v[74:77], v[166:169], v[218:221], v[74:77]
	s_setprio 0
	s_setprio 1
	v_mfma_f32_16x16x32_bf16 v[118:121], v[170:173], v[190:193], v[118:121]
	v_mfma_f32_16x16x32_bf16 v[110:113], v[182:185], v[190:193], v[110:113]
	v_mfma_f32_16x16x32_bf16 v[102:105], v[170:173], v[198:201], v[102:105]
	v_mfma_f32_16x16x32_bf16 v[94:97], v[182:185], v[198:201], v[94:97]
	v_mfma_f32_16x16x32_bf16 v[86:89], v[170:173], v[206:209], v[86:89]
	v_mfma_f32_16x16x32_bf16 v[78:81], v[182:185], v[206:209], v[78:81]
	v_mfma_f32_16x16x32_bf16 v[70:73], v[170:173], v[214:217], v[70:73]
	v_mfma_f32_16x16x32_bf16 v[66:69], v[182:185], v[214:217], v[66:69]
	v_mfma_f32_16x16x32_bf16 v[118:121], v[178:181], v[194:197], v[118:121]
	v_mfma_f32_16x16x32_bf16 v[110:113], v[186:189], v[194:197], v[110:113]
	v_mfma_f32_16x16x32_bf16 v[102:105], v[178:181], v[202:205], v[102:105]
	v_mfma_f32_16x16x32_bf16 v[94:97], v[186:189], v[202:205], v[94:97]
	v_mfma_f32_16x16x32_bf16 v[86:89], v[178:181], v[210:213], v[86:89]
	v_mfma_f32_16x16x32_bf16 v[78:81], v[186:189], v[210:213], v[78:81]
	v_mfma_f32_16x16x32_bf16 v[70:73], v[178:181], v[218:221], v[70:73]
	v_mfma_f32_16x16x32_bf16 v[66:69], v[186:189], v[218:221], v[66:69]
	s_setprio 0
	s_barrier
	s_add_i32 s2, s53, s34
	v_lshl_add_u64 v[144:145], v[144:145], 0, s[6:7]
	s_mov_b32 m0, s2
	ds_read_b128 v[190:193], v153 offset:49152
	ds_read_b128 v[194:197], v153 offset:50176
	ds_read_b128 v[198:201], v153 offset:51200
	ds_read_b128 v[202:205], v153 offset:52224
	ds_read_b128 v[206:209], v153 offset:53248
	ds_read_b128 v[210:213], v153 offset:54272
	ds_read_b128 v[214:217], v153 offset:55296
	ds_read_b128 v[218:221], v153 offset:56320
	global_load_lds_dwordx4 v[144:145], off
	s_add_i32 m0, s2, 0x2000
	s_add_u32 s2, s28, 0x40080
	v_lshl_add_u64 v[144:145], v[174:175], 0, s[6:7]
	s_addc_u32 s3, s29, 0
	s_add_i32 s28, s54, s34
	global_load_lds_dwordx4 v[144:145], off
	v_lshl_add_u64 v[144:145], s[2:3], 0, v[134:135]
	s_mov_b32 m0, s28
	s_nop 0
	global_load_lds_dwordx4 v[144:145], off
	v_lshl_add_u64 v[144:145], s[2:3], 0, v[130:131]
	s_add_i32 m0, s28, 0x2000
	s_nop 0
	global_load_lds_dwordx4 v[144:145], off
	v_lshl_add_u64 v[144:145], v[222:223], 0, s[6:7]
	s_mov_b32 m0, s41
	s_nop 0
	global_load_lds_dwordx4 v[144:145], off
	v_lshl_add_u64 v[144:145], v[224:225], 0, s[6:7]
	s_mov_b32 m0, s42
	s_nop 0
	global_load_lds_dwordx4 v[144:145], off
	s_waitcnt vmcnt(8)
	s_waitcnt lgkmcnt(0)
	s_barrier
	s_setprio 1
	s_waitcnt lgkmcnt(0)
	v_mfma_f32_16x16x32_bf16 v[62:65], v[154:157], v[190:193], v[62:65]
	v_mfma_f32_16x16x32_bf16 v[58:61], v[162:165], v[190:193], v[58:61]
	v_mfma_f32_16x16x32_bf16 v[50:53], v[154:157], v[198:201], v[50:53]
	v_mfma_f32_16x16x32_bf16 v[42:45], v[162:165], v[198:201], v[42:45]
	v_mfma_f32_16x16x32_bf16 v[34:37], v[154:157], v[206:209], v[34:37]
	v_mfma_f32_16x16x32_bf16 v[26:29], v[162:165], v[206:209], v[26:29]
	v_mfma_f32_16x16x32_bf16 v[18:21], v[154:157], v[214:217], v[18:21]
	v_mfma_f32_16x16x32_bf16 v[10:13], v[162:165], v[214:217], v[10:13]
	v_mfma_f32_16x16x32_bf16 v[62:65], v[158:161], v[194:197], v[62:65]
	v_mfma_f32_16x16x32_bf16 v[58:61], v[166:169], v[194:197], v[58:61]
	v_mfma_f32_16x16x32_bf16 v[50:53], v[158:161], v[202:205], v[50:53]
	v_mfma_f32_16x16x32_bf16 v[42:45], v[166:169], v[202:205], v[42:45]
	v_mfma_f32_16x16x32_bf16 v[34:37], v[158:161], v[210:213], v[34:37]
	v_mfma_f32_16x16x32_bf16 v[26:29], v[166:169], v[210:213], v[26:29]
	v_mfma_f32_16x16x32_bf16 v[18:21], v[158:161], v[218:221], v[18:21]
	v_mfma_f32_16x16x32_bf16 v[10:13], v[166:169], v[218:221], v[10:13]
	s_setprio 0
	s_setprio 1
	v_mfma_f32_16x16x32_bf16 v[54:57], v[170:173], v[190:193], v[54:57]
	v_mfma_f32_16x16x32_bf16 v[46:49], v[182:185], v[190:193], v[46:49]
	v_mfma_f32_16x16x32_bf16 v[38:41], v[170:173], v[198:201], v[38:41]
	v_mfma_f32_16x16x32_bf16 v[30:33], v[182:185], v[198:201], v[30:33]
	v_mfma_f32_16x16x32_bf16 v[22:25], v[170:173], v[206:209], v[22:25]
	v_mfma_f32_16x16x32_bf16 v[14:17], v[182:185], v[206:209], v[14:17]
	v_mfma_f32_16x16x32_bf16 v[6:9], v[170:173], v[214:217], v[6:9]
	v_mfma_f32_16x16x32_bf16 v[2:5], v[182:185], v[214:217], v[2:5]
	v_mfma_f32_16x16x32_bf16 v[54:57], v[178:181], v[194:197], v[54:57]
	v_mfma_f32_16x16x32_bf16 v[46:49], v[186:189], v[194:197], v[46:49]
	v_mfma_f32_16x16x32_bf16 v[38:41], v[178:181], v[202:205], v[38:41]
	v_mfma_f32_16x16x32_bf16 v[30:33], v[186:189], v[202:205], v[30:33]
	v_mfma_f32_16x16x32_bf16 v[22:25], v[178:181], v[210:213], v[22:25]
	v_mfma_f32_16x16x32_bf16 v[14:17], v[186:189], v[210:213], v[14:17]
	v_mfma_f32_16x16x32_bf16 v[6:9], v[178:181], v[218:221], v[6:9]
	v_mfma_f32_16x16x32_bf16 v[2:5], v[186:189], v[218:221], v[2:5]
	s_setprio 0
	s_barrier
	s_add_i32 s52, s52, 2
	s_add_u32 s26, s26, 0x100
	s_addc_u32 s27, s27, 0
	s_add_u32 s50, s50, 0x100
	s_addc_u32 s51, s51, 0
	s_cmp_gt_u32 s52, 13
	s_cbranch_scc0 .LBB0_555
	s_branch .Lpk555_exit

.Lpk1098_peel:
	ds_read_b128 v[152:155], v148
	ds_read_b128 v[156:159], v148 offset:1024
	ds_read_b128 v[160:163], v148 offset:2048
	ds_read_b128 v[164:167], v148 offset:3072
	ds_read_b128 v[168:171], v149
	ds_read_b128 v[172:175], v149 offset:1024
	ds_read_b128 v[178:181], v149 offset:2048
	ds_read_b128 v[182:185], v149 offset:3072
	s_add_u32 s2, s30, 0xfffc0080
	s_addc_u32 s3, s31, -1
	s_cmp_eq_u32 s56, 12
	s_cselect_b32 s3, s15, s3
	s_cselect_b32 s2, s17, s2
	s_cselect_b32 s35, s52, s55
	s_cselect_b32 s34, s53, s54
	v_lshl_add_u64 v[144:145], s[30:31], 0, v[138:139]
	s_add_i32 m0, s40, 0xc000
	ds_read_b128 v[186:189], v150
	ds_read_b128 v[190:193], v150 offset:1024
	ds_read_b128 v[194:197], v150 offset:2048
	ds_read_b128 v[198:201], v150 offset:3072
	ds_read_b128 v[202:205], v150 offset:4096
	ds_read_b128 v[206:209], v150 offset:5120
	ds_read_b128 v[210:213], v150 offset:6144
	ds_read_b128 v[214:217], v150 offset:7168
	global_load_lds_dwordx4 v[144:145], off
	v_lshl_add_u64 v[144:145], s[30:31], 0, v[140:141]
	s_add_i32 m0, s40, 0xe000
	s_nop 0
	global_load_lds_dwordx4 v[144:145], off
	s_waitcnt vmcnt(24)
	s_waitcnt lgkmcnt(0)
	s_barrier
	s_setprio 1
	s_waitcnt lgkmcnt(0)
	v_mfma_f32_16x16x32_bf16 v[126:129], v[152:155], v[186:189], 0
	v_mfma_f32_16x16x32_bf16 v[122:125], v[160:163], v[186:189], 0
	v_mfma_f32_16x16x32_bf16 v[114:117], v[152:155], v[194:197], 0
	v_mfma_f32_16x16x32_bf16 v[106:109], v[160:163], v[194:197], 0
	v_mfma_f32_16x16x32_bf16 v[98:101], v[152:155], v[202:205], 0
	v_mfma_f32_16x16x32_bf16 v[90:93], v[160:163], v[202:205], 0
	v_mfma_f32_16x16x32_bf16 v[82:85], v[152:155], v[210:213], 0
	v_mfma_f32_16x16x32_bf16 v[74:77], v[160:163], v[210:213], 0
	v_mfma_f32_16x16x32_bf16 v[126:129], v[156:159], v[190:193], v[126:129]
	v_mfma_f32_16x16x32_bf16 v[122:125], v[164:167], v[190:193], v[122:125]
	v_mfma_f32_16x16x32_bf16 v[114:117], v[156:159], v[198:201], v[114:117]
	v_mfma_f32_16x16x32_bf16 v[106:109], v[164:167], v[198:201], v[106:109]
	v_mfma_f32_16x16x32_bf16 v[98:101], v[156:159], v[206:209], v[98:101]
	v_mfma_f32_16x16x32_bf16 v[90:93], v[164:167], v[206:209], v[90:93]
	v_mfma_f32_16x16x32_bf16 v[82:85], v[156:159], v[214:217], v[82:85]
	v_mfma_f32_16x16x32_bf16 v[74:77], v[164:167], v[214:217], v[74:77]
	s_setprio 0
	s_setprio 1
	v_mfma_f32_16x16x32_bf16 v[118:121], v[168:171], v[186:189], 0
	v_mfma_f32_16x16x32_bf16 v[110:113], v[178:181], v[186:189], 0
	v_mfma_f32_16x16x32_bf16 v[102:105], v[168:171], v[194:197], 0
	v_mfma_f32_16x16x32_bf16 v[94:97], v[178:181], v[194:197], 0
	v_mfma_f32_16x16x32_bf16 v[86:89], v[168:171], v[202:205], 0
	v_mfma_f32_16x16x32_bf16 v[78:81], v[178:181], v[202:205], 0
	v_mfma_f32_16x16x32_bf16 v[70:73], v[168:171], v[210:213], 0
	v_mfma_f32_16x16x32_bf16 v[66:69], v[178:181], v[210:213], 0
	v_mfma_f32_16x16x32_bf16 v[118:121], v[172:175], v[190:193], v[118:121]
	v_mfma_f32_16x16x32_bf16 v[110:113], v[182:185], v[190:193], v[110:113]
	v_mfma_f32_16x16x32_bf16 v[102:105], v[172:175], v[198:201], v[102:105]
	v_mfma_f32_16x16x32_bf16 v[94:97], v[182:185], v[198:201], v[94:97]
	v_mfma_f32_16x16x32_bf16 v[86:89], v[172:175], v[206:209], v[86:89]
	v_mfma_f32_16x16x32_bf16 v[78:81], v[182:185], v[206:209], v[78:81]
	v_mfma_f32_16x16x32_bf16 v[70:73], v[172:175], v[214:217], v[70:73]
	v_mfma_f32_16x16x32_bf16 v[66:69], v[182:185], v[214:217], v[66:69]
	s_setprio 0
	s_barrier
	s_add_i32 s57, s47, s39
	v_lshl_add_u64 v[144:145], s[34:35], 0, v[132:133]
	s_mov_b32 m0, s57
	ds_read_b128 v[186:189], v150 offset:16384
	ds_read_b128 v[190:193], v150 offset:17408
	ds_read_b128 v[194:197], v150 offset:18432
	ds_read_b128 v[198:201], v150 offset:19456
	ds_read_b128 v[202:205], v150 offset:20480
	ds_read_b128 v[206:209], v150 offset:21504
	ds_read_b128 v[210:213], v150 offset:22528
	ds_read_b128 v[214:217], v150 offset:23552
	global_load_lds_dwordx4 v[144:145], off
	s_add_i32 m0, s57, 0x2000
	s_add_u32 s58, s34, 0x40000
	v_lshl_add_u64 v[218:219], s[34:35], 0, v[136:137]
	s_addc_u32 s59, s35, 0
	s_add_i32 s57, s48, s39
	global_load_lds_dwordx4 v[218:219], off
	v_lshl_add_u64 v[220:221], s[58:59], 0, v[132:133]
	s_mov_b32 m0, s57
	v_lshl_add_u64 v[222:223], s[2:3], 0, v[134:135]
	global_load_lds_dwordx4 v[220:221], off
	v_lshl_add_u64 v[220:221], s[58:59], 0, v[136:137]
	s_add_i32 m0, s57, 0x2000
	s_nop 0
	global_load_lds_dwordx4 v[220:221], off
	v_lshl_add_u64 v[220:221], s[2:3], 0, v[130:131]
	s_mov_b32 m0, s40
	s_nop 0
	global_load_lds_dwordx4 v[220:221], off
	s_mov_b32 m0, s29
	s_nop 0
	global_load_lds_dwordx4 v[222:223], off
	s_waitcnt vmcnt(24)
	s_waitcnt lgkmcnt(0)
	s_barrier
	s_setprio 1
	s_waitcnt lgkmcnt(0)
	v_mfma_f32_16x16x32_bf16 v[62:65], v[152:155], v[186:189], 0
	v_mfma_f32_16x16x32_bf16 v[58:61], v[160:163], v[186:189], 0
	v_mfma_f32_16x16x32_bf16 v[50:53], v[152:155], v[194:197], 0
	v_mfma_f32_16x16x32_bf16 v[42:45], v[160:163], v[194:197], 0
	v_mfma_f32_16x16x32_bf16 v[34:37], v[152:155], v[202:205], 0
	v_mfma_f32_16x16x32_bf16 v[26:29], v[160:163], v[202:205], 0
	v_mfma_f32_16x16x32_bf16 v[18:21], v[152:155], v[210:213], 0
	v_mfma_f32_16x16x32_bf16 v[10:13], v[160:163], v[210:213], 0
	v_mfma_f32_16x16x32_bf16 v[62:65], v[156:159], v[190:193], v[62:65]
	v_mfma_f32_16x16x32_bf16 v[58:61], v[164:167], v[190:193], v[58:61]
	v_mfma_f32_16x16x32_bf16 v[50:53], v[156:159], v[198:201], v[50:53]
	v_mfma_f32_16x16x32_bf16 v[42:45], v[164:167], v[198:201], v[42:45]
	v_mfma_f32_16x16x32_bf16 v[34:37], v[156:159], v[206:209], v[34:37]
	v_mfma_f32_16x16x32_bf16 v[26:29], v[164:167], v[206:209], v[26:29]
	v_mfma_f32_16x16x32_bf16 v[18:21], v[156:159], v[214:217], v[18:21]
	v_mfma_f32_16x16x32_bf16 v[10:13], v[164:167], v[214:217], v[10:13]
	s_setprio 0
	s_setprio 1
	v_mfma_f32_16x16x32_bf16 v[54:57], v[168:171], v[186:189], 0
	v_mfma_f32_16x16x32_bf16 v[46:49], v[178:181], v[186:189], 0
	v_mfma_f32_16x16x32_bf16 v[38:41], v[168:171], v[194:197], 0
	v_mfma_f32_16x16x32_bf16 v[30:33], v[178:181], v[194:197], 0
	v_mfma_f32_16x16x32_bf16 v[22:25], v[168:171], v[202:205], 0
	v_mfma_f32_16x16x32_bf16 v[14:17], v[178:181], v[202:205], 0
	v_mfma_f32_16x16x32_bf16 v[6:9], v[168:171], v[210:213], 0
	v_mfma_f32_16x16x32_bf16 v[2:5], v[178:181], v[210:213], 0
	v_mfma_f32_16x16x32_bf16 v[54:57], v[172:175], v[190:193], v[54:57]
	v_mfma_f32_16x16x32_bf16 v[46:49], v[182:185], v[190:193], v[46:49]
	v_mfma_f32_16x16x32_bf16 v[38:41], v[172:175], v[198:201], v[38:41]
	v_mfma_f32_16x16x32_bf16 v[30:33], v[182:185], v[198:201], v[30:33]
	v_mfma_f32_16x16x32_bf16 v[22:25], v[172:175], v[206:209], v[22:25]
	v_mfma_f32_16x16x32_bf16 v[14:17], v[182:185], v[206:209], v[14:17]
	v_mfma_f32_16x16x32_bf16 v[6:9], v[172:175], v[214:217], v[6:9]
	v_mfma_f32_16x16x32_bf16 v[2:5], v[182:185], v[214:217], v[2:5]
	s_setprio 0
	s_barrier
	s_add_i32 s57, 0, 0x18000
	v_add_u32_e32 v151, s57, v146
	s_add_i32 s58, 0, 0x1c000
	ds_read_b128 v[152:155], v151
	ds_read_b128 v[156:159], v151 offset:1024
	ds_read_b128 v[160:163], v151 offset:2048
	ds_read_b128 v[164:167], v151 offset:3072
	v_add_u32_e32 v151, s58, v146
	ds_read_b128 v[168:171], v151
	ds_read_b128 v[172:175], v151 offset:1024
	ds_read_b128 v[178:181], v151 offset:2048
	ds_read_b128 v[182:185], v151 offset:3072
	s_add_u32 s2, s2, 0x40000
	s_addc_u32 s3, s3, 0
	s_mov_b32 m0, s41
	v_lshl_add_u64 v[224:225], s[2:3], 0, v[130:131]
	ds_read_b128 v[186:189], v150 offset:32768
	ds_read_b128 v[190:193], v150 offset:33792
	ds_read_b128 v[194:197], v150 offset:34816
	ds_read_b128 v[198:201], v150 offset:35840
	ds_read_b128 v[202:205], v150 offset:36864
	ds_read_b128 v[206:209], v150 offset:37888
	ds_read_b128 v[210:213], v150 offset:38912
	ds_read_b128 v[214:217], v150 offset:39936
	global_load_lds_dwordx4 v[224:225], off
	v_lshl_add_u64 v[224:225], s[2:3], 0, v[134:135]
	s_mov_b32 m0, s42
	s_nop 0
	global_load_lds_dwordx4 v[224:225], off
	s_waitcnt vmcnt(8)
	s_waitcnt lgkmcnt(0)
	s_barrier
	s_setprio 1
	s_waitcnt lgkmcnt(0)
	v_mfma_f32_16x16x32_bf16 v[126:129], v[152:155], v[186:189], v[126:129]
	v_mfma_f32_16x16x32_bf16 v[122:125], v[160:163], v[186:189], v[122:125]
	v_mfma_f32_16x16x32_bf16 v[114:117], v[152:155], v[194:197], v[114:117]
	v_mfma_f32_16x16x32_bf16 v[106:109], v[160:163], v[194:197], v[106:109]
	v_mfma_f32_16x16x32_bf16 v[98:101], v[152:155], v[202:205], v[98:101]
	v_mfma_f32_16x16x32_bf16 v[90:93], v[160:163], v[202:205], v[90:93]
	v_mfma_f32_16x16x32_bf16 v[82:85], v[152:155], v[210:213], v[82:85]
	v_mfma_f32_16x16x32_bf16 v[74:77], v[160:163], v[210:213], v[74:77]
	v_mfma_f32_16x16x32_bf16 v[126:129], v[156:159], v[190:193], v[126:129]
	v_mfma_f32_16x16x32_bf16 v[122:125], v[164:167], v[190:193], v[122:125]
	v_mfma_f32_16x16x32_bf16 v[114:117], v[156:159], v[198:201], v[114:117]
	v_mfma_f32_16x16x32_bf16 v[106:109], v[164:167], v[198:201], v[106:109]
	v_mfma_f32_16x16x32_bf16 v[98:101], v[156:159], v[206:209], v[98:101]
	v_mfma_f32_16x16x32_bf16 v[90:93], v[164:167], v[206:209], v[90:93]
	v_mfma_f32_16x16x32_bf16 v[82:85], v[156:159], v[214:217], v[82:85]
	v_mfma_f32_16x16x32_bf16 v[74:77], v[164:167], v[214:217], v[74:77]
	s_setprio 0
	s_setprio 1
	v_mfma_f32_16x16x32_bf16 v[118:121], v[168:171], v[186:189], v[118:121]
	v_mfma_f32_16x16x32_bf16 v[110:113], v[178:181], v[186:189], v[110:113]
	v_mfma_f32_16x16x32_bf16 v[102:105], v[168:171], v[194:197], v[102:105]
	v_mfma_f32_16x16x32_bf16 v[94:97], v[178:181], v[194:197], v[94:97]
	v_mfma_f32_16x16x32_bf16 v[86:89], v[168:171], v[202:205], v[86:89]
	v_mfma_f32_16x16x32_bf16 v[78:81], v[178:181], v[202:205], v[78:81]
	v_mfma_f32_16x16x32_bf16 v[70:73], v[168:171], v[210:213], v[70:73]
	v_mfma_f32_16x16x32_bf16 v[66:69], v[178:181], v[210:213], v[66:69]
	v_mfma_f32_16x16x32_bf16 v[118:121], v[172:175], v[190:193], v[118:121]
	v_mfma_f32_16x16x32_bf16 v[110:113], v[182:185], v[190:193], v[110:113]
	v_mfma_f32_16x16x32_bf16 v[102:105], v[172:175], v[198:201], v[102:105]
	v_mfma_f32_16x16x32_bf16 v[94:97], v[182:185], v[198:201], v[94:97]
	v_mfma_f32_16x16x32_bf16 v[86:89], v[172:175], v[206:209], v[86:89]
	v_mfma_f32_16x16x32_bf16 v[78:81], v[182:185], v[206:209], v[78:81]
	v_mfma_f32_16x16x32_bf16 v[70:73], v[172:175], v[214:217], v[70:73]
	v_mfma_f32_16x16x32_bf16 v[66:69], v[182:185], v[214:217], v[66:69]
	s_setprio 0
	s_barrier
	s_add_i32 s2, s57, s39
	v_lshl_add_u64 v[144:145], v[144:145], 0, s[6:7]
	s_mov_b32 m0, s2
	ds_read_b128 v[186:189], v150 offset:49152
	ds_read_b128 v[190:193], v150 offset:50176
	ds_read_b128 v[194:197], v150 offset:51200
	ds_read_b128 v[198:201], v150 offset:52224
	ds_read_b128 v[202:205], v150 offset:53248
	ds_read_b128 v[206:209], v150 offset:54272
	ds_read_b128 v[210:213], v150 offset:55296
	ds_read_b128 v[214:217], v150 offset:56320
	global_load_lds_dwordx4 v[144:145], off
	s_add_i32 m0, s2, 0x2000
	s_add_u32 s2, s34, 0x40080
	v_lshl_add_u64 v[144:145], v[218:219], 0, s[6:7]
	s_addc_u32 s3, s35, 0
	s_add_i32 s34, s58, s39
	global_load_lds_dwordx4 v[144:145], off
	v_lshl_add_u64 v[144:145], s[2:3], 0, v[132:133]
	s_mov_b32 m0, s34
	s_nop 0
	global_load_lds_dwordx4 v[144:145], off
	v_lshl_add_u64 v[144:145], s[2:3], 0, v[136:137]
	s_add_i32 m0, s34, 0x2000
	s_nop 0
	global_load_lds_dwordx4 v[144:145], off
	v_lshl_add_u64 v[144:145], v[220:221], 0, s[6:7]
	s_mov_b32 m0, s44
	s_nop 0
	global_load_lds_dwordx4 v[144:145], off
	v_lshl_add_u64 v[144:145], v[222:223], 0, s[6:7]
	s_mov_b32 m0, s45
	s_nop 0
	global_load_lds_dwordx4 v[144:145], off
	s_waitcnt vmcnt(8)
	s_waitcnt lgkmcnt(0)
	s_barrier
	s_setprio 1
	s_waitcnt lgkmcnt(0)
	v_mfma_f32_16x16x32_bf16 v[62:65], v[152:155], v[186:189], v[62:65]
	v_mfma_f32_16x16x32_bf16 v[58:61], v[160:163], v[186:189], v[58:61]
	v_mfma_f32_16x16x32_bf16 v[50:53], v[152:155], v[194:197], v[50:53]
	v_mfma_f32_16x16x32_bf16 v[42:45], v[160:163], v[194:197], v[42:45]
	v_mfma_f32_16x16x32_bf16 v[34:37], v[152:155], v[202:205], v[34:37]
	v_mfma_f32_16x16x32_bf16 v[26:29], v[160:163], v[202:205], v[26:29]
	v_mfma_f32_16x16x32_bf16 v[18:21], v[152:155], v[210:213], v[18:21]
	v_mfma_f32_16x16x32_bf16 v[10:13], v[160:163], v[210:213], v[10:13]
	v_mfma_f32_16x16x32_bf16 v[62:65], v[156:159], v[190:193], v[62:65]
	v_mfma_f32_16x16x32_bf16 v[58:61], v[164:167], v[190:193], v[58:61]
	v_mfma_f32_16x16x32_bf16 v[50:53], v[156:159], v[198:201], v[50:53]
	v_mfma_f32_16x16x32_bf16 v[42:45], v[164:167], v[198:201], v[42:45]
	v_mfma_f32_16x16x32_bf16 v[34:37], v[156:159], v[206:209], v[34:37]
	v_mfma_f32_16x16x32_bf16 v[26:29], v[164:167], v[206:209], v[26:29]
	v_mfma_f32_16x16x32_bf16 v[18:21], v[156:159], v[214:217], v[18:21]
	v_mfma_f32_16x16x32_bf16 v[10:13], v[164:167], v[214:217], v[10:13]
	s_setprio 0
	s_setprio 1
	v_mfma_f32_16x16x32_bf16 v[54:57], v[168:171], v[186:189], v[54:57]
	v_mfma_f32_16x16x32_bf16 v[46:49], v[178:181], v[186:189], v[46:49]
	v_mfma_f32_16x16x32_bf16 v[38:41], v[168:171], v[194:197], v[38:41]
	v_mfma_f32_16x16x32_bf16 v[30:33], v[178:181], v[194:197], v[30:33]
	v_mfma_f32_16x16x32_bf16 v[22:25], v[168:171], v[202:205], v[22:25]
	v_mfma_f32_16x16x32_bf16 v[14:17], v[178:181], v[202:205], v[14:17]
	v_mfma_f32_16x16x32_bf16 v[6:9], v[168:171], v[210:213], v[6:9]
	v_mfma_f32_16x16x32_bf16 v[2:5], v[178:181], v[210:213], v[2:5]
	v_mfma_f32_16x16x32_bf16 v[54:57], v[172:175], v[190:193], v[54:57]
	v_mfma_f32_16x16x32_bf16 v[46:49], v[182:185], v[190:193], v[46:49]
	v_mfma_f32_16x16x32_bf16 v[38:41], v[172:175], v[198:201], v[38:41]
	v_mfma_f32_16x16x32_bf16 v[30:33], v[182:185], v[198:201], v[30:33]
	v_mfma_f32_16x16x32_bf16 v[22:25], v[172:175], v[206:209], v[22:25]
	v_mfma_f32_16x16x32_bf16 v[14:17], v[182:185], v[206:209], v[14:17]
	v_mfma_f32_16x16x32_bf16 v[6:9], v[172:175], v[214:217], v[6:9]
	v_mfma_f32_16x16x32_bf16 v[2:5], v[182:185], v[214:217], v[2:5]
	s_setprio 0
	s_barrier
	s_add_i32 s56, s56, 2
	s_add_u32 s30, s30, 0x100
	s_addc_u32 s31, s31, 0
	s_add_u32 s54, s54, 0x100
	s_addc_u32 s55, s55, 0
	s_cmp_gt_u32 s56, 13
	s_cbranch_scc0 .LBB0_1098
	s_branch .Lpk1098_exit

.Lpk1179_peel:
	ds_read_b128 v[144:147], v158
	ds_read_b128 v[164:167], v158 offset:1024
	ds_read_b128 v[168:171], v158 offset:2048
	ds_read_b128 v[172:175], v158 offset:3072
	ds_read_b128 v[178:181], v159
	ds_read_b128 v[182:185], v159 offset:1024
	ds_read_b128 v[186:189], v159 offset:2048
	ds_read_b128 v[190:193], v159 offset:3072
	s_add_u32 s2, s36, 0xfffc0080
	s_addc_u32 s3, s37, -1
	s_cmp_eq_u32 s61, 12
	s_cselect_b32 s3, s19, s3
	s_cselect_b32 s2, s21, s2
	s_cselect_b32 s39, s57, s60
	s_cselect_b32 s38, s58, s59
	v_lshl_add_u64 v[226:227], s[36:37], 0, v[138:139]
	s_add_i32 m0, s42, 0xc000
	ds_read_b128 v[194:197], v160
	ds_read_b128 v[198:201], v160 offset:1024
	ds_read_b128 v[202:205], v160 offset:2048
	ds_read_b128 v[206:209], v160 offset:3072
	ds_read_b128 v[210:213], v160 offset:4096
	ds_read_b128 v[214:217], v160 offset:5120
	ds_read_b128 v[218:221], v160 offset:6144
	ds_read_b128 v[222:225], v160 offset:7168
	global_load_lds_dwordx4 v[226:227], off
	v_lshl_add_u64 v[226:227], s[36:37], 0, v[140:141]
	s_add_i32 m0, s42, 0xe000
	s_nop 0
	global_load_lds_dwordx4 v[226:227], off
	s_waitcnt vmcnt(24)
	s_waitcnt lgkmcnt(0)
	s_barrier
	s_setprio 1
	s_waitcnt lgkmcnt(0)
	v_mfma_f32_16x16x32_bf16 v[126:129], v[144:147], v[194:197], 0
	v_mfma_f32_16x16x32_bf16 v[122:125], v[168:171], v[194:197], 0
	v_mfma_f32_16x16x32_bf16 v[114:117], v[144:147], v[202:205], 0
	v_mfma_f32_16x16x32_bf16 v[106:109], v[168:171], v[202:205], 0
	v_mfma_f32_16x16x32_bf16 v[98:101], v[144:147], v[210:213], 0
	v_mfma_f32_16x16x32_bf16 v[90:93], v[168:171], v[210:213], 0
	v_mfma_f32_16x16x32_bf16 v[82:85], v[144:147], v[218:221], 0
	v_mfma_f32_16x16x32_bf16 v[74:77], v[168:171], v[218:221], 0
	v_mfma_f32_16x16x32_bf16 v[126:129], v[164:167], v[198:201], v[126:129]
	v_mfma_f32_16x16x32_bf16 v[122:125], v[172:175], v[198:201], v[122:125]
	v_mfma_f32_16x16x32_bf16 v[114:117], v[164:167], v[206:209], v[114:117]
	v_mfma_f32_16x16x32_bf16 v[106:109], v[172:175], v[206:209], v[106:109]
	v_mfma_f32_16x16x32_bf16 v[98:101], v[164:167], v[214:217], v[98:101]
	v_mfma_f32_16x16x32_bf16 v[90:93], v[172:175], v[214:217], v[90:93]
	v_mfma_f32_16x16x32_bf16 v[82:85], v[164:167], v[222:225], v[82:85]
	v_mfma_f32_16x16x32_bf16 v[74:77], v[172:175], v[222:225], v[74:77]
	s_setprio 0
	s_setprio 1
	v_mfma_f32_16x16x32_bf16 v[118:121], v[178:181], v[194:197], 0
	v_mfma_f32_16x16x32_bf16 v[110:113], v[186:189], v[194:197], 0
	v_mfma_f32_16x16x32_bf16 v[102:105], v[178:181], v[202:205], 0
	v_mfma_f32_16x16x32_bf16 v[94:97], v[186:189], v[202:205], 0
	v_mfma_f32_16x16x32_bf16 v[86:89], v[178:181], v[210:213], 0
	v_mfma_f32_16x16x32_bf16 v[78:81], v[186:189], v[210:213], 0
	v_mfma_f32_16x16x32_bf16 v[70:73], v[178:181], v[218:221], 0
	v_mfma_f32_16x16x32_bf16 v[66:69], v[186:189], v[218:221], 0
	v_mfma_f32_16x16x32_bf16 v[118:121], v[182:185], v[198:201], v[118:121]
	v_mfma_f32_16x16x32_bf16 v[110:113], v[190:193], v[198:201], v[110:113]
	v_mfma_f32_16x16x32_bf16 v[102:105], v[182:185], v[206:209], v[102:105]
	v_mfma_f32_16x16x32_bf16 v[94:97], v[190:193], v[206:209], v[94:97]
	v_mfma_f32_16x16x32_bf16 v[86:89], v[182:185], v[214:217], v[86:89]
	v_mfma_f32_16x16x32_bf16 v[78:81], v[190:193], v[214:217], v[78:81]
	v_mfma_f32_16x16x32_bf16 v[70:73], v[182:185], v[222:225], v[70:73]
	v_mfma_f32_16x16x32_bf16 v[66:69], v[190:193], v[222:225], v[66:69]
	s_setprio 0
	s_barrier
	s_add_i32 s62, s51, s41
	v_lshl_add_u64 v[226:227], s[38:39], 0, v[132:133]
	s_mov_b32 m0, s62
	ds_read_b128 v[194:197], v160 offset:16384
	ds_read_b128 v[198:201], v160 offset:17408
	ds_read_b128 v[202:205], v160 offset:18432
	ds_read_b128 v[206:209], v160 offset:19456
	ds_read_b128 v[210:213], v160 offset:20480
	ds_read_b128 v[214:217], v160 offset:21504
	ds_read_b128 v[218:221], v160 offset:22528
	ds_read_b128 v[222:225], v160 offset:23552
	global_load_lds_dwordx4 v[226:227], off
	s_add_i32 m0, s62, 0x2000
	s_add_u32 s62, s38, 0x40000
	v_lshl_add_u64 v[228:229], s[38:39], 0, v[136:137]
	s_addc_u32 s63, s39, 0
	s_add_i32 s64, s52, s41
	global_load_lds_dwordx4 v[228:229], off
	v_lshl_add_u64 v[230:231], s[62:63], 0, v[132:133]
	s_mov_b32 m0, s64
	v_lshl_add_u64 v[232:233], s[2:3], 0, v[134:135]
	global_load_lds_dwordx4 v[230:231], off
	v_lshl_add_u64 v[230:231], s[62:63], 0, v[136:137]
	s_add_i32 m0, s64, 0x2000
	s_nop 0
	global_load_lds_dwordx4 v[230:231], off
	v_lshl_add_u64 v[230:231], s[2:3], 0, v[130:131]
	s_mov_b32 m0, s42
	s_nop 0
	global_load_lds_dwordx4 v[230:231], off
	s_mov_b32 m0, s43
	s_nop 0
	global_load_lds_dwordx4 v[232:233], off
	s_waitcnt vmcnt(24)
	s_waitcnt lgkmcnt(0)
	s_barrier
	s_setprio 1
	s_waitcnt lgkmcnt(0)
	v_mfma_f32_16x16x32_bf16 v[62:65], v[144:147], v[194:197], 0
	v_mfma_f32_16x16x32_bf16 v[58:61], v[168:171], v[194:197], 0
	v_mfma_f32_16x16x32_bf16 v[50:53], v[144:147], v[202:205], 0
	v_mfma_f32_16x16x32_bf16 v[42:45], v[168:171], v[202:205], 0
	v_mfma_f32_16x16x32_bf16 v[34:37], v[144:147], v[210:213], 0
	v_mfma_f32_16x16x32_bf16 v[26:29], v[168:171], v[210:213], 0
	v_mfma_f32_16x16x32_bf16 v[18:21], v[144:147], v[218:221], 0
	v_mfma_f32_16x16x32_bf16 v[10:13], v[168:171], v[218:221], 0
	v_mfma_f32_16x16x32_bf16 v[62:65], v[164:167], v[198:201], v[62:65]
	v_mfma_f32_16x16x32_bf16 v[58:61], v[172:175], v[198:201], v[58:61]
	v_mfma_f32_16x16x32_bf16 v[50:53], v[164:167], v[206:209], v[50:53]
	v_mfma_f32_16x16x32_bf16 v[42:45], v[172:175], v[206:209], v[42:45]
	v_mfma_f32_16x16x32_bf16 v[34:37], v[164:167], v[214:217], v[34:37]
	v_mfma_f32_16x16x32_bf16 v[26:29], v[172:175], v[214:217], v[26:29]
	v_mfma_f32_16x16x32_bf16 v[18:21], v[164:167], v[222:225], v[18:21]
	v_mfma_f32_16x16x32_bf16 v[10:13], v[172:175], v[222:225], v[10:13]
	s_setprio 0
	s_setprio 1
	v_mfma_f32_16x16x32_bf16 v[54:57], v[178:181], v[194:197], 0
	v_mfma_f32_16x16x32_bf16 v[46:49], v[186:189], v[194:197], 0
	v_mfma_f32_16x16x32_bf16 v[38:41], v[178:181], v[202:205], 0
	v_mfma_f32_16x16x32_bf16 v[30:33], v[186:189], v[202:205], 0
	v_mfma_f32_16x16x32_bf16 v[22:25], v[178:181], v[210:213], 0
	v_mfma_f32_16x16x32_bf16 v[14:17], v[186:189], v[210:213], 0
	v_mfma_f32_16x16x32_bf16 v[6:9], v[178:181], v[218:221], 0
	v_mfma_f32_16x16x32_bf16 v[2:5], v[186:189], v[218:221], 0
	v_mfma_f32_16x16x32_bf16 v[54:57], v[182:185], v[198:201], v[54:57]
	v_mfma_f32_16x16x32_bf16 v[46:49], v[190:193], v[198:201], v[46:49]
	v_mfma_f32_16x16x32_bf16 v[38:41], v[182:185], v[206:209], v[38:41]
	v_mfma_f32_16x16x32_bf16 v[30:33], v[190:193], v[206:209], v[30:33]
	v_mfma_f32_16x16x32_bf16 v[22:25], v[182:185], v[214:217], v[22:25]
	v_mfma_f32_16x16x32_bf16 v[14:17], v[190:193], v[214:217], v[14:17]
	v_mfma_f32_16x16x32_bf16 v[6:9], v[182:185], v[222:225], v[6:9]
	v_mfma_f32_16x16x32_bf16 v[2:5], v[190:193], v[222:225], v[2:5]
	s_setprio 0
	s_barrier
	s_add_i32 s62, 0, 0x18000
	v_add_u32_e32 v163, s62, v148
	s_add_i32 s63, 0, 0x1c000
	ds_read_b128 v[144:147], v163
	ds_read_b128 v[164:167], v163 offset:1024
	ds_read_b128 v[168:171], v163 offset:2048
	ds_read_b128 v[172:175], v163 offset:3072
	v_add_u32_e32 v163, s63, v148
	ds_read_b128 v[178:181], v163
	ds_read_b128 v[182:185], v163 offset:1024
	ds_read_b128 v[186:189], v163 offset:2048
	ds_read_b128 v[190:193], v163 offset:3072
	s_add_u32 s2, s2, 0x40000
	s_addc_u32 s3, s3, 0
	s_mov_b32 m0, s44
	v_lshl_add_u64 v[234:235], s[2:3], 0, v[130:131]
	ds_read_b128 v[194:197], v160 offset:32768
	ds_read_b128 v[198:201], v160 offset:33792
	ds_read_b128 v[202:205], v160 offset:34816
	ds_read_b128 v[206:209], v160 offset:35840
	ds_read_b128 v[210:213], v160 offset:36864
	ds_read_b128 v[214:217], v160 offset:37888
	ds_read_b128 v[218:221], v160 offset:38912
	ds_read_b128 v[222:225], v160 offset:39936
	global_load_lds_dwordx4 v[234:235], off
	v_lshl_add_u64 v[234:235], s[2:3], 0, v[134:135]
	s_mov_b32 m0, s45
	s_nop 0
	global_load_lds_dwordx4 v[234:235], off
	s_waitcnt vmcnt(8)
	s_waitcnt lgkmcnt(0)
	s_barrier
	s_setprio 1
	s_waitcnt lgkmcnt(0)
	v_mfma_f32_16x16x32_bf16 v[126:129], v[144:147], v[194:197], v[126:129]
	v_mfma_f32_16x16x32_bf16 v[122:125], v[168:171], v[194:197], v[122:125]
	v_mfma_f32_16x16x32_bf16 v[114:117], v[144:147], v[202:205], v[114:117]
	v_mfma_f32_16x16x32_bf16 v[106:109], v[168:171], v[202:205], v[106:109]
	v_mfma_f32_16x16x32_bf16 v[98:101], v[144:147], v[210:213], v[98:101]
	v_mfma_f32_16x16x32_bf16 v[90:93], v[168:171], v[210:213], v[90:93]
	v_mfma_f32_16x16x32_bf16 v[82:85], v[144:147], v[218:221], v[82:85]
	v_mfma_f32_16x16x32_bf16 v[74:77], v[168:171], v[218:221], v[74:77]
	v_mfma_f32_16x16x32_bf16 v[126:129], v[164:167], v[198:201], v[126:129]
	v_mfma_f32_16x16x32_bf16 v[122:125], v[172:175], v[198:201], v[122:125]
	v_mfma_f32_16x16x32_bf16 v[114:117], v[164:167], v[206:209], v[114:117]
	v_mfma_f32_16x16x32_bf16 v[106:109], v[172:175], v[206:209], v[106:109]
	v_mfma_f32_16x16x32_bf16 v[98:101], v[164:167], v[214:217], v[98:101]
	v_mfma_f32_16x16x32_bf16 v[90:93], v[172:175], v[214:217], v[90:93]
	v_mfma_f32_16x16x32_bf16 v[82:85], v[164:167], v[222:225], v[82:85]
	v_mfma_f32_16x16x32_bf16 v[74:77], v[172:175], v[222:225], v[74:77]
	s_setprio 0
	s_setprio 1
	v_mfma_f32_16x16x32_bf16 v[118:121], v[178:181], v[194:197], v[118:121]
	v_mfma_f32_16x16x32_bf16 v[110:113], v[186:189], v[194:197], v[110:113]
	v_mfma_f32_16x16x32_bf16 v[102:105], v[178:181], v[202:205], v[102:105]
	v_mfma_f32_16x16x32_bf16 v[94:97], v[186:189], v[202:205], v[94:97]
	v_mfma_f32_16x16x32_bf16 v[86:89], v[178:181], v[210:213], v[86:89]
	v_mfma_f32_16x16x32_bf16 v[78:81], v[186:189], v[210:213], v[78:81]
	v_mfma_f32_16x16x32_bf16 v[70:73], v[178:181], v[218:221], v[70:73]
	v_mfma_f32_16x16x32_bf16 v[66:69], v[186:189], v[218:221], v[66:69]
	v_mfma_f32_16x16x32_bf16 v[118:121], v[182:185], v[198:201], v[118:121]
	v_mfma_f32_16x16x32_bf16 v[110:113], v[190:193], v[198:201], v[110:113]
	v_mfma_f32_16x16x32_bf16 v[102:105], v[182:185], v[206:209], v[102:105]
	v_mfma_f32_16x16x32_bf16 v[94:97], v[190:193], v[206:209], v[94:97]
	v_mfma_f32_16x16x32_bf16 v[86:89], v[182:185], v[214:217], v[86:89]
	v_mfma_f32_16x16x32_bf16 v[78:81], v[190:193], v[214:217], v[78:81]
	v_mfma_f32_16x16x32_bf16 v[70:73], v[182:185], v[222:225], v[70:73]
	v_mfma_f32_16x16x32_bf16 v[66:69], v[190:193], v[222:225], v[66:69]
	s_setprio 0
	s_barrier
	s_add_i32 s2, s62, s41
	v_lshl_add_u64 v[226:227], v[226:227], 0, s[10:11]
	s_mov_b32 m0, s2
	ds_read_b128 v[194:197], v160 offset:49152
	ds_read_b128 v[198:201], v160 offset:50176
	ds_read_b128 v[202:205], v160 offset:51200
	ds_read_b128 v[206:209], v160 offset:52224
	ds_read_b128 v[210:213], v160 offset:53248
	ds_read_b128 v[214:217], v160 offset:54272
	ds_read_b128 v[218:221], v160 offset:55296
	ds_read_b128 v[222:225], v160 offset:56320
	global_load_lds_dwordx4 v[226:227], off
	s_add_i32 m0, s2, 0x2000
	s_add_u32 s2, s38, 0x40080
	v_lshl_add_u64 v[226:227], v[228:229], 0, s[10:11]
	s_addc_u32 s3, s39, 0
	s_add_i32 s38, s63, s41
	global_load_lds_dwordx4 v[226:227], off
	v_lshl_add_u64 v[226:227], s[2:3], 0, v[132:133]
	s_mov_b32 m0, s38
	s_nop 0
	global_load_lds_dwordx4 v[226:227], off
	v_lshl_add_u64 v[226:227], s[2:3], 0, v[136:137]
	s_add_i32 m0, s38, 0x2000
	s_nop 0
	global_load_lds_dwordx4 v[226:227], off
	v_lshl_add_u64 v[226:227], v[230:231], 0, s[10:11]
	s_mov_b32 m0, s47
	s_nop 0
	global_load_lds_dwordx4 v[226:227], off
	v_lshl_add_u64 v[226:227], v[232:233], 0, s[10:11]
	s_mov_b32 m0, s48
	s_nop 0
	global_load_lds_dwordx4 v[226:227], off
	s_waitcnt vmcnt(8)
	s_waitcnt lgkmcnt(0)
	s_barrier
	s_setprio 1
	s_waitcnt lgkmcnt(0)
	v_mfma_f32_16x16x32_bf16 v[62:65], v[144:147], v[194:197], v[62:65]
	v_mfma_f32_16x16x32_bf16 v[58:61], v[168:171], v[194:197], v[58:61]
	v_mfma_f32_16x16x32_bf16 v[50:53], v[144:147], v[202:205], v[50:53]
	v_mfma_f32_16x16x32_bf16 v[42:45], v[168:171], v[202:205], v[42:45]
	v_mfma_f32_16x16x32_bf16 v[34:37], v[144:147], v[210:213], v[34:37]
	v_mfma_f32_16x16x32_bf16 v[26:29], v[168:171], v[210:213], v[26:29]
	v_mfma_f32_16x16x32_bf16 v[18:21], v[144:147], v[218:221], v[18:21]
	v_mfma_f32_16x16x32_bf16 v[10:13], v[168:171], v[218:221], v[10:13]
	v_mfma_f32_16x16x32_bf16 v[62:65], v[164:167], v[198:201], v[62:65]
	v_mfma_f32_16x16x32_bf16 v[58:61], v[172:175], v[198:201], v[58:61]
	v_mfma_f32_16x16x32_bf16 v[50:53], v[164:167], v[206:209], v[50:53]
	v_mfma_f32_16x16x32_bf16 v[42:45], v[172:175], v[206:209], v[42:45]
	v_mfma_f32_16x16x32_bf16 v[34:37], v[164:167], v[214:217], v[34:37]
	v_mfma_f32_16x16x32_bf16 v[26:29], v[172:175], v[214:217], v[26:29]
	v_mfma_f32_16x16x32_bf16 v[18:21], v[164:167], v[222:225], v[18:21]
	v_mfma_f32_16x16x32_bf16 v[10:13], v[172:175], v[222:225], v[10:13]
	s_setprio 0
	s_setprio 1
	v_mfma_f32_16x16x32_bf16 v[54:57], v[178:181], v[194:197], v[54:57]
	v_mfma_f32_16x16x32_bf16 v[46:49], v[186:189], v[194:197], v[46:49]
	v_mfma_f32_16x16x32_bf16 v[38:41], v[178:181], v[202:205], v[38:41]
	v_mfma_f32_16x16x32_bf16 v[30:33], v[186:189], v[202:205], v[30:33]
	v_mfma_f32_16x16x32_bf16 v[22:25], v[178:181], v[210:213], v[22:25]
	v_mfma_f32_16x16x32_bf16 v[14:17], v[186:189], v[210:213], v[14:17]
	v_mfma_f32_16x16x32_bf16 v[6:9], v[178:181], v[218:221], v[6:9]
	v_mfma_f32_16x16x32_bf16 v[2:5], v[186:189], v[218:221], v[2:5]
	v_mfma_f32_16x16x32_bf16 v[54:57], v[182:185], v[198:201], v[54:57]
	v_mfma_f32_16x16x32_bf16 v[46:49], v[190:193], v[198:201], v[46:49]
	v_mfma_f32_16x16x32_bf16 v[38:41], v[182:185], v[206:209], v[38:41]
	v_mfma_f32_16x16x32_bf16 v[30:33], v[190:193], v[206:209], v[30:33]
	v_mfma_f32_16x16x32_bf16 v[22:25], v[182:185], v[214:217], v[22:25]
	v_mfma_f32_16x16x32_bf16 v[14:17], v[190:193], v[214:217], v[14:17]
	v_mfma_f32_16x16x32_bf16 v[6:9], v[182:185], v[222:225], v[6:9]
	v_mfma_f32_16x16x32_bf16 v[2:5], v[190:193], v[222:225], v[2:5]
	s_setprio 0
	s_barrier
	s_add_i32 s61, s61, 2
	s_add_u32 s36, s36, 0x100
	s_addc_u32 s37, s37, 0
	s_add_u32 s59, s59, 0x100
	s_addc_u32 s60, s60, 0
	s_cmp_gt_u32 s61, 13
	s_cbranch_scc0 .LBB0_1179
	s_branch .Lpk1179_exit

.Lpk1239_peel:
	ds_read_b128 v[152:155], v148
	ds_read_b128 v[156:159], v148 offset:1024
	ds_read_b128 v[160:163], v148 offset:2048
	ds_read_b128 v[164:167], v148 offset:3072
	ds_read_b128 v[168:171], v149
	ds_read_b128 v[172:175], v149 offset:1024
	ds_read_b128 v[178:181], v149 offset:2048
	ds_read_b128 v[182:185], v149 offset:3072
	s_add_u32 s2, s36, 0xfffc0080
	s_addc_u32 s3, s37, -1
	s_cmp_eq_u32 s62, 12
	s_cselect_b32 s3, s19, s3
	s_cselect_b32 s2, s21, s2
	s_cselect_b32 s39, s58, s61
	s_cselect_b32 s38, s59, s60
	v_lshl_add_u64 v[144:145], s[36:37], 0, v[138:139]
	s_add_i32 m0, s44, 0xc000
	ds_read_b128 v[186:189], v150
	ds_read_b128 v[190:193], v150 offset:1024
	ds_read_b128 v[194:197], v150 offset:2048
	ds_read_b128 v[198:201], v150 offset:3072
	ds_read_b128 v[202:205], v150 offset:4096
	ds_read_b128 v[206:209], v150 offset:5120
	ds_read_b128 v[210:213], v150 offset:6144
	ds_read_b128 v[214:217], v150 offset:7168
	global_load_lds_dwordx4 v[144:145], off
	v_lshl_add_u64 v[144:145], s[36:37], 0, v[140:141]
	s_add_i32 m0, s44, 0xe000
	s_nop 0
	global_load_lds_dwordx4 v[144:145], off
	s_waitcnt vmcnt(24)
	s_waitcnt lgkmcnt(0)
	s_barrier
	s_setprio 1
	s_waitcnt lgkmcnt(0)
	v_mfma_f32_16x16x32_bf16 v[126:129], v[152:155], v[186:189], 0
	v_mfma_f32_16x16x32_bf16 v[122:125], v[160:163], v[186:189], 0
	v_mfma_f32_16x16x32_bf16 v[114:117], v[152:155], v[194:197], 0
	v_mfma_f32_16x16x32_bf16 v[106:109], v[160:163], v[194:197], 0
	v_mfma_f32_16x16x32_bf16 v[98:101], v[152:155], v[202:205], 0
	v_mfma_f32_16x16x32_bf16 v[90:93], v[160:163], v[202:205], 0
	v_mfma_f32_16x16x32_bf16 v[82:85], v[152:155], v[210:213], 0
	v_mfma_f32_16x16x32_bf16 v[74:77], v[160:163], v[210:213], 0
	v_mfma_f32_16x16x32_bf16 v[126:129], v[156:159], v[190:193], v[126:129]
	v_mfma_f32_16x16x32_bf16 v[122:125], v[164:167], v[190:193], v[122:125]
	v_mfma_f32_16x16x32_bf16 v[114:117], v[156:159], v[198:201], v[114:117]
	v_mfma_f32_16x16x32_bf16 v[106:109], v[164:167], v[198:201], v[106:109]
	v_mfma_f32_16x16x32_bf16 v[98:101], v[156:159], v[206:209], v[98:101]
	v_mfma_f32_16x16x32_bf16 v[90:93], v[164:167], v[206:209], v[90:93]
	v_mfma_f32_16x16x32_bf16 v[82:85], v[156:159], v[214:217], v[82:85]
	v_mfma_f32_16x16x32_bf16 v[74:77], v[164:167], v[214:217], v[74:77]
	s_setprio 0
	s_setprio 1
	v_mfma_f32_16x16x32_bf16 v[118:121], v[168:171], v[186:189], 0
	v_mfma_f32_16x16x32_bf16 v[110:113], v[178:181], v[186:189], 0
	v_mfma_f32_16x16x32_bf16 v[102:105], v[168:171], v[194:197], 0
	v_mfma_f32_16x16x32_bf16 v[94:97], v[178:181], v[194:197], 0
	v_mfma_f32_16x16x32_bf16 v[86:89], v[168:171], v[202:205], 0
	v_mfma_f32_16x16x32_bf16 v[78:81], v[178:181], v[202:205], 0
	v_mfma_f32_16x16x32_bf16 v[70:73], v[168:171], v[210:213], 0
	v_mfma_f32_16x16x32_bf16 v[66:69], v[178:181], v[210:213], 0
	v_mfma_f32_16x16x32_bf16 v[118:121], v[172:175], v[190:193], v[118:121]
	v_mfma_f32_16x16x32_bf16 v[110:113], v[182:185], v[190:193], v[110:113]
	v_mfma_f32_16x16x32_bf16 v[102:105], v[172:175], v[198:201], v[102:105]
	v_mfma_f32_16x16x32_bf16 v[94:97], v[182:185], v[198:201], v[94:97]
	v_mfma_f32_16x16x32_bf16 v[86:89], v[172:175], v[206:209], v[86:89]
	v_mfma_f32_16x16x32_bf16 v[78:81], v[182:185], v[206:209], v[78:81]
	v_mfma_f32_16x16x32_bf16 v[70:73], v[172:175], v[214:217], v[70:73]
	v_mfma_f32_16x16x32_bf16 v[66:69], v[182:185], v[214:217], v[66:69]
	s_setprio 0
	s_barrier
	s_add_i32 s63, s51, s43
	v_lshl_add_u64 v[144:145], s[38:39], 0, v[132:133]
	s_mov_b32 m0, s63
	ds_read_b128 v[186:189], v150 offset:16384
	ds_read_b128 v[190:193], v150 offset:17408
	ds_read_b128 v[194:197], v150 offset:18432
	ds_read_b128 v[198:201], v150 offset:19456
	ds_read_b128 v[202:205], v150 offset:20480
	ds_read_b128 v[206:209], v150 offset:21504
	ds_read_b128 v[210:213], v150 offset:22528
	ds_read_b128 v[214:217], v150 offset:23552
	global_load_lds_dwordx4 v[144:145], off
	s_add_i32 m0, s63, 0x2000
	s_add_u32 s64, s38, 0x40000
	v_lshl_add_u64 v[218:219], s[38:39], 0, v[136:137]
	s_addc_u32 s65, s39, 0
	s_add_i32 s63, s52, s43
	global_load_lds_dwordx4 v[218:219], off
	v_lshl_add_u64 v[220:221], s[64:65], 0, v[132:133]
	s_mov_b32 m0, s63
	v_lshl_add_u64 v[222:223], s[2:3], 0, v[134:135]
	global_load_lds_dwordx4 v[220:221], off
	v_lshl_add_u64 v[220:221], s[64:65], 0, v[136:137]
	s_add_i32 m0, s63, 0x2000
	s_nop 0
	global_load_lds_dwordx4 v[220:221], off
	v_lshl_add_u64 v[220:221], s[2:3], 0, v[130:131]
	s_mov_b32 m0, s44
	s_nop 0
	global_load_lds_dwordx4 v[220:221], off
	s_mov_b32 m0, s35
	s_nop 0
	global_load_lds_dwordx4 v[222:223], off
	s_waitcnt vmcnt(24)
	s_waitcnt lgkmcnt(0)
	s_barrier
	s_setprio 1
	s_waitcnt lgkmcnt(0)
	v_mfma_f32_16x16x32_bf16 v[62:65], v[152:155], v[186:189], 0
	v_mfma_f32_16x16x32_bf16 v[58:61], v[160:163], v[186:189], 0
	v_mfma_f32_16x16x32_bf16 v[50:53], v[152:155], v[194:197], 0
	v_mfma_f32_16x16x32_bf16 v[42:45], v[160:163], v[194:197], 0
	v_mfma_f32_16x16x32_bf16 v[34:37], v[152:155], v[202:205], 0
	v_mfma_f32_16x16x32_bf16 v[26:29], v[160:163], v[202:205], 0
	v_mfma_f32_16x16x32_bf16 v[18:21], v[152:155], v[210:213], 0
	v_mfma_f32_16x16x32_bf16 v[10:13], v[160:163], v[210:213], 0
	v_mfma_f32_16x16x32_bf16 v[62:65], v[156:159], v[190:193], v[62:65]
	v_mfma_f32_16x16x32_bf16 v[58:61], v[164:167], v[190:193], v[58:61]
	v_mfma_f32_16x16x32_bf16 v[50:53], v[156:159], v[198:201], v[50:53]
	v_mfma_f32_16x16x32_bf16 v[42:45], v[164:167], v[198:201], v[42:45]
	v_mfma_f32_16x16x32_bf16 v[34:37], v[156:159], v[206:209], v[34:37]
	v_mfma_f32_16x16x32_bf16 v[26:29], v[164:167], v[206:209], v[26:29]
	v_mfma_f32_16x16x32_bf16 v[18:21], v[156:159], v[214:217], v[18:21]
	v_mfma_f32_16x16x32_bf16 v[10:13], v[164:167], v[214:217], v[10:13]
	s_setprio 0
	s_setprio 1
	v_mfma_f32_16x16x32_bf16 v[54:57], v[168:171], v[186:189], 0
	v_mfma_f32_16x16x32_bf16 v[46:49], v[178:181], v[186:189], 0
	v_mfma_f32_16x16x32_bf16 v[38:41], v[168:171], v[194:197], 0
	v_mfma_f32_16x16x32_bf16 v[30:33], v[178:181], v[194:197], 0
	v_mfma_f32_16x16x32_bf16 v[22:25], v[168:171], v[202:205], 0
	v_mfma_f32_16x16x32_bf16 v[14:17], v[178:181], v[202:205], 0
	v_mfma_f32_16x16x32_bf16 v[6:9], v[168:171], v[210:213], 0
	v_mfma_f32_16x16x32_bf16 v[2:5], v[178:181], v[210:213], 0
	v_mfma_f32_16x16x32_bf16 v[54:57], v[172:175], v[190:193], v[54:57]
	v_mfma_f32_16x16x32_bf16 v[46:49], v[182:185], v[190:193], v[46:49]
	v_mfma_f32_16x16x32_bf16 v[38:41], v[172:175], v[198:201], v[38:41]
	v_mfma_f32_16x16x32_bf16 v[30:33], v[182:185], v[198:201], v[30:33]
	v_mfma_f32_16x16x32_bf16 v[22:25], v[172:175], v[206:209], v[22:25]
	v_mfma_f32_16x16x32_bf16 v[14:17], v[182:185], v[206:209], v[14:17]
	v_mfma_f32_16x16x32_bf16 v[6:9], v[172:175], v[214:217], v[6:9]
	v_mfma_f32_16x16x32_bf16 v[2:5], v[182:185], v[214:217], v[2:5]
	s_setprio 0
	s_barrier
	s_add_i32 s63, 0, 0x18000
	v_add_u32_e32 v151, s63, v146
	s_add_i32 s64, 0, 0x1c000
	ds_read_b128 v[152:155], v151
	ds_read_b128 v[156:159], v151 offset:1024
	ds_read_b128 v[160:163], v151 offset:2048
	ds_read_b128 v[164:167], v151 offset:3072
	v_add_u32_e32 v151, s64, v146
	ds_read_b128 v[168:171], v151
	ds_read_b128 v[172:175], v151 offset:1024
	ds_read_b128 v[178:181], v151 offset:2048
	ds_read_b128 v[182:185], v151 offset:3072
	s_add_u32 s2, s2, 0x40000
	s_addc_u32 s3, s3, 0
	s_mov_b32 m0, s45
	v_lshl_add_u64 v[224:225], s[2:3], 0, v[130:131]
	ds_read_b128 v[186:189], v150 offset:32768
	ds_read_b128 v[190:193], v150 offset:33792
	ds_read_b128 v[194:197], v150 offset:34816
	ds_read_b128 v[198:201], v150 offset:35840
	ds_read_b128 v[202:205], v150 offset:36864
	ds_read_b128 v[206:209], v150 offset:37888
	ds_read_b128 v[210:213], v150 offset:38912
	ds_read_b128 v[214:217], v150 offset:39936
	global_load_lds_dwordx4 v[224:225], off
	v_lshl_add_u64 v[224:225], s[2:3], 0, v[134:135]
	s_mov_b32 m0, s46
	s_nop 0
	global_load_lds_dwordx4 v[224:225], off
	s_waitcnt vmcnt(8)
	s_waitcnt lgkmcnt(0)
	s_barrier
	s_setprio 1
	s_waitcnt lgkmcnt(0)
	v_mfma_f32_16x16x32_bf16 v[126:129], v[152:155], v[186:189], v[126:129]
	v_mfma_f32_16x16x32_bf16 v[122:125], v[160:163], v[186:189], v[122:125]
	v_mfma_f32_16x16x32_bf16 v[114:117], v[152:155], v[194:197], v[114:117]
	v_mfma_f32_16x16x32_bf16 v[106:109], v[160:163], v[194:197], v[106:109]
	v_mfma_f32_16x16x32_bf16 v[98:101], v[152:155], v[202:205], v[98:101]
	v_mfma_f32_16x16x32_bf16 v[90:93], v[160:163], v[202:205], v[90:93]
	v_mfma_f32_16x16x32_bf16 v[82:85], v[152:155], v[210:213], v[82:85]
	v_mfma_f32_16x16x32_bf16 v[74:77], v[160:163], v[210:213], v[74:77]
	v_mfma_f32_16x16x32_bf16 v[126:129], v[156:159], v[190:193], v[126:129]
	v_mfma_f32_16x16x32_bf16 v[122:125], v[164:167], v[190:193], v[122:125]
	v_mfma_f32_16x16x32_bf16 v[114:117], v[156:159], v[198:201], v[114:117]
	v_mfma_f32_16x16x32_bf16 v[106:109], v[164:167], v[198:201], v[106:109]
	v_mfma_f32_16x16x32_bf16 v[98:101], v[156:159], v[206:209], v[98:101]
	v_mfma_f32_16x16x32_bf16 v[90:93], v[164:167], v[206:209], v[90:93]
	v_mfma_f32_16x16x32_bf16 v[82:85], v[156:159], v[214:217], v[82:85]
	v_mfma_f32_16x16x32_bf16 v[74:77], v[164:167], v[214:217], v[74:77]
	s_setprio 0
	s_setprio 1
	v_mfma_f32_16x16x32_bf16 v[118:121], v[168:171], v[186:189], v[118:121]
	v_mfma_f32_16x16x32_bf16 v[110:113], v[178:181], v[186:189], v[110:113]
	v_mfma_f32_16x16x32_bf16 v[102:105], v[168:171], v[194:197], v[102:105]
	v_mfma_f32_16x16x32_bf16 v[94:97], v[178:181], v[194:197], v[94:97]
	v_mfma_f32_16x16x32_bf16 v[86:89], v[168:171], v[202:205], v[86:89]
	v_mfma_f32_16x16x32_bf16 v[78:81], v[178:181], v[202:205], v[78:81]
	v_mfma_f32_16x16x32_bf16 v[70:73], v[168:171], v[210:213], v[70:73]
	v_mfma_f32_16x16x32_bf16 v[66:69], v[178:181], v[210:213], v[66:69]
	v_mfma_f32_16x16x32_bf16 v[118:121], v[172:175], v[190:193], v[118:121]
	v_mfma_f32_16x16x32_bf16 v[110:113], v[182:185], v[190:193], v[110:113]
	v_mfma_f32_16x16x32_bf16 v[102:105], v[172:175], v[198:201], v[102:105]
	v_mfma_f32_16x16x32_bf16 v[94:97], v[182:185], v[198:201], v[94:97]
	v_mfma_f32_16x16x32_bf16 v[86:89], v[172:175], v[206:209], v[86:89]
	v_mfma_f32_16x16x32_bf16 v[78:81], v[182:185], v[206:209], v[78:81]
	v_mfma_f32_16x16x32_bf16 v[70:73], v[172:175], v[214:217], v[70:73]
	v_mfma_f32_16x16x32_bf16 v[66:69], v[182:185], v[214:217], v[66:69]
	s_setprio 0
	s_barrier
	s_add_i32 s2, s63, s43
	v_lshl_add_u64 v[144:145], v[144:145], 0, s[8:9]
	s_mov_b32 m0, s2
	ds_read_b128 v[186:189], v150 offset:49152
	ds_read_b128 v[190:193], v150 offset:50176
	ds_read_b128 v[194:197], v150 offset:51200
	ds_read_b128 v[198:201], v150 offset:52224
	ds_read_b128 v[202:205], v150 offset:53248
	ds_read_b128 v[206:209], v150 offset:54272
	ds_read_b128 v[210:213], v150 offset:55296
	ds_read_b128 v[214:217], v150 offset:56320
	global_load_lds_dwordx4 v[144:145], off
	s_add_i32 m0, s2, 0x2000
	s_add_u32 s2, s38, 0x40080
	v_lshl_add_u64 v[144:145], v[218:219], 0, s[8:9]
	s_addc_u32 s3, s39, 0
	s_add_i32 s38, s64, s43
	global_load_lds_dwordx4 v[144:145], off
	v_lshl_add_u64 v[144:145], s[2:3], 0, v[132:133]
	s_mov_b32 m0, s38
	s_nop 0
	global_load_lds_dwordx4 v[144:145], off
	v_lshl_add_u64 v[144:145], s[2:3], 0, v[136:137]
	s_add_i32 m0, s38, 0x2000
	s_nop 0
	global_load_lds_dwordx4 v[144:145], off
	v_lshl_add_u64 v[144:145], v[220:221], 0, s[8:9]
	s_mov_b32 m0, s48
	s_nop 0
	global_load_lds_dwordx4 v[144:145], off
	v_lshl_add_u64 v[144:145], v[222:223], 0, s[8:9]
	s_mov_b32 m0, s49
	s_nop 0
	global_load_lds_dwordx4 v[144:145], off
	s_waitcnt vmcnt(8)
	s_waitcnt lgkmcnt(0)
	s_barrier
	s_setprio 1
	s_waitcnt lgkmcnt(0)
	v_mfma_f32_16x16x32_bf16 v[62:65], v[152:155], v[186:189], v[62:65]
	v_mfma_f32_16x16x32_bf16 v[58:61], v[160:163], v[186:189], v[58:61]
	v_mfma_f32_16x16x32_bf16 v[50:53], v[152:155], v[194:197], v[50:53]
	v_mfma_f32_16x16x32_bf16 v[42:45], v[160:163], v[194:197], v[42:45]
	v_mfma_f32_16x16x32_bf16 v[34:37], v[152:155], v[202:205], v[34:37]
	v_mfma_f32_16x16x32_bf16 v[26:29], v[160:163], v[202:205], v[26:29]
	v_mfma_f32_16x16x32_bf16 v[18:21], v[152:155], v[210:213], v[18:21]
	v_mfma_f32_16x16x32_bf16 v[10:13], v[160:163], v[210:213], v[10:13]
	v_mfma_f32_16x16x32_bf16 v[62:65], v[156:159], v[190:193], v[62:65]
	v_mfma_f32_16x16x32_bf16 v[58:61], v[164:167], v[190:193], v[58:61]
	v_mfma_f32_16x16x32_bf16 v[50:53], v[156:159], v[198:201], v[50:53]
	v_mfma_f32_16x16x32_bf16 v[42:45], v[164:167], v[198:201], v[42:45]
	v_mfma_f32_16x16x32_bf16 v[34:37], v[156:159], v[206:209], v[34:37]
	v_mfma_f32_16x16x32_bf16 v[26:29], v[164:167], v[206:209], v[26:29]
	v_mfma_f32_16x16x32_bf16 v[18:21], v[156:159], v[214:217], v[18:21]
	v_mfma_f32_16x16x32_bf16 v[10:13], v[164:167], v[214:217], v[10:13]
	s_setprio 0
	s_setprio 1
	v_mfma_f32_16x16x32_bf16 v[54:57], v[168:171], v[186:189], v[54:57]
	v_mfma_f32_16x16x32_bf16 v[46:49], v[178:181], v[186:189], v[46:49]
	v_mfma_f32_16x16x32_bf16 v[38:41], v[168:171], v[194:197], v[38:41]
	v_mfma_f32_16x16x32_bf16 v[30:33], v[178:181], v[194:197], v[30:33]
	v_mfma_f32_16x16x32_bf16 v[22:25], v[168:171], v[202:205], v[22:25]
	v_mfma_f32_16x16x32_bf16 v[14:17], v[178:181], v[202:205], v[14:17]
	v_mfma_f32_16x16x32_bf16 v[6:9], v[168:171], v[210:213], v[6:9]
	v_mfma_f32_16x16x32_bf16 v[2:5], v[178:181], v[210:213], v[2:5]
	v_mfma_f32_16x16x32_bf16 v[54:57], v[172:175], v[190:193], v[54:57]
	v_mfma_f32_16x16x32_bf16 v[46:49], v[182:185], v[190:193], v[46:49]
	v_mfma_f32_16x16x32_bf16 v[38:41], v[172:175], v[198:201], v[38:41]
	v_mfma_f32_16x16x32_bf16 v[30:33], v[182:185], v[198:201], v[30:33]
	v_mfma_f32_16x16x32_bf16 v[22:25], v[172:175], v[206:209], v[22:25]
	v_mfma_f32_16x16x32_bf16 v[14:17], v[182:185], v[206:209], v[14:17]
	v_mfma_f32_16x16x32_bf16 v[6:9], v[172:175], v[214:217], v[6:9]
	v_mfma_f32_16x16x32_bf16 v[2:5], v[182:185], v[214:217], v[2:5]
	s_setprio 0
	s_barrier
	s_add_i32 s62, s62, 2
	s_add_u32 s36, s36, 0x100
	s_addc_u32 s37, s37, 0
	s_add_u32 s60, s60, 0x100
	s_addc_u32 s61, s61, 0
	s_cmp_gt_u32 s62, 13
	s_cbranch_scc0 .LBB0_1239
	s_branch .Lpk1239_exit

.Lpk1303_peel:
	ds_read_b128 v[166:169], v139
	ds_read_b128 v[170:173], v139 offset:1024
	ds_read_b128 v[178:181], v139 offset:2048
	ds_read_b128 v[182:185], v139 offset:3072
	ds_read_b128 v[186:189], v163
	ds_read_b128 v[190:193], v163 offset:1024
	ds_read_b128 v[194:197], v163 offset:2048
	ds_read_b128 v[198:201], v163 offset:3072
	s_add_u32 s2, s26, 0xfffc0080
	s_addc_u32 s3, s27, -1
	s_cmp_eq_u32 s55, 12
	s_cselect_b32 s3, s11, s3
	s_cselect_b32 s2, s13, s2
	s_cselect_b32 s29, s47, s54
	s_cselect_b32 s28, s52, s53
	v_lshl_add_u64 v[148:149], s[26:27], 0, v[142:143]
	s_add_i32 m0, s34, 0xc000
	ds_read_b128 v[202:205], v164
	ds_read_b128 v[206:209], v164 offset:1024
	ds_read_b128 v[210:213], v164 offset:2048
	ds_read_b128 v[214:217], v164 offset:3072
	ds_read_b128 v[218:221], v164 offset:4096
	ds_read_b128 v[222:225], v164 offset:5120
	ds_read_b128 v[226:229], v164 offset:6144
	ds_read_b128 v[230:233], v164 offset:7168
	global_load_lds_dwordx4 v[148:149], off
	v_lshl_add_u64 v[148:149], s[26:27], 0, v[144:145]
	s_add_i32 m0, s34, 0xe000
	s_nop 0
	global_load_lds_dwordx4 v[148:149], off
	s_waitcnt vmcnt(16)
	s_waitcnt lgkmcnt(0)
	s_barrier
	s_setprio 1
	s_waitcnt lgkmcnt(0)
	v_mfma_f32_16x16x32_bf16 v[126:129], v[166:169], v[202:205], 0
	v_mfma_f32_16x16x32_bf16 v[122:125], v[178:181], v[202:205], 0
	v_mfma_f32_16x16x32_bf16 v[110:113], v[166:169], v[210:213], 0
	v_mfma_f32_16x16x32_bf16 v[106:109], v[178:181], v[210:213], 0
	v_mfma_f32_16x16x32_bf16 v[94:97], v[166:169], v[218:221], 0
	v_mfma_f32_16x16x32_bf16 v[90:93], v[178:181], v[218:221], 0
	v_mfma_f32_16x16x32_bf16 v[78:81], v[166:169], v[226:229], 0
	v_mfma_f32_16x16x32_bf16 v[74:77], v[178:181], v[226:229], 0
	v_mfma_f32_16x16x32_bf16 v[126:129], v[170:173], v[206:209], v[126:129]
	v_mfma_f32_16x16x32_bf16 v[122:125], v[182:185], v[206:209], v[122:125]
	v_mfma_f32_16x16x32_bf16 v[110:113], v[170:173], v[214:217], v[110:113]
	v_mfma_f32_16x16x32_bf16 v[106:109], v[182:185], v[214:217], v[106:109]
	v_mfma_f32_16x16x32_bf16 v[94:97], v[170:173], v[222:225], v[94:97]
	v_mfma_f32_16x16x32_bf16 v[90:93], v[182:185], v[222:225], v[90:93]
	v_mfma_f32_16x16x32_bf16 v[78:81], v[170:173], v[230:233], v[78:81]
	v_mfma_f32_16x16x32_bf16 v[74:77], v[182:185], v[230:233], v[74:77]
	s_setprio 0
	s_setprio 1
	v_mfma_f32_16x16x32_bf16 v[118:121], v[186:189], v[202:205], 0
	v_mfma_f32_16x16x32_bf16 v[114:117], v[194:197], v[202:205], 0
	v_mfma_f32_16x16x32_bf16 v[102:105], v[186:189], v[210:213], 0
	v_mfma_f32_16x16x32_bf16 v[98:101], v[194:197], v[210:213], 0
	v_mfma_f32_16x16x32_bf16 v[86:89], v[186:189], v[218:221], 0
	v_mfma_f32_16x16x32_bf16 v[82:85], v[194:197], v[218:221], 0
	v_mfma_f32_16x16x32_bf16 v[70:73], v[186:189], v[226:229], 0
	v_mfma_f32_16x16x32_bf16 v[66:69], v[194:197], v[226:229], 0
	v_mfma_f32_16x16x32_bf16 v[118:121], v[190:193], v[206:209], v[118:121]
	v_mfma_f32_16x16x32_bf16 v[114:117], v[198:201], v[206:209], v[114:117]
	v_mfma_f32_16x16x32_bf16 v[102:105], v[190:193], v[214:217], v[102:105]
	v_mfma_f32_16x16x32_bf16 v[98:101], v[198:201], v[214:217], v[98:101]
	v_mfma_f32_16x16x32_bf16 v[86:89], v[190:193], v[222:225], v[86:89]
	v_mfma_f32_16x16x32_bf16 v[82:85], v[198:201], v[222:225], v[82:85]
	v_mfma_f32_16x16x32_bf16 v[70:73], v[190:193], v[230:233], v[70:73]
	v_mfma_f32_16x16x32_bf16 v[66:69], v[198:201], v[230:233], v[66:69]
	s_setprio 0
	s_barrier
	s_add_i32 s56, s42, s30
	v_lshl_add_u64 v[148:149], s[28:29], 0, v[132:133]
	s_mov_b32 m0, s56
	ds_read_b128 v[202:205], v164 offset:16384
	ds_read_b128 v[206:209], v164 offset:17408
	ds_read_b128 v[210:213], v164 offset:18432
	ds_read_b128 v[214:217], v164 offset:19456
	ds_read_b128 v[218:221], v164 offset:20480
	ds_read_b128 v[222:225], v164 offset:21504
	ds_read_b128 v[226:229], v164 offset:22528
	ds_read_b128 v[230:233], v164 offset:23552
	global_load_lds_dwordx4 v[148:149], off
	s_add_i32 m0, s56, 0x2000
	s_add_u32 s56, s28, 0x40000
	v_lshl_add_u64 v[174:175], s[28:29], 0, v[136:137]
	s_addc_u32 s57, s29, 0
	s_add_i32 s58, s43, s30
	global_load_lds_dwordx4 v[174:175], off
	v_lshl_add_u64 v[234:235], s[56:57], 0, v[132:133]
	s_mov_b32 m0, s58
	v_lshl_add_u64 v[236:237], s[2:3], 0, v[134:135]
	global_load_lds_dwordx4 v[234:235], off
	v_lshl_add_u64 v[234:235], s[56:57], 0, v[136:137]
	s_add_i32 m0, s58, 0x2000
	s_nop 0
	global_load_lds_dwordx4 v[234:235], off
	v_lshl_add_u64 v[234:235], s[2:3], 0, v[130:131]
	s_mov_b32 m0, s34
	s_nop 0
	global_load_lds_dwordx4 v[234:235], off
	s_mov_b32 m0, s25
	s_nop 0
	global_load_lds_dwordx4 v[236:237], off
	s_waitcnt vmcnt(16)
	s_waitcnt lgkmcnt(0)
	s_barrier
	s_setprio 1
	s_waitcnt lgkmcnt(0)
	v_mfma_f32_16x16x32_bf16 v[62:65], v[166:169], v[202:205], 0
	v_mfma_f32_16x16x32_bf16 v[58:61], v[178:181], v[202:205], 0
	v_mfma_f32_16x16x32_bf16 v[46:49], v[166:169], v[210:213], 0
	v_mfma_f32_16x16x32_bf16 v[42:45], v[178:181], v[210:213], 0
	v_mfma_f32_16x16x32_bf16 v[30:33], v[166:169], v[218:221], 0
	v_mfma_f32_16x16x32_bf16 v[26:29], v[178:181], v[218:221], 0
	v_mfma_f32_16x16x32_bf16 v[14:17], v[166:169], v[226:229], 0
	v_mfma_f32_16x16x32_bf16 v[10:13], v[178:181], v[226:229], 0
	v_mfma_f32_16x16x32_bf16 v[62:65], v[170:173], v[206:209], v[62:65]
	v_mfma_f32_16x16x32_bf16 v[58:61], v[182:185], v[206:209], v[58:61]
	v_mfma_f32_16x16x32_bf16 v[46:49], v[170:173], v[214:217], v[46:49]
	v_mfma_f32_16x16x32_bf16 v[42:45], v[182:185], v[214:217], v[42:45]
	v_mfma_f32_16x16x32_bf16 v[30:33], v[170:173], v[222:225], v[30:33]
	v_mfma_f32_16x16x32_bf16 v[26:29], v[182:185], v[222:225], v[26:29]
	v_mfma_f32_16x16x32_bf16 v[14:17], v[170:173], v[230:233], v[14:17]
	v_mfma_f32_16x16x32_bf16 v[10:13], v[182:185], v[230:233], v[10:13]
	s_setprio 0
	s_setprio 1
	v_mfma_f32_16x16x32_bf16 v[54:57], v[186:189], v[202:205], 0
	v_mfma_f32_16x16x32_bf16 v[50:53], v[194:197], v[202:205], 0
	v_mfma_f32_16x16x32_bf16 v[38:41], v[186:189], v[210:213], 0
	v_mfma_f32_16x16x32_bf16 v[34:37], v[194:197], v[210:213], 0
	v_mfma_f32_16x16x32_bf16 v[22:25], v[186:189], v[218:221], 0
	v_mfma_f32_16x16x32_bf16 v[18:21], v[194:197], v[218:221], 0
	v_mfma_f32_16x16x32_bf16 v[6:9], v[186:189], v[226:229], 0
	v_mfma_f32_16x16x32_bf16 v[2:5], v[194:197], v[226:229], 0
	v_mfma_f32_16x16x32_bf16 v[54:57], v[190:193], v[206:209], v[54:57]
	v_mfma_f32_16x16x32_bf16 v[50:53], v[198:201], v[206:209], v[50:53]
	v_mfma_f32_16x16x32_bf16 v[38:41], v[190:193], v[214:217], v[38:41]
	v_mfma_f32_16x16x32_bf16 v[34:37], v[198:201], v[214:217], v[34:37]
	v_mfma_f32_16x16x32_bf16 v[22:25], v[190:193], v[222:225], v[22:25]
	v_mfma_f32_16x16x32_bf16 v[18:21], v[198:201], v[222:225], v[18:21]
	v_mfma_f32_16x16x32_bf16 v[6:9], v[190:193], v[230:233], v[6:9]
	v_mfma_f32_16x16x32_bf16 v[2:5], v[198:201], v[230:233], v[2:5]
	s_setprio 0
	s_barrier
	s_add_i32 s56, 0, 0x18000
	v_add_u32_e32 v165, s56, v162
	s_add_i32 s57, 0, 0x1c000
	ds_read_b128 v[166:169], v165
	ds_read_b128 v[170:173], v165 offset:1024
	ds_read_b128 v[178:181], v165 offset:2048
	ds_read_b128 v[182:185], v165 offset:3072
	v_add_u32_e32 v165, s57, v162
	ds_read_b128 v[186:189], v165
	ds_read_b128 v[190:193], v165 offset:1024
	ds_read_b128 v[194:197], v165 offset:2048
	ds_read_b128 v[198:201], v165 offset:3072
	s_add_u32 s2, s2, 0x40000
	s_addc_u32 s3, s3, 0
	s_mov_b32 m0, s35
	v_lshl_add_u64 v[238:239], s[2:3], 0, v[130:131]
	ds_read_b128 v[202:205], v164 offset:32768
	ds_read_b128 v[206:209], v164 offset:33792
	ds_read_b128 v[210:213], v164 offset:34816
	ds_read_b128 v[214:217], v164 offset:35840
	ds_read_b128 v[218:221], v164 offset:36864
	ds_read_b128 v[222:225], v164 offset:37888
	ds_read_b128 v[226:229], v164 offset:38912
	ds_read_b128 v[230:233], v164 offset:39936
	global_load_lds_dwordx4 v[238:239], off
	v_lshl_add_u64 v[238:239], s[2:3], 0, v[134:135]
	s_mov_b32 m0, s36
	s_nop 0
	global_load_lds_dwordx4 v[238:239], off
	s_waitcnt vmcnt(8)
	s_waitcnt lgkmcnt(0)
	s_barrier
	s_setprio 1
	s_waitcnt lgkmcnt(0)
	v_mfma_f32_16x16x32_bf16 v[126:129], v[166:169], v[202:205], v[126:129]
	v_mfma_f32_16x16x32_bf16 v[122:125], v[178:181], v[202:205], v[122:125]
	v_mfma_f32_16x16x32_bf16 v[110:113], v[166:169], v[210:213], v[110:113]
	v_mfma_f32_16x16x32_bf16 v[106:109], v[178:181], v[210:213], v[106:109]
	v_mfma_f32_16x16x32_bf16 v[94:97], v[166:169], v[218:221], v[94:97]
	v_mfma_f32_16x16x32_bf16 v[90:93], v[178:181], v[218:221], v[90:93]
	v_mfma_f32_16x16x32_bf16 v[78:81], v[166:169], v[226:229], v[78:81]
	v_mfma_f32_16x16x32_bf16 v[74:77], v[178:181], v[226:229], v[74:77]
	v_mfma_f32_16x16x32_bf16 v[126:129], v[170:173], v[206:209], v[126:129]
	v_mfma_f32_16x16x32_bf16 v[122:125], v[182:185], v[206:209], v[122:125]
	v_mfma_f32_16x16x32_bf16 v[110:113], v[170:173], v[214:217], v[110:113]
	v_mfma_f32_16x16x32_bf16 v[106:109], v[182:185], v[214:217], v[106:109]
	v_mfma_f32_16x16x32_bf16 v[94:97], v[170:173], v[222:225], v[94:97]
	v_mfma_f32_16x16x32_bf16 v[90:93], v[182:185], v[222:225], v[90:93]
	v_mfma_f32_16x16x32_bf16 v[78:81], v[170:173], v[230:233], v[78:81]
	v_mfma_f32_16x16x32_bf16 v[74:77], v[182:185], v[230:233], v[74:77]
	s_setprio 0
	s_setprio 1
	v_mfma_f32_16x16x32_bf16 v[118:121], v[186:189], v[202:205], v[118:121]
	v_mfma_f32_16x16x32_bf16 v[114:117], v[194:197], v[202:205], v[114:117]
	v_mfma_f32_16x16x32_bf16 v[102:105], v[186:189], v[210:213], v[102:105]
	v_mfma_f32_16x16x32_bf16 v[98:101], v[194:197], v[210:213], v[98:101]
	v_mfma_f32_16x16x32_bf16 v[86:89], v[186:189], v[218:221], v[86:89]
	v_mfma_f32_16x16x32_bf16 v[82:85], v[194:197], v[218:221], v[82:85]
	v_mfma_f32_16x16x32_bf16 v[70:73], v[186:189], v[226:229], v[70:73]
	v_mfma_f32_16x16x32_bf16 v[66:69], v[194:197], v[226:229], v[66:69]
	v_mfma_f32_16x16x32_bf16 v[118:121], v[190:193], v[206:209], v[118:121]
	v_mfma_f32_16x16x32_bf16 v[114:117], v[198:201], v[206:209], v[114:117]
	v_mfma_f32_16x16x32_bf16 v[102:105], v[190:193], v[214:217], v[102:105]
	v_mfma_f32_16x16x32_bf16 v[98:101], v[198:201], v[214:217], v[98:101]
	v_mfma_f32_16x16x32_bf16 v[86:89], v[190:193], v[222:225], v[86:89]
	v_mfma_f32_16x16x32_bf16 v[82:85], v[198:201], v[222:225], v[82:85]
	v_mfma_f32_16x16x32_bf16 v[70:73], v[190:193], v[230:233], v[70:73]
	v_mfma_f32_16x16x32_bf16 v[66:69], v[198:201], v[230:233], v[66:69]
	s_setprio 0
	s_barrier
	s_add_i32 s2, s56, s30
	v_lshl_add_u64 v[148:149], v[148:149], 0, s[6:7]
	s_mov_b32 m0, s2
	ds_read_b128 v[202:205], v164 offset:49152
	ds_read_b128 v[206:209], v164 offset:50176
	ds_read_b128 v[210:213], v164 offset:51200
	ds_read_b128 v[214:217], v164 offset:52224
	ds_read_b128 v[218:221], v164 offset:53248
	ds_read_b128 v[222:225], v164 offset:54272
	ds_read_b128 v[226:229], v164 offset:55296
	ds_read_b128 v[230:233], v164 offset:56320
	global_load_lds_dwordx4 v[148:149], off
	s_add_i32 m0, s2, 0x2000
	s_add_u32 s2, s28, 0x40080
	v_lshl_add_u64 v[148:149], v[174:175], 0, s[6:7]
	s_addc_u32 s3, s29, 0
	s_add_i32 s28, s57, s30
	global_load_lds_dwordx4 v[148:149], off
	v_lshl_add_u64 v[148:149], s[2:3], 0, v[132:133]
	s_mov_b32 m0, s28
	s_nop 0
	global_load_lds_dwordx4 v[148:149], off
	v_lshl_add_u64 v[148:149], s[2:3], 0, v[136:137]
	s_add_i32 m0, s28, 0x2000
	s_nop 0
	global_load_lds_dwordx4 v[148:149], off
	v_lshl_add_u64 v[148:149], v[234:235], 0, s[6:7]
	s_mov_b32 m0, s39
	s_nop 0
	global_load_lds_dwordx4 v[148:149], off
	v_lshl_add_u64 v[148:149], v[236:237], 0, s[6:7]
	s_mov_b32 m0, s40
	s_nop 0
	global_load_lds_dwordx4 v[148:149], off
	s_waitcnt vmcnt(8)
	s_waitcnt lgkmcnt(0)
	s_barrier
	s_setprio 1
	s_waitcnt lgkmcnt(0)
	v_mfma_f32_16x16x32_bf16 v[62:65], v[166:169], v[202:205], v[62:65]
	v_mfma_f32_16x16x32_bf16 v[58:61], v[178:181], v[202:205], v[58:61]
	v_mfma_f32_16x16x32_bf16 v[46:49], v[166:169], v[210:213], v[46:49]
	v_mfma_f32_16x16x32_bf16 v[42:45], v[178:181], v[210:213], v[42:45]
	v_mfma_f32_16x16x32_bf16 v[30:33], v[166:169], v[218:221], v[30:33]
	v_mfma_f32_16x16x32_bf16 v[26:29], v[178:181], v[218:221], v[26:29]
	v_mfma_f32_16x16x32_bf16 v[14:17], v[166:169], v[226:229], v[14:17]
	v_mfma_f32_16x16x32_bf16 v[10:13], v[178:181], v[226:229], v[10:13]
	v_mfma_f32_16x16x32_bf16 v[62:65], v[170:173], v[206:209], v[62:65]
	v_mfma_f32_16x16x32_bf16 v[58:61], v[182:185], v[206:209], v[58:61]
	v_mfma_f32_16x16x32_bf16 v[46:49], v[170:173], v[214:217], v[46:49]
	v_mfma_f32_16x16x32_bf16 v[42:45], v[182:185], v[214:217], v[42:45]
	v_mfma_f32_16x16x32_bf16 v[30:33], v[170:173], v[222:225], v[30:33]
	v_mfma_f32_16x16x32_bf16 v[26:29], v[182:185], v[222:225], v[26:29]
	v_mfma_f32_16x16x32_bf16 v[14:17], v[170:173], v[230:233], v[14:17]
	v_mfma_f32_16x16x32_bf16 v[10:13], v[182:185], v[230:233], v[10:13]
	s_setprio 0
	s_setprio 1
	v_mfma_f32_16x16x32_bf16 v[54:57], v[186:189], v[202:205], v[54:57]
	v_mfma_f32_16x16x32_bf16 v[50:53], v[194:197], v[202:205], v[50:53]
	v_mfma_f32_16x16x32_bf16 v[38:41], v[186:189], v[210:213], v[38:41]
	v_mfma_f32_16x16x32_bf16 v[34:37], v[194:197], v[210:213], v[34:37]
	v_mfma_f32_16x16x32_bf16 v[22:25], v[186:189], v[218:221], v[22:25]
	v_mfma_f32_16x16x32_bf16 v[18:21], v[194:197], v[218:221], v[18:21]
	v_mfma_f32_16x16x32_bf16 v[6:9], v[186:189], v[226:229], v[6:9]
	v_mfma_f32_16x16x32_bf16 v[2:5], v[194:197], v[226:229], v[2:5]
	v_mfma_f32_16x16x32_bf16 v[54:57], v[190:193], v[206:209], v[54:57]
	v_mfma_f32_16x16x32_bf16 v[50:53], v[198:201], v[206:209], v[50:53]
	v_mfma_f32_16x16x32_bf16 v[38:41], v[190:193], v[214:217], v[38:41]
	v_mfma_f32_16x16x32_bf16 v[34:37], v[198:201], v[214:217], v[34:37]
	v_mfma_f32_16x16x32_bf16 v[22:25], v[190:193], v[222:225], v[22:25]
	v_mfma_f32_16x16x32_bf16 v[18:21], v[198:201], v[222:225], v[18:21]
	v_mfma_f32_16x16x32_bf16 v[6:9], v[190:193], v[230:233], v[6:9]
	v_mfma_f32_16x16x32_bf16 v[2:5], v[198:201], v[230:233], v[2:5]
	s_setprio 0
	s_barrier
	s_add_i32 s55, s55, 2
	s_add_u32 s26, s26, 0x100
	s_addc_u32 s27, s27, 0
	s_add_u32 s53, s53, 0x100
	s_addc_u32 s54, s54, 0
	s_cmp_gt_u32 s55, 13
	s_cbranch_scc0 .LBB0_1303
	s_branch .Lpk1303_exit

.LBB0_1393:
	s_mov_b64 s[6:7], 0x80
	s_add_i32 m0, s25, 0x18000
	v_lshl_add_u64 v[8:9], v[8:9], 0, s[6:7]
	s_and_b32 s9, s3, 3
	s_lshl_b32 s12, s8, 13
	s_waitcnt vmcnt(2)
	s_barrier
	global_load_lds_dwordx4 v[8:9], off
	v_lshl_add_u64 v[6:7], v[6:7], 0, s[6:7]
	s_add_i32 m0, s25, 0x1a000
	s_add_i32 s40, s25, 0x8000
	s_add_i32 s41, s25, 0xa000
	global_load_lds_dwordx4 v[6:7], off
	v_lshl_add_u64 v[4:5], v[4:5], 0, s[6:7]
	s_mov_b32 m0, s40
	s_add_u32 s10, s30, 0x40080
	global_load_lds_dwordx4 v[4:5], off
	v_lshl_add_u64 v[2:3], v[2:3], 0, s[6:7]
	s_mov_b32 m0, s41
	s_addc_u32 s11, s31, 0
	global_load_lds_dwordx4 v[2:3], off
	s_add_i32 m0, s25, 0x1c000
	v_lshl_add_u64 v[2:3], s[10:11], 0, v[132:133]
	global_load_lds_dwordx4 v[2:3], off
	v_lshl_add_u64 v[2:3], s[10:11], 0, v[136:137]
	s_add_i32 m0, s25, 0x1e000
	s_cmpk_lt_u32 s2, 0x100
	global_load_lds_dwordx4 v[2:3], off
	v_lshl_or_b32 v2, s8, 6, v155
	v_lshl_or_b32 v148, s9, 12, v156
	s_cselect_b64 s[8:9], -1, 0
	s_lshl_b32 s2, s3, 6
	v_lshlrev_b32_e32 v4, 2, v155
	s_bfe_u32 s42, s3, 0x10001
	s_and_b32 s2, s2, 64
	v_readlane_b32 s3, v253, 54
	v_lshl_or_b32 v3, v155, 6, v138
	v_and_b32_e32 v4, 32, v4
	s_add_u32 s2, s3, s2
	v_readlane_b32 s3, v253, 7
	v_bitop3_b32 v6, v3, s12, v4 bitop3:0xde
	v_mov_b32_e32 v3, v133
	s_addc_u32 s3, s3, 0
	v_mov_b32_e32 v139, v133
	v_lshl_add_u64 v[4:5], s[2:3], 0, v[138:139]
	v_lshlrev_b64 v[2:3], 7, v[2:3]
	v_lshl_add_u64 v[138:139], v[4:5], 0, v[2:3]
	v_lshlrev_b32_e32 v2, 8, v0
	v_and_b32_e32 v2, 0x18000, v2
	v_lshlrev_b32_e32 v3, 11, v153
	v_or3_b32 v2, v1, v2, v3
	v_add_u32_e32 v140, v2, v152
	v_lshlrev_b32_e32 v2, 4, v154
	s_waitcnt vmcnt(6)
	v_and_b32_e32 v2, 0x38000, v2
	v_or3_b32 v1, v1, v2, v3
	s_add_i32 s43, 0, 0x10000
	s_add_i32 s44, 0, 0x14000
	v_mov_b32_e32 v141, v133
	v_add_u32_e32 v142, v1, v152
	v_mov_b32_e32 v143, v133
	v_add_u32_e32 v1, s43, v148
	v_add_u32_e32 v149, s44, v148
	v_add_u32_e32 v150, 0, v6
	s_movk_i32 s45, 0x1000
	s_movk_i32 s46, 0x5000
	v_mov_b64_e32 v[144:145], 0xaff
	s_barrier
	s_waitcnt vmcnt(0)
	s_branch .LBB0_1396

.Lpk1400_peel:
	ds_read_b128 v[152:155], v1
	ds_read_b128 v[156:159], v1 offset:1024
	ds_read_b128 v[160:163], v1 offset:2048
	ds_read_b128 v[164:167], v1 offset:3072
	ds_read_b128 v[168:171], v149
	ds_read_b128 v[172:175], v149 offset:1024
	ds_read_b128 v[178:181], v149 offset:2048
	ds_read_b128 v[182:185], v149 offset:3072
	s_add_u32 s2, s28, 0xfffc0080
	s_addc_u32 s3, s29, -1
	s_cmp_eq_u32 s55, 12
	s_cselect_b32 s3, s11, s3
	s_cselect_b32 s2, s13, s2
	s_cselect_b32 s31, s47, s54
	s_cselect_b32 s30, s52, s53
	v_lshl_add_u64 v[146:147], s[28:29], 0, v[140:141]
	s_add_i32 m0, s25, 0xc000
	ds_read_b128 v[186:189], v150
	ds_read_b128 v[190:193], v150 offset:1024
	ds_read_b128 v[194:197], v150 offset:2048
	ds_read_b128 v[198:201], v150 offset:3072
	ds_read_b128 v[202:205], v150 offset:4096
	ds_read_b128 v[206:209], v150 offset:5120
	ds_read_b128 v[210:213], v150 offset:6144
	ds_read_b128 v[214:217], v150 offset:7168
	global_load_lds_dwordx4 v[146:147], off
	v_lshl_add_u64 v[146:147], s[28:29], 0, v[142:143]
	s_add_i32 m0, s25, 0xe000
	s_nop 0
	global_load_lds_dwordx4 v[146:147], off
	s_waitcnt vmcnt(16)
	s_waitcnt lgkmcnt(0)
	s_barrier
	s_setprio 1
	s_waitcnt lgkmcnt(0)
	v_mfma_f32_16x16x32_bf16 v[126:129], v[152:155], v[186:189], 0
	v_mfma_f32_16x16x32_bf16 v[122:125], v[160:163], v[186:189], 0
	v_mfma_f32_16x16x32_bf16 v[110:113], v[152:155], v[194:197], 0
	v_mfma_f32_16x16x32_bf16 v[106:109], v[160:163], v[194:197], 0
	v_mfma_f32_16x16x32_bf16 v[94:97], v[152:155], v[202:205], 0
	v_mfma_f32_16x16x32_bf16 v[90:93], v[160:163], v[202:205], 0
	v_mfma_f32_16x16x32_bf16 v[78:81], v[152:155], v[210:213], 0
	v_mfma_f32_16x16x32_bf16 v[74:77], v[160:163], v[210:213], 0
	v_mfma_f32_16x16x32_bf16 v[126:129], v[156:159], v[190:193], v[126:129]
	v_mfma_f32_16x16x32_bf16 v[122:125], v[164:167], v[190:193], v[122:125]
	v_mfma_f32_16x16x32_bf16 v[110:113], v[156:159], v[198:201], v[110:113]
	v_mfma_f32_16x16x32_bf16 v[106:109], v[164:167], v[198:201], v[106:109]
	v_mfma_f32_16x16x32_bf16 v[94:97], v[156:159], v[206:209], v[94:97]
	v_mfma_f32_16x16x32_bf16 v[90:93], v[164:167], v[206:209], v[90:93]
	v_mfma_f32_16x16x32_bf16 v[78:81], v[156:159], v[214:217], v[78:81]
	v_mfma_f32_16x16x32_bf16 v[74:77], v[164:167], v[214:217], v[74:77]
	s_setprio 0
	s_setprio 1
	v_mfma_f32_16x16x32_bf16 v[118:121], v[168:171], v[186:189], 0
	v_mfma_f32_16x16x32_bf16 v[114:117], v[178:181], v[186:189], 0
	v_mfma_f32_16x16x32_bf16 v[102:105], v[168:171], v[194:197], 0
	v_mfma_f32_16x16x32_bf16 v[98:101], v[178:181], v[194:197], 0
	v_mfma_f32_16x16x32_bf16 v[86:89], v[168:171], v[202:205], 0
	v_mfma_f32_16x16x32_bf16 v[82:85], v[178:181], v[202:205], 0
	v_mfma_f32_16x16x32_bf16 v[70:73], v[168:171], v[210:213], 0
	v_mfma_f32_16x16x32_bf16 v[66:69], v[178:181], v[210:213], 0
	v_mfma_f32_16x16x32_bf16 v[118:121], v[172:175], v[190:193], v[118:121]
	v_mfma_f32_16x16x32_bf16 v[114:117], v[182:185], v[190:193], v[114:117]
	v_mfma_f32_16x16x32_bf16 v[102:105], v[172:175], v[198:201], v[102:105]
	v_mfma_f32_16x16x32_bf16 v[98:101], v[182:185], v[198:201], v[98:101]
	v_mfma_f32_16x16x32_bf16 v[86:89], v[172:175], v[206:209], v[86:89]
	v_mfma_f32_16x16x32_bf16 v[82:85], v[182:185], v[206:209], v[82:85]
	v_mfma_f32_16x16x32_bf16 v[70:73], v[172:175], v[214:217], v[70:73]
	v_mfma_f32_16x16x32_bf16 v[66:69], v[182:185], v[214:217], v[66:69]
	s_setprio 0
	s_barrier
	s_add_i32 s56, s43, s34
	v_lshl_add_u64 v[146:147], s[30:31], 0, v[132:133]
	s_mov_b32 m0, s56
	ds_read_b128 v[186:189], v150 offset:16384
	ds_read_b128 v[190:193], v150 offset:17408
	ds_read_b128 v[194:197], v150 offset:18432
	ds_read_b128 v[198:201], v150 offset:19456
	ds_read_b128 v[202:205], v150 offset:20480
	ds_read_b128 v[206:209], v150 offset:21504
	ds_read_b128 v[210:213], v150 offset:22528
	ds_read_b128 v[214:217], v150 offset:23552
	global_load_lds_dwordx4 v[146:147], off
	s_add_i32 m0, s56, 0x2000
	s_add_u32 s56, s30, 0x40000
	v_lshl_add_u64 v[218:219], s[30:31], 0, v[136:137]
	s_addc_u32 s57, s31, 0
	s_add_i32 s58, s44, s34
	global_load_lds_dwordx4 v[218:219], off
	v_lshl_add_u64 v[220:221], s[56:57], 0, v[132:133]
	s_mov_b32 m0, s58
	v_lshl_add_u64 v[222:223], s[2:3], 0, v[134:135]
	global_load_lds_dwordx4 v[220:221], off
	v_lshl_add_u64 v[220:221], s[56:57], 0, v[136:137]
	s_add_i32 m0, s58, 0x2000
	s_nop 0
	global_load_lds_dwordx4 v[220:221], off
	v_lshl_add_u64 v[220:221], s[2:3], 0, v[130:131]
	s_mov_b32 m0, s25
	s_nop 0
	global_load_lds_dwordx4 v[220:221], off
	s_mov_b32 m0, s27
	s_nop 0
	global_load_lds_dwordx4 v[222:223], off
	s_waitcnt vmcnt(16)
	s_waitcnt lgkmcnt(0)
	s_barrier
	s_setprio 1
	s_waitcnt lgkmcnt(0)
	v_mfma_f32_16x16x32_bf16 v[62:65], v[152:155], v[186:189], 0
	v_mfma_f32_16x16x32_bf16 v[58:61], v[160:163], v[186:189], 0
	v_mfma_f32_16x16x32_bf16 v[46:49], v[152:155], v[194:197], 0
	v_mfma_f32_16x16x32_bf16 v[42:45], v[160:163], v[194:197], 0
	v_mfma_f32_16x16x32_bf16 v[30:33], v[152:155], v[202:205], 0
	v_mfma_f32_16x16x32_bf16 v[26:29], v[160:163], v[202:205], 0
	v_mfma_f32_16x16x32_bf16 v[14:17], v[152:155], v[210:213], 0
	v_mfma_f32_16x16x32_bf16 v[10:13], v[160:163], v[210:213], 0
	v_mfma_f32_16x16x32_bf16 v[62:65], v[156:159], v[190:193], v[62:65]
	v_mfma_f32_16x16x32_bf16 v[58:61], v[164:167], v[190:193], v[58:61]
	v_mfma_f32_16x16x32_bf16 v[46:49], v[156:159], v[198:201], v[46:49]
	v_mfma_f32_16x16x32_bf16 v[42:45], v[164:167], v[198:201], v[42:45]
	v_mfma_f32_16x16x32_bf16 v[30:33], v[156:159], v[206:209], v[30:33]
	v_mfma_f32_16x16x32_bf16 v[26:29], v[164:167], v[206:209], v[26:29]
	v_mfma_f32_16x16x32_bf16 v[14:17], v[156:159], v[214:217], v[14:17]
	v_mfma_f32_16x16x32_bf16 v[10:13], v[164:167], v[214:217], v[10:13]
	s_setprio 0
	s_setprio 1
	v_mfma_f32_16x16x32_bf16 v[54:57], v[168:171], v[186:189], 0
	v_mfma_f32_16x16x32_bf16 v[50:53], v[178:181], v[186:189], 0
	v_mfma_f32_16x16x32_bf16 v[38:41], v[168:171], v[194:197], 0
	v_mfma_f32_16x16x32_bf16 v[34:37], v[178:181], v[194:197], 0
	v_mfma_f32_16x16x32_bf16 v[22:25], v[168:171], v[202:205], 0
	v_mfma_f32_16x16x32_bf16 v[18:21], v[178:181], v[202:205], 0
	v_mfma_f32_16x16x32_bf16 v[6:9], v[168:171], v[210:213], 0
	v_mfma_f32_16x16x32_bf16 v[2:5], v[178:181], v[210:213], 0
	v_mfma_f32_16x16x32_bf16 v[54:57], v[172:175], v[190:193], v[54:57]
	v_mfma_f32_16x16x32_bf16 v[50:53], v[182:185], v[190:193], v[50:53]
	v_mfma_f32_16x16x32_bf16 v[38:41], v[172:175], v[198:201], v[38:41]
	v_mfma_f32_16x16x32_bf16 v[34:37], v[182:185], v[198:201], v[34:37]
	v_mfma_f32_16x16x32_bf16 v[22:25], v[172:175], v[206:209], v[22:25]
	v_mfma_f32_16x16x32_bf16 v[18:21], v[182:185], v[206:209], v[18:21]
	v_mfma_f32_16x16x32_bf16 v[6:9], v[172:175], v[214:217], v[6:9]
	v_mfma_f32_16x16x32_bf16 v[2:5], v[182:185], v[214:217], v[2:5]
	s_setprio 0
	s_barrier
	s_add_i32 s56, 0, 0x18000
	v_add_u32_e32 v151, s56, v148
	s_add_i32 s57, 0, 0x1c000
	ds_read_b128 v[152:155], v151
	ds_read_b128 v[156:159], v151 offset:1024
	ds_read_b128 v[160:163], v151 offset:2048
	ds_read_b128 v[164:167], v151 offset:3072
	v_add_u32_e32 v151, s57, v148
	ds_read_b128 v[168:171], v151
	ds_read_b128 v[172:175], v151 offset:1024
	ds_read_b128 v[178:181], v151 offset:2048
	ds_read_b128 v[182:185], v151 offset:3072
	s_add_u32 s2, s2, 0x40000
	s_addc_u32 s3, s3, 0
	s_mov_b32 m0, s36
	v_lshl_add_u64 v[224:225], s[2:3], 0, v[130:131]
	ds_read_b128 v[186:189], v150 offset:32768
	ds_read_b128 v[190:193], v150 offset:33792
	ds_read_b128 v[194:197], v150 offset:34816
	ds_read_b128 v[198:201], v150 offset:35840
	ds_read_b128 v[202:205], v150 offset:36864
	ds_read_b128 v[206:209], v150 offset:37888
	ds_read_b128 v[210:213], v150 offset:38912
	ds_read_b128 v[214:217], v150 offset:39936
	global_load_lds_dwordx4 v[224:225], off
	v_lshl_add_u64 v[224:225], s[2:3], 0, v[134:135]
	s_mov_b32 m0, s37
	s_nop 0
	global_load_lds_dwordx4 v[224:225], off
	s_waitcnt vmcnt(8)
	s_waitcnt lgkmcnt(0)
	s_barrier
	s_setprio 1
	s_waitcnt lgkmcnt(0)
	v_mfma_f32_16x16x32_bf16 v[126:129], v[152:155], v[186:189], v[126:129]
	v_mfma_f32_16x16x32_bf16 v[122:125], v[160:163], v[186:189], v[122:125]
	v_mfma_f32_16x16x32_bf16 v[110:113], v[152:155], v[194:197], v[110:113]
	v_mfma_f32_16x16x32_bf16 v[106:109], v[160:163], v[194:197], v[106:109]
	v_mfma_f32_16x16x32_bf16 v[94:97], v[152:155], v[202:205], v[94:97]
	v_mfma_f32_16x16x32_bf16 v[90:93], v[160:163], v[202:205], v[90:93]
	v_mfma_f32_16x16x32_bf16 v[78:81], v[152:155], v[210:213], v[78:81]
	v_mfma_f32_16x16x32_bf16 v[74:77], v[160:163], v[210:213], v[74:77]
	v_mfma_f32_16x16x32_bf16 v[126:129], v[156:159], v[190:193], v[126:129]
	v_mfma_f32_16x16x32_bf16 v[122:125], v[164:167], v[190:193], v[122:125]
	v_mfma_f32_16x16x32_bf16 v[110:113], v[156:159], v[198:201], v[110:113]
	v_mfma_f32_16x16x32_bf16 v[106:109], v[164:167], v[198:201], v[106:109]
	v_mfma_f32_16x16x32_bf16 v[94:97], v[156:159], v[206:209], v[94:97]
	v_mfma_f32_16x16x32_bf16 v[90:93], v[164:167], v[206:209], v[90:93]
	v_mfma_f32_16x16x32_bf16 v[78:81], v[156:159], v[214:217], v[78:81]
	v_mfma_f32_16x16x32_bf16 v[74:77], v[164:167], v[214:217], v[74:77]
	s_setprio 0
	s_setprio 1
	v_mfma_f32_16x16x32_bf16 v[118:121], v[168:171], v[186:189], v[118:121]
	v_mfma_f32_16x16x32_bf16 v[114:117], v[178:181], v[186:189], v[114:117]
	v_mfma_f32_16x16x32_bf16 v[102:105], v[168:171], v[194:197], v[102:105]
	v_mfma_f32_16x16x32_bf16 v[98:101], v[178:181], v[194:197], v[98:101]
	v_mfma_f32_16x16x32_bf16 v[86:89], v[168:171], v[202:205], v[86:89]
	v_mfma_f32_16x16x32_bf16 v[82:85], v[178:181], v[202:205], v[82:85]
	v_mfma_f32_16x16x32_bf16 v[70:73], v[168:171], v[210:213], v[70:73]
	v_mfma_f32_16x16x32_bf16 v[66:69], v[178:181], v[210:213], v[66:69]
	v_mfma_f32_16x16x32_bf16 v[118:121], v[172:175], v[190:193], v[118:121]
	v_mfma_f32_16x16x32_bf16 v[114:117], v[182:185], v[190:193], v[114:117]
	v_mfma_f32_16x16x32_bf16 v[102:105], v[172:175], v[198:201], v[102:105]
	v_mfma_f32_16x16x32_bf16 v[98:101], v[182:185], v[198:201], v[98:101]
	v_mfma_f32_16x16x32_bf16 v[86:89], v[172:175], v[206:209], v[86:89]
	v_mfma_f32_16x16x32_bf16 v[82:85], v[182:185], v[206:209], v[82:85]
	v_mfma_f32_16x16x32_bf16 v[70:73], v[172:175], v[214:217], v[70:73]
	v_mfma_f32_16x16x32_bf16 v[66:69], v[182:185], v[214:217], v[66:69]
	s_setprio 0
	s_barrier
	s_add_i32 s2, s56, s34
	v_lshl_add_u64 v[146:147], v[146:147], 0, s[6:7]
	s_mov_b32 m0, s2
	ds_read_b128 v[186:189], v150 offset:49152
	ds_read_b128 v[190:193], v150 offset:50176
	ds_read_b128 v[194:197], v150 offset:51200
	ds_read_b128 v[198:201], v150 offset:52224
	ds_read_b128 v[202:205], v150 offset:53248
	ds_read_b128 v[206:209], v150 offset:54272
	ds_read_b128 v[210:213], v150 offset:55296
	ds_read_b128 v[214:217], v150 offset:56320
	global_load_lds_dwordx4 v[146:147], off
	s_add_i32 m0, s2, 0x2000
	s_add_u32 s2, s30, 0x40080
	v_lshl_add_u64 v[146:147], v[218:219], 0, s[6:7]
	s_addc_u32 s3, s31, 0
	s_add_i32 s30, s57, s34
	global_load_lds_dwordx4 v[146:147], off
	v_lshl_add_u64 v[146:147], s[2:3], 0, v[132:133]
	s_mov_b32 m0, s30
	s_nop 0
	global_load_lds_dwordx4 v[146:147], off
	v_lshl_add_u64 v[146:147], s[2:3], 0, v[136:137]
	s_add_i32 m0, s30, 0x2000
	s_nop 0
	global_load_lds_dwordx4 v[146:147], off
	v_lshl_add_u64 v[146:147], v[220:221], 0, s[6:7]
	s_mov_b32 m0, s40
	s_nop 0
	global_load_lds_dwordx4 v[146:147], off
	v_lshl_add_u64 v[146:147], v[222:223], 0, s[6:7]
	s_mov_b32 m0, s41
	s_nop 0
	global_load_lds_dwordx4 v[146:147], off
	s_waitcnt vmcnt(8)
	s_waitcnt lgkmcnt(0)
	s_barrier
	s_setprio 1
	s_waitcnt lgkmcnt(0)
	v_mfma_f32_16x16x32_bf16 v[62:65], v[152:155], v[186:189], v[62:65]
	v_mfma_f32_16x16x32_bf16 v[58:61], v[160:163], v[186:189], v[58:61]
	v_mfma_f32_16x16x32_bf16 v[46:49], v[152:155], v[194:197], v[46:49]
	v_mfma_f32_16x16x32_bf16 v[42:45], v[160:163], v[194:197], v[42:45]
	v_mfma_f32_16x16x32_bf16 v[30:33], v[152:155], v[202:205], v[30:33]
	v_mfma_f32_16x16x32_bf16 v[26:29], v[160:163], v[202:205], v[26:29]
	v_mfma_f32_16x16x32_bf16 v[14:17], v[152:155], v[210:213], v[14:17]
	v_mfma_f32_16x16x32_bf16 v[10:13], v[160:163], v[210:213], v[10:13]
	v_mfma_f32_16x16x32_bf16 v[62:65], v[156:159], v[190:193], v[62:65]
	v_mfma_f32_16x16x32_bf16 v[58:61], v[164:167], v[190:193], v[58:61]
	v_mfma_f32_16x16x32_bf16 v[46:49], v[156:159], v[198:201], v[46:49]
	v_mfma_f32_16x16x32_bf16 v[42:45], v[164:167], v[198:201], v[42:45]
	v_mfma_f32_16x16x32_bf16 v[30:33], v[156:159], v[206:209], v[30:33]
	v_mfma_f32_16x16x32_bf16 v[26:29], v[164:167], v[206:209], v[26:29]
	v_mfma_f32_16x16x32_bf16 v[14:17], v[156:159], v[214:217], v[14:17]
	v_mfma_f32_16x16x32_bf16 v[10:13], v[164:167], v[214:217], v[10:13]
	s_setprio 0
	s_setprio 1
	v_mfma_f32_16x16x32_bf16 v[54:57], v[168:171], v[186:189], v[54:57]
	v_mfma_f32_16x16x32_bf16 v[50:53], v[178:181], v[186:189], v[50:53]
	v_mfma_f32_16x16x32_bf16 v[38:41], v[168:171], v[194:197], v[38:41]
	v_mfma_f32_16x16x32_bf16 v[34:37], v[178:181], v[194:197], v[34:37]
	v_mfma_f32_16x16x32_bf16 v[22:25], v[168:171], v[202:205], v[22:25]
	v_mfma_f32_16x16x32_bf16 v[18:21], v[178:181], v[202:205], v[18:21]
	v_mfma_f32_16x16x32_bf16 v[6:9], v[168:171], v[210:213], v[6:9]
	v_mfma_f32_16x16x32_bf16 v[2:5], v[178:181], v[210:213], v[2:5]
	v_mfma_f32_16x16x32_bf16 v[54:57], v[172:175], v[190:193], v[54:57]
	v_mfma_f32_16x16x32_bf16 v[50:53], v[182:185], v[190:193], v[50:53]
	v_mfma_f32_16x16x32_bf16 v[38:41], v[172:175], v[198:201], v[38:41]
	v_mfma_f32_16x16x32_bf16 v[34:37], v[182:185], v[198:201], v[34:37]
	v_mfma_f32_16x16x32_bf16 v[22:25], v[172:175], v[206:209], v[22:25]
	v_mfma_f32_16x16x32_bf16 v[18:21], v[182:185], v[206:209], v[18:21]
	v_mfma_f32_16x16x32_bf16 v[6:9], v[172:175], v[214:217], v[6:9]
	v_mfma_f32_16x16x32_bf16 v[2:5], v[182:185], v[214:217], v[2:5]
	s_setprio 0
	s_barrier
	s_add_i32 s55, s55, 2
	s_add_u32 s28, s28, 0x100
	s_addc_u32 s29, s29, 0
	s_add_u32 s53, s53, 0x100
	s_addc_u32 s54, s54, 0
	s_cmp_gt_u32 s55, 13
	s_cbranch_scc0 .LBB0_1400
	s_branch .Lpk1400_exit

.Lpk1444_peel:
	ds_read_b128 v[152:155], v148
	ds_read_b128 v[156:159], v148 offset:1024
	ds_read_b128 v[160:163], v148 offset:2048
	ds_read_b128 v[164:167], v148 offset:3072
	ds_read_b128 v[168:171], v149
	ds_read_b128 v[172:175], v149 offset:1024
	ds_read_b128 v[178:181], v149 offset:2048
	ds_read_b128 v[182:185], v149 offset:3072
	s_add_u32 s2, s26, 0x4000
	s_addc_u32 s3, s27, 0
	s_cmp_eq_u32 s62, 40
	s_cselect_b32 s2, s57, s2
	s_cselect_b32 s3, s56, s3
	s_cselect_b32 s31, s58, s61
	s_cselect_b32 s30, s59, s60
	s_add_u32 s28, s2, 0x8000
	s_addc_u32 s29, s3, 0
	v_lshl_add_u64 v[144:145], s[26:27], 0, v[138:139]
	s_add_i32 m0, s39, 0xc000
	ds_read_b128 v[186:189], v150
	ds_read_b128 v[190:193], v150 offset:1024
	ds_read_b128 v[194:197], v150 offset:2048
	ds_read_b128 v[198:201], v150 offset:3072
	ds_read_b128 v[202:205], v150 offset:4096
	ds_read_b128 v[206:209], v150 offset:5120
	ds_read_b128 v[210:213], v150 offset:6144
	ds_read_b128 v[214:217], v150 offset:7168
	global_load_lds_dwordx4 v[144:145], off
	v_lshl_add_u64 v[144:145], s[26:27], 0, v[140:141]
	s_add_i32 m0, s39, 0xe000
	s_nop 0
	global_load_lds_dwordx4 v[144:145], off
	s_waitcnt vmcnt(24)
	s_waitcnt lgkmcnt(0)
	s_barrier
	s_setprio 1
	s_waitcnt lgkmcnt(0)
	v_mfma_f32_16x16x32_bf16 v[126:129], v[152:155], v[186:189], 0
	v_mfma_f32_16x16x32_bf16 v[122:125], v[160:163], v[186:189], 0
	v_mfma_f32_16x16x32_bf16 v[114:117], v[152:155], v[194:197], 0
	v_mfma_f32_16x16x32_bf16 v[106:109], v[160:163], v[194:197], 0
	v_mfma_f32_16x16x32_bf16 v[98:101], v[152:155], v[202:205], 0
	v_mfma_f32_16x16x32_bf16 v[90:93], v[160:163], v[202:205], 0
	v_mfma_f32_16x16x32_bf16 v[82:85], v[152:155], v[210:213], 0
	v_mfma_f32_16x16x32_bf16 v[74:77], v[160:163], v[210:213], 0
	v_mfma_f32_16x16x32_bf16 v[126:129], v[156:159], v[190:193], v[126:129]
	v_mfma_f32_16x16x32_bf16 v[122:125], v[164:167], v[190:193], v[122:125]
	v_mfma_f32_16x16x32_bf16 v[114:117], v[156:159], v[198:201], v[114:117]
	v_mfma_f32_16x16x32_bf16 v[106:109], v[164:167], v[198:201], v[106:109]
	v_mfma_f32_16x16x32_bf16 v[98:101], v[156:159], v[206:209], v[98:101]
	v_mfma_f32_16x16x32_bf16 v[90:93], v[164:167], v[206:209], v[90:93]
	v_mfma_f32_16x16x32_bf16 v[82:85], v[156:159], v[214:217], v[82:85]
	v_mfma_f32_16x16x32_bf16 v[74:77], v[164:167], v[214:217], v[74:77]
	s_setprio 0
	s_setprio 1
	v_mfma_f32_16x16x32_bf16 v[118:121], v[168:171], v[186:189], 0
	v_mfma_f32_16x16x32_bf16 v[110:113], v[178:181], v[186:189], 0
	v_mfma_f32_16x16x32_bf16 v[102:105], v[168:171], v[194:197], 0
	v_mfma_f32_16x16x32_bf16 v[94:97], v[178:181], v[194:197], 0
	v_mfma_f32_16x16x32_bf16 v[86:89], v[168:171], v[202:205], 0
	v_mfma_f32_16x16x32_bf16 v[78:81], v[178:181], v[202:205], 0
	v_mfma_f32_16x16x32_bf16 v[70:73], v[168:171], v[210:213], 0
	v_mfma_f32_16x16x32_bf16 v[66:69], v[178:181], v[210:213], 0
	v_mfma_f32_16x16x32_bf16 v[118:121], v[172:175], v[190:193], v[118:121]
	v_mfma_f32_16x16x32_bf16 v[110:113], v[182:185], v[190:193], v[110:113]
	v_mfma_f32_16x16x32_bf16 v[102:105], v[172:175], v[198:201], v[102:105]
	v_mfma_f32_16x16x32_bf16 v[94:97], v[182:185], v[198:201], v[94:97]
	v_mfma_f32_16x16x32_bf16 v[86:89], v[172:175], v[206:209], v[86:89]
	v_mfma_f32_16x16x32_bf16 v[78:81], v[182:185], v[206:209], v[78:81]
	v_mfma_f32_16x16x32_bf16 v[70:73], v[172:175], v[214:217], v[70:73]
	v_mfma_f32_16x16x32_bf16 v[66:69], v[182:185], v[214:217], v[66:69]
	s_setprio 0
	s_barrier
	s_add_i32 s63, s46, s38
	v_lshl_add_u64 v[144:145], s[30:31], 0, v[132:133]
	s_mov_b32 m0, s63
	ds_read_b128 v[186:189], v150 offset:16384
	ds_read_b128 v[190:193], v150 offset:17408
	ds_read_b128 v[194:197], v150 offset:18432
	ds_read_b128 v[198:201], v150 offset:19456
	ds_read_b128 v[202:205], v150 offset:20480
	ds_read_b128 v[206:209], v150 offset:21504
	ds_read_b128 v[210:213], v150 offset:22528
	ds_read_b128 v[214:217], v150 offset:23552
	global_load_lds_dwordx4 v[144:145], off
	s_add_i32 m0, s63, 0x2000
	s_add_u32 s64, s30, 0x4000
	v_lshl_add_u64 v[144:145], s[30:31], 0, v[136:137]
	s_addc_u32 s65, s31, 0
	s_add_i32 s63, s47, s38
	global_load_lds_dwordx4 v[144:145], off
	v_lshl_add_u64 v[144:145], s[64:65], 0, v[132:133]
	s_mov_b32 m0, s63
	s_nop 0
	global_load_lds_dwordx4 v[144:145], off
	v_lshl_add_u64 v[144:145], s[64:65], 0, v[136:137]
	s_add_i32 m0, s63, 0x2000
	s_nop 0
	global_load_lds_dwordx4 v[144:145], off
	v_lshl_add_u64 v[144:145], s[2:3], 0, v[130:131]
	s_mov_b32 m0, s39
	s_nop 0
	global_load_lds_dwordx4 v[144:145], off
	v_lshl_add_u64 v[144:145], s[2:3], 0, v[134:135]
	s_mov_b32 m0, s40
	s_nop 0
	global_load_lds_dwordx4 v[144:145], off
	s_waitcnt vmcnt(24)
	s_waitcnt lgkmcnt(0)
	s_barrier
	s_setprio 1
	s_waitcnt lgkmcnt(0)
	v_mfma_f32_16x16x32_bf16 v[62:65], v[152:155], v[186:189], 0
	v_mfma_f32_16x16x32_bf16 v[58:61], v[160:163], v[186:189], 0
	v_mfma_f32_16x16x32_bf16 v[50:53], v[152:155], v[194:197], 0
	v_mfma_f32_16x16x32_bf16 v[42:45], v[160:163], v[194:197], 0
	v_mfma_f32_16x16x32_bf16 v[34:37], v[152:155], v[202:205], 0
	v_mfma_f32_16x16x32_bf16 v[26:29], v[160:163], v[202:205], 0
	v_mfma_f32_16x16x32_bf16 v[18:21], v[152:155], v[210:213], 0
	v_mfma_f32_16x16x32_bf16 v[10:13], v[160:163], v[210:213], 0
	v_mfma_f32_16x16x32_bf16 v[62:65], v[156:159], v[190:193], v[62:65]
	v_mfma_f32_16x16x32_bf16 v[58:61], v[164:167], v[190:193], v[58:61]
	v_mfma_f32_16x16x32_bf16 v[50:53], v[156:159], v[198:201], v[50:53]
	v_mfma_f32_16x16x32_bf16 v[42:45], v[164:167], v[198:201], v[42:45]
	v_mfma_f32_16x16x32_bf16 v[34:37], v[156:159], v[206:209], v[34:37]
	v_mfma_f32_16x16x32_bf16 v[26:29], v[164:167], v[206:209], v[26:29]
	v_mfma_f32_16x16x32_bf16 v[18:21], v[156:159], v[214:217], v[18:21]
	v_mfma_f32_16x16x32_bf16 v[10:13], v[164:167], v[214:217], v[10:13]
	s_setprio 0
	s_setprio 1
	v_mfma_f32_16x16x32_bf16 v[54:57], v[168:171], v[186:189], 0
	v_mfma_f32_16x16x32_bf16 v[46:49], v[178:181], v[186:189], 0
	v_mfma_f32_16x16x32_bf16 v[38:41], v[168:171], v[194:197], 0
	v_mfma_f32_16x16x32_bf16 v[30:33], v[178:181], v[194:197], 0
	v_mfma_f32_16x16x32_bf16 v[22:25], v[168:171], v[202:205], 0
	v_mfma_f32_16x16x32_bf16 v[14:17], v[178:181], v[202:205], 0
	v_mfma_f32_16x16x32_bf16 v[6:9], v[168:171], v[210:213], 0
	v_mfma_f32_16x16x32_bf16 v[2:5], v[178:181], v[210:213], 0
	v_mfma_f32_16x16x32_bf16 v[54:57], v[172:175], v[190:193], v[54:57]
	v_mfma_f32_16x16x32_bf16 v[46:49], v[182:185], v[190:193], v[46:49]
	v_mfma_f32_16x16x32_bf16 v[38:41], v[172:175], v[198:201], v[38:41]
	v_mfma_f32_16x16x32_bf16 v[30:33], v[182:185], v[198:201], v[30:33]
	v_mfma_f32_16x16x32_bf16 v[22:25], v[172:175], v[206:209], v[22:25]
	v_mfma_f32_16x16x32_bf16 v[14:17], v[182:185], v[206:209], v[14:17]
	v_mfma_f32_16x16x32_bf16 v[6:9], v[172:175], v[214:217], v[6:9]
	v_mfma_f32_16x16x32_bf16 v[2:5], v[182:185], v[214:217], v[2:5]
	s_setprio 0
	s_barrier
	s_add_i32 s63, 0, 0x18000
	v_add_u32_e32 v144, s63, v146
	s_add_i32 s64, 0, 0x1c000
	ds_read_b128 v[152:155], v144
	ds_read_b128 v[156:159], v144 offset:1024
	ds_read_b128 v[160:163], v144 offset:2048
	ds_read_b128 v[164:167], v144 offset:3072
	v_add_u32_e32 v144, s64, v146
	ds_read_b128 v[168:171], v144
	ds_read_b128 v[172:175], v144 offset:1024
	ds_read_b128 v[178:181], v144 offset:2048
	ds_read_b128 v[182:185], v144 offset:3072
	s_add_u32 s2, s2, 0x4000
	s_addc_u32 s3, s3, 0
	s_mov_b32 m0, s41
	v_lshl_add_u64 v[144:145], s[2:3], 0, v[130:131]
	ds_read_b128 v[186:189], v150 offset:32768
	ds_read_b128 v[190:193], v150 offset:33792
	ds_read_b128 v[194:197], v150 offset:34816
	ds_read_b128 v[198:201], v150 offset:35840
	ds_read_b128 v[202:205], v150 offset:36864
	ds_read_b128 v[206:209], v150 offset:37888
	ds_read_b128 v[210:213], v150 offset:38912
	ds_read_b128 v[214:217], v150 offset:39936
	global_load_lds_dwordx4 v[144:145], off
	v_lshl_add_u64 v[144:145], s[2:3], 0, v[134:135]
	s_mov_b32 m0, s42
	s_nop 0
	global_load_lds_dwordx4 v[144:145], off
	s_waitcnt vmcnt(8)
	s_waitcnt lgkmcnt(0)
	s_barrier
	s_setprio 1
	s_waitcnt lgkmcnt(0)
	v_mfma_f32_16x16x32_bf16 v[126:129], v[152:155], v[186:189], v[126:129]
	v_mfma_f32_16x16x32_bf16 v[122:125], v[160:163], v[186:189], v[122:125]
	v_mfma_f32_16x16x32_bf16 v[114:117], v[152:155], v[194:197], v[114:117]
	v_mfma_f32_16x16x32_bf16 v[106:109], v[160:163], v[194:197], v[106:109]
	v_mfma_f32_16x16x32_bf16 v[98:101], v[152:155], v[202:205], v[98:101]
	v_mfma_f32_16x16x32_bf16 v[90:93], v[160:163], v[202:205], v[90:93]
	v_mfma_f32_16x16x32_bf16 v[82:85], v[152:155], v[210:213], v[82:85]
	v_mfma_f32_16x16x32_bf16 v[74:77], v[160:163], v[210:213], v[74:77]
	v_mfma_f32_16x16x32_bf16 v[126:129], v[156:159], v[190:193], v[126:129]
	v_mfma_f32_16x16x32_bf16 v[122:125], v[164:167], v[190:193], v[122:125]
	v_mfma_f32_16x16x32_bf16 v[114:117], v[156:159], v[198:201], v[114:117]
	v_mfma_f32_16x16x32_bf16 v[106:109], v[164:167], v[198:201], v[106:109]
	v_mfma_f32_16x16x32_bf16 v[98:101], v[156:159], v[206:209], v[98:101]
	v_mfma_f32_16x16x32_bf16 v[90:93], v[164:167], v[206:209], v[90:93]
	v_mfma_f32_16x16x32_bf16 v[82:85], v[156:159], v[214:217], v[82:85]
	v_mfma_f32_16x16x32_bf16 v[74:77], v[164:167], v[214:217], v[74:77]
	s_setprio 0
	s_setprio 1
	v_mfma_f32_16x16x32_bf16 v[118:121], v[168:171], v[186:189], v[118:121]
	v_mfma_f32_16x16x32_bf16 v[110:113], v[178:181], v[186:189], v[110:113]
	v_mfma_f32_16x16x32_bf16 v[102:105], v[168:171], v[194:197], v[102:105]
	v_mfma_f32_16x16x32_bf16 v[94:97], v[178:181], v[194:197], v[94:97]
	v_mfma_f32_16x16x32_bf16 v[86:89], v[168:171], v[202:205], v[86:89]
	v_mfma_f32_16x16x32_bf16 v[78:81], v[178:181], v[202:205], v[78:81]
	v_mfma_f32_16x16x32_bf16 v[70:73], v[168:171], v[210:213], v[70:73]
	v_mfma_f32_16x16x32_bf16 v[66:69], v[178:181], v[210:213], v[66:69]
	v_mfma_f32_16x16x32_bf16 v[118:121], v[172:175], v[190:193], v[118:121]
	v_mfma_f32_16x16x32_bf16 v[110:113], v[182:185], v[190:193], v[110:113]
	v_mfma_f32_16x16x32_bf16 v[102:105], v[172:175], v[198:201], v[102:105]
	v_mfma_f32_16x16x32_bf16 v[94:97], v[182:185], v[198:201], v[94:97]
	v_mfma_f32_16x16x32_bf16 v[86:89], v[172:175], v[206:209], v[86:89]
	v_mfma_f32_16x16x32_bf16 v[78:81], v[182:185], v[206:209], v[78:81]
	v_mfma_f32_16x16x32_bf16 v[70:73], v[172:175], v[214:217], v[70:73]
	v_mfma_f32_16x16x32_bf16 v[66:69], v[182:185], v[214:217], v[66:69]
	s_setprio 0
	s_barrier
	s_add_u32 s2, s30, 0x8000
	s_addc_u32 s3, s31, 0
	s_add_i32 s63, s63, s38
	v_lshl_add_u64 v[144:145], s[2:3], 0, v[132:133]
	s_mov_b32 m0, s63
	ds_read_b128 v[186:189], v150 offset:49152
	ds_read_b128 v[190:193], v150 offset:50176
	ds_read_b128 v[194:197], v150 offset:51200
	ds_read_b128 v[198:201], v150 offset:52224
	ds_read_b128 v[202:205], v150 offset:53248
	ds_read_b128 v[206:209], v150 offset:54272
	ds_read_b128 v[210:213], v150 offset:55296
	ds_read_b128 v[214:217], v150 offset:56320
	global_load_lds_dwordx4 v[144:145], off
	s_add_i32 m0, s63, 0x2000
	v_lshl_add_u64 v[144:145], s[2:3], 0, v[136:137]
	s_add_u32 s2, s30, 0xc000
	s_addc_u32 s3, s31, 0
	s_add_i32 s30, s64, s38
	global_load_lds_dwordx4 v[144:145], off
	v_lshl_add_u64 v[144:145], s[2:3], 0, v[132:133]
	s_mov_b32 m0, s30
	s_nop 0
	global_load_lds_dwordx4 v[144:145], off
	v_lshl_add_u64 v[144:145], s[2:3], 0, v[136:137]
	s_add_i32 m0, s30, 0x2000
	s_nop 0
	global_load_lds_dwordx4 v[144:145], off
	v_lshl_add_u64 v[144:145], s[28:29], 0, v[130:131]
	s_mov_b32 m0, s44
	s_nop 0
	global_load_lds_dwordx4 v[144:145], off
	v_lshl_add_u64 v[144:145], s[28:29], 0, v[134:135]
	s_mov_b32 m0, s45
	s_nop 0
	global_load_lds_dwordx4 v[144:145], off
	s_waitcnt vmcnt(8)
	s_waitcnt lgkmcnt(0)
	s_barrier
	s_setprio 1
	s_waitcnt lgkmcnt(0)
	v_mfma_f32_16x16x32_bf16 v[62:65], v[152:155], v[186:189], v[62:65]
	v_mfma_f32_16x16x32_bf16 v[58:61], v[160:163], v[186:189], v[58:61]
	v_mfma_f32_16x16x32_bf16 v[50:53], v[152:155], v[194:197], v[50:53]
	v_mfma_f32_16x16x32_bf16 v[42:45], v[160:163], v[194:197], v[42:45]
	v_mfma_f32_16x16x32_bf16 v[34:37], v[152:155], v[202:205], v[34:37]
	v_mfma_f32_16x16x32_bf16 v[26:29], v[160:163], v[202:205], v[26:29]
	v_mfma_f32_16x16x32_bf16 v[18:21], v[152:155], v[210:213], v[18:21]
	v_mfma_f32_16x16x32_bf16 v[10:13], v[160:163], v[210:213], v[10:13]
	v_mfma_f32_16x16x32_bf16 v[62:65], v[156:159], v[190:193], v[62:65]
	v_mfma_f32_16x16x32_bf16 v[58:61], v[164:167], v[190:193], v[58:61]
	v_mfma_f32_16x16x32_bf16 v[50:53], v[156:159], v[198:201], v[50:53]
	v_mfma_f32_16x16x32_bf16 v[42:45], v[164:167], v[198:201], v[42:45]
	v_mfma_f32_16x16x32_bf16 v[34:37], v[156:159], v[206:209], v[34:37]
	v_mfma_f32_16x16x32_bf16 v[26:29], v[164:167], v[206:209], v[26:29]
	v_mfma_f32_16x16x32_bf16 v[18:21], v[156:159], v[214:217], v[18:21]
	v_mfma_f32_16x16x32_bf16 v[10:13], v[164:167], v[214:217], v[10:13]
	s_setprio 0
	s_setprio 1
	v_mfma_f32_16x16x32_bf16 v[54:57], v[168:171], v[186:189], v[54:57]
	v_mfma_f32_16x16x32_bf16 v[46:49], v[178:181], v[186:189], v[46:49]
	v_mfma_f32_16x16x32_bf16 v[38:41], v[168:171], v[194:197], v[38:41]
	v_mfma_f32_16x16x32_bf16 v[30:33], v[178:181], v[194:197], v[30:33]
	v_mfma_f32_16x16x32_bf16 v[22:25], v[168:171], v[202:205], v[22:25]
	v_mfma_f32_16x16x32_bf16 v[14:17], v[178:181], v[202:205], v[14:17]
	v_mfma_f32_16x16x32_bf16 v[6:9], v[168:171], v[210:213], v[6:9]
	v_mfma_f32_16x16x32_bf16 v[2:5], v[178:181], v[210:213], v[2:5]
	v_mfma_f32_16x16x32_bf16 v[54:57], v[172:175], v[190:193], v[54:57]
	v_mfma_f32_16x16x32_bf16 v[46:49], v[182:185], v[190:193], v[46:49]
	v_mfma_f32_16x16x32_bf16 v[38:41], v[172:175], v[198:201], v[38:41]
	v_mfma_f32_16x16x32_bf16 v[30:33], v[182:185], v[198:201], v[30:33]
	v_mfma_f32_16x16x32_bf16 v[22:25], v[172:175], v[206:209], v[22:25]
	v_mfma_f32_16x16x32_bf16 v[14:17], v[182:185], v[206:209], v[14:17]
	v_mfma_f32_16x16x32_bf16 v[6:9], v[172:175], v[214:217], v[6:9]
	v_mfma_f32_16x16x32_bf16 v[2:5], v[182:185], v[214:217], v[2:5]
	s_setprio 0
	s_barrier
	s_add_i32 s62, s62, 2
	s_add_u32 s26, s26, 0x10000
	s_addc_u32 s27, s27, 0
	s_add_u32 s60, s60, 0x10000
	s_addc_u32 s61, s61, 0
	s_cmp_gt_u32 s62, 41
	s_cbranch_scc0 .LBB0_1444
	s_branch .Lpk1444_exit
